# GLA log-decay kept in log2 units so every exp of a cumulative sum is a bare v_exp (196 multiplies removed per wave and direction); gelu constant chain folded into one multiply; mov+fmac pairs replaced
# speedup vs baseline: 1.0207x; 1.0029x over previous
; template <int MODE> __device__ void mixer_lru(const Params& p, int l, int n, LAS unsigned char* lds) {
;     ...
;         const bf16_t* PB = (const bf16_t*)(ws + WS_PB); const float* carry = (const float*)(ws + WS_CA);
;         const int ch0 = 8 * lane;
;         const float* cfp = carry + (size_t)(0 * NCH + n) * 512 + ch0; const float* cbp = carry + (size_t)(1 * NCH + n) * 512 + ch0; const float* gnp = p.in[11] + (size_t)l * 512 + ch0;
;         const f32x4 cf0 = *(const f32x4*)cfp, cf1 = *(const f32x4*)(cfp + 4), cb0 = *(const f32x4*)cbp, cb1 = *(const f32x4*)(cbp + 4), g0 = *(const f32x4*)gnp, g1 = *(const f32x4*)(gnp + 4);
;         const float cf[8] = {cf0[0], cf0[1], cf0[2], cf0[3], cf1[0], cf1[1], cf1[2], cf1[3]}, cb[8] = {cb0[0], cb0[1], cb0[2], cb0[3], cb1[0], cb1[1], cb1[2], cb1[3]};
;         const float gg[8] = {g0[0], g0[1], g0[2], g0[3], g1[0], g1[1], g1[2], g1[3]};
;         {
;             bf16x8 h0[8], pf[8], pb[8], gt[8];
; #pragma unroll
;             for (int i = 0; i < 8; ++i) { const size_t row = (size_t)(t0 + wave * 8 + i);
;                 h0[i] = *(const bf16x8*)(y + row * D + ch0); pf[i] = *(const bf16x8*)(y + row * D + 512 + ch0); pb[i] = *(const bf16x8*)(PB + row * 512 + ch0); gt[i] = *(const bf16x8*)(proj + row * DINP + 512 + ch0); }
.LBB0_146:
	v_mov_b32_e32 v24, v245
	s_ashr_i32 s1, s0, 31
	s_lshl_b64 s[6:7], s[0:1], 11
	v_lshlrev_b32_e32 v0, 3, v24
	v_and_b32_e32 v25, 0x1f8, v0
	s_add_u32 s6, s10, s6
	s_addc_u32 s7, s11, s7
	v_lshlrev_b32_e32 v176, 2, v25
	v_lshl_add_u64 v[0:1], s[6:7], 0, v[176:177]
	s_mov_b64 s[8:9], 0x80000
	s_mov_b32 s1, 0x80000
	v_ashrrev_i32_e32 v24, 3, v24
	v_lshl_add_u64 v[2:3], v[0:1], 0, s[8:9]
	v_add_co_u32_e32 v0, vcc, s1, v0
	v_and_b32_e32 v24, -8, v24
	s_nop 0
	v_addc_co_u32_e32 v1, vcc, 0, v1, vcc
	v_lshl_add_u32 v24, s0, 6, v24
	global_load_dwordx4 v[8:11], v176, s[6:7]
	global_load_dwordx4 v[16:19], v176, s[6:7] offset:16
	global_load_dwordx4 v[12:15], v[0:1], off
	global_load_dwordx4 v[20:23], v[2:3], off offset:16
	s_nop 0
	global_load_dwordx4 v[0:3], v176, s[4:5] offset:16
	global_load_dwordx4 v[4:7], v176, s[4:5]
	v_lshlrev_b32_e32 v176, 1, v25
	v_ashrrev_i32_e32 v25, 31, v24
	v_lshlrev_b64 v[160:161], 11, v[24:25]
	v_lshl_add_u64 v[26:27], s[94:95], 0, v[160:161]
	v_mov_b64_e32 v[164:165], s[60:61]
	v_lshl_add_u64 v[26:27], v[26:27], 0, v[176:177]
	v_mad_i64_i32 v[28:29], s[6:7], v24, s81, v[164:165]
	v_lshl_add_u64 v[158:159], s[28:29], 0, v[176:177]
	global_load_dwordx4 v[136:139], v[26:27], off
	global_load_dwordx4 v[128:131], v[26:27], off offset:1024
	v_lshlrev_b64 v[26:27], 10, v[24:25]
	v_lshl_add_u64 v[28:29], v[28:29], 0, v[176:177]
	v_lshl_add_u64 v[26:27], v[158:159], 0, v[26:27]
	v_add_co_u32_e32 v28, vcc, s84, v28
	v_or_b32_e32 v166, 7, v24
	s_nop 0
	v_addc_co_u32_e32 v29, vcc, 0, v29, vcc
	global_load_dwordx4 v[132:135], v[26:27], off
	global_load_dwordx4 v[140:143], v[28:29], off offset:1024
	v_or_b32_e32 v26, 1, v24
	v_ashrrev_i32_e32 v27, 31, v26
	v_lshlrev_b64 v[154:155], 11, v[26:27]
	v_lshl_add_u64 v[28:29], s[94:95], 0, v[154:155]
	v_lshl_add_u64 v[28:29], v[28:29], 0, v[176:177]
	global_load_dwordx4 v[120:123], v[28:29], off
	global_load_dwordx4 v[64:67], v[28:29], off offset:1024
	v_lshlrev_b64 v[28:29], 10, v[26:27]
	v_mad_i64_i32 v[26:27], s[6:7], v26, s81, v[164:165]
	v_lshl_add_u64 v[26:27], v[26:27], 0, v[176:177]
	v_lshl_add_u64 v[28:29], v[158:159], 0, v[28:29]
	v_add_co_u32_e32 v26, vcc, s84, v26
	v_ashrrev_i32_e32 v167, 31, v166
	s_nop 0
	v_addc_co_u32_e32 v27, vcc, 0, v27, vcc
	global_load_dwordx4 v[68:71], v[28:29], off
	global_load_dwordx4 v[124:127], v[26:27], off offset:1024
	v_or_b32_e32 v26, 2, v24
	v_ashrrev_i32_e32 v27, 31, v26
	v_lshlrev_b64 v[156:157], 11, v[26:27]
	v_lshl_add_u64 v[28:29], s[94:95], 0, v[156:157]
	v_lshl_add_u64 v[28:29], v[28:29], 0, v[176:177]
	global_load_dwordx4 v[112:115], v[28:29], off
	global_load_dwordx4 v[104:107], v[28:29], off offset:1024
	v_lshlrev_b64 v[28:29], 10, v[26:27]
	v_mad_i64_i32 v[26:27], s[6:7], v26, s81, v[164:165]
	v_lshl_add_u64 v[26:27], v[26:27], 0, v[176:177]
	v_lshl_add_u64 v[28:29], v[158:159], 0, v[28:29]
	v_add_co_u32_e32 v26, vcc, s84, v26
	v_lshlrev_b64 v[162:163], 10, v[166:167]
	s_nop 0
	v_addc_co_u32_e32 v27, vcc, 0, v27, vcc
	global_load_dwordx4 v[108:111], v[28:29], off
	global_load_dwordx4 v[116:119], v[26:27], off offset:1024
	v_or_b32_e32 v26, 3, v24
	v_ashrrev_i32_e32 v27, 31, v26
	v_lshlrev_b64 v[150:151], 11, v[26:27]
	v_lshl_add_u64 v[28:29], s[94:95], 0, v[150:151]
	v_lshl_add_u64 v[28:29], v[28:29], 0, v[176:177]
	global_load_dwordx4 v[96:99], v[28:29], off
	global_load_dwordx4 v[88:91], v[28:29], off offset:1024
	v_lshlrev_b64 v[28:29], 10, v[26:27]
	v_mad_i64_i32 v[26:27], s[6:7], v26, s81, v[164:165]
	v_lshl_add_u64 v[26:27], v[26:27], 0, v[176:177]
	v_lshl_add_u64 v[28:29], v[158:159], 0, v[28:29]
	v_add_co_u32_e32 v26, vcc, s84, v26
	v_lshl_add_u64 v[162:163], v[158:159], 0, v[162:163]
	s_nop 0
	v_addc_co_u32_e32 v27, vcc, 0, v27, vcc
	global_load_dwordx4 v[92:95], v[28:29], off
	global_load_dwordx4 v[100:103], v[26:27], off offset:1024
	v_or_b32_e32 v26, 4, v24
	v_ashrrev_i32_e32 v27, 31, v26
	v_lshlrev_b64 v[152:153], 11, v[26:27]
	v_lshl_add_u64 v[28:29], s[94:95], 0, v[152:153]
	v_lshl_add_u64 v[28:29], v[28:29], 0, v[176:177]
	global_load_dwordx4 v[80:83], v[28:29], off
	global_load_dwordx4 v[72:75], v[28:29], off offset:1024
	v_lshlrev_b64 v[28:29], 10, v[26:27]
	v_mad_i64_i32 v[26:27], s[6:7], v26, s81, v[164:165]
	v_lshl_add_u64 v[26:27], v[26:27], 0, v[176:177]
	v_lshl_add_u64 v[28:29], v[158:159], 0, v[28:29]
	v_add_co_u32_e32 v26, vcc, s84, v26
	v_lshlrev_b64 v[144:145], 11, v[166:167]
	s_nop 0
	v_addc_co_u32_e32 v27, vcc, 0, v27, vcc
	global_load_dwordx4 v[76:79], v[28:29], off
	global_load_dwordx4 v[84:87], v[26:27], off offset:1024
	v_or_b32_e32 v26, 5, v24
	v_ashrrev_i32_e32 v27, 31, v26
	v_lshlrev_b64 v[146:147], 11, v[26:27]
	v_lshl_add_u64 v[28:29], s[94:95], 0, v[146:147]
	v_lshl_add_u64 v[28:29], v[28:29], 0, v[176:177]
	global_load_dwordx4 v[56:59], v[28:29], off
	global_load_dwordx4 v[48:51], v[28:29], off offset:1024
	v_lshlrev_b64 v[28:29], 10, v[26:27]
	v_mad_i64_i32 v[26:27], s[6:7], v26, s81, v[164:165]
	v_lshl_add_u64 v[26:27], v[26:27], 0, v[176:177]
	v_lshl_add_u64 v[28:29], v[158:159], 0, v[28:29]
	v_add_co_u32_e32 v26, vcc, s84, v26
	s_waitcnt vmcnt(21)
	v_and_b32_e32 v169, 0xffff0000, v139
	v_addc_co_u32_e32 v27, vcc, 0, v27, vcc
	global_load_dwordx4 v[52:55], v[28:29], off
	global_load_dwordx4 v[60:63], v[26:27], off offset:1024
	v_or_b32_e32 v26, 6, v24
	v_ashrrev_i32_e32 v27, 31, v26
	v_lshlrev_b64 v[148:149], 11, v[26:27]
	v_lshl_add_u64 v[28:29], s[94:95], 0, v[148:149]
	v_lshl_add_u64 v[28:29], v[28:29], 0, v[176:177]
	global_load_dwordx4 v[40:43], v[28:29], off
	global_load_dwordx4 v[32:35], v[28:29], off offset:1024
	v_lshlrev_b64 v[28:29], 10, v[26:27]
	v_lshl_add_u64 v[28:29], v[158:159], 0, v[28:29]
	v_mad_i64_i32 v[158:159], s[6:7], v166, s81, v[164:165]
	v_mad_i64_i32 v[26:27], s[6:7], v26, s81, v[164:165]
	v_lshl_add_u64 v[164:165], v[158:159], 0, v[176:177]
	v_and_b32_e32 v158, 64, v228
	v_add_u32_e32 v174, 64, v158
	s_waitcnt vmcnt(22)
; __device__ __forceinline__ float bf2f(bf16_t b) { return __uint_as_float(((unsigned)b) << 16); }
; __device__ __forceinline__ unsigned cvtpk(float lo, float hi) { const f32x2 v = (f32x2){lo, hi}; const bf16v2 b = __builtin_convertvector(v, bf16v2); return __builtin_bit_cast(unsigned, b); }
; __device__ __forceinline__ float geluf_(float x) { const float y = 0.7978845608028654f * (x + 0.044715f * x * x * x); const float t = 1.0f - 2.0f * __builtin_amdgcn_rcpf(__expf(2.0f * y) + 1.0f); return 0.5f * x * (1.0f + t); }
; template <int MODE> __device__ void mixer_lru(const Params& p, int l, int n, LAS unsigned char* lds) {
;     ...
;             for (int i = 0; i < 8; ++i) { const size_t row = (size_t)(t0 + wave * 8 + i);
;                 float v[8]; float ss = 0.f;
; #pragma unroll
;                 for (int k = 0; k < 8; ++k) { v[k] = (bf2f((bf16_t)h0[i][k]) + bf2f((bf16_t)pf[i][k]) * cf[k] + bf2f((bf16_t)pb[i][k]) * cb[k]) * geluf_(bf2f((bf16_t)gt[i][k])); ss += v[k] * v[k]; }
; #pragma unroll
;                 for (int o = 32; o >= 1; o >>= 1) ss += __shfl_xor(ss, o);
;                 const float rs = rsqrtf(ss * (1.0f / 512.0f) + EPS);
;                 *(u32x4*)(y + row * D + ch0) = (u32x4){cvtpk(v[0] * rs * gg[0], v[1] * rs * gg[1]), cvtpk(v[2] * rs * gg[2], v[3] * rs * gg[3]), cvtpk(v[4] * rs * gg[4], v[5] * rs * gg[5]), cvtpk(v[6] * rs * gg[6], v[7] * rs * gg[7])}; }
	v_lshlrev_b32_e32 v158, 16, v143
	v_mul_f32_e32 v166, 0x3d372713, v158
	v_mul_f32_e32 v166, v166, v158
	v_fma_f32 v167, v166, v158, v158
	v_mul_f32_e32 v166, 0x40135761, v167
	v_lshl_add_u64 v[26:27], v[26:27], 0, v[176:177]
	v_add_co_u32_e32 v26, vcc, s84, v26
	s_nop 0
	s_nop 0
	v_addc_co_u32_e32 v27, vcc, 0, v27, vcc
	v_xor_b32_e32 v159, 32, v228
	v_exp_f32_e32 v166, v166
	v_cmp_lt_i32_e32 vcc, v159, v174
	v_lshlrev_b32_e32 v168, 16, v139
	v_and_b32_e32 v171, 0xffff0000, v131
	v_cndmask_b32_e32 v159, v228, v159, vcc
	v_lshlrev_b32_e32 v172, 2, v159
	v_and_b32_e32 v159, 0xffff0000, v143
	v_add_f32_e32 v143, 1.0, v166
	v_mul_f32_e32 v139, 0x3d372713, v159
	v_rcp_f32_e32 v166, v143
	v_mul_f32_e32 v139, v139, v159
	v_fma_f32 v143, v139, v159, v159
	v_mul_f32_e32 v139, 0x40135761, v143
	v_exp_f32_e32 v139, v139
	v_lshlrev_b32_e32 v170, 16, v131
	v_pk_mul_f32 v[158:159], v[158:159], 0.5 op_sel_hi:[1,0]
	v_pk_fma_f32 v[168:169], v[18:19], v[170:171], v[168:169]
	v_add_f32_e32 v131, 1.0, v139
	v_rcp_f32_e32 v167, v131
	v_and_b32_e32 v171, 0xffff0000, v135
	v_lshlrev_b32_e32 v170, 16, v135
	v_and_b32_e32 v139, 0xffff0000, v138
	v_pk_fma_f32 v[166:167], v[166:167], 2.0, 1.0 op_sel_hi:[1,0,0] neg_lo:[1,0,0] neg_hi:[1,0,0]
	v_lshlrev_b32_e32 v138, 16, v138
	v_pk_add_f32 v[166:167], v[166:167], 1.0 op_sel_hi:[1,0]
	v_pk_fma_f32 v[168:169], v[22:23], v[170:171], v[168:169]
	v_pk_mul_f32 v[158:159], v[158:159], v[166:167]
	v_lshlrev_b32_e32 v166, 16, v142
	v_mul_f32_e32 v131, 0x3d372713, v166
	v_mul_f32_e32 v131, v131, v166
	v_fma_f32 v135, v131, v166, v166
	v_mul_f32_e32 v131, 0x40135761, v135
	v_exp_f32_e32 v131, v131
	v_and_b32_e32 v167, 0xffff0000, v142
	v_mov_b32_e32 v135, v167
	v_and_b32_e32 v171, 0xffff0000, v129
	v_add_f32_e32 v131, 1.0, v131
	v_rcp_f32_e32 v142, v131
	v_mul_f32_e32 v131, 0x3d372713, v167
	v_mul_f32_e32 v131, v131, v167
	v_fmac_f32_e32 v135, v131, v135
	v_mul_f32_e32 v131, 0x40135761, v135
	v_exp_f32_e32 v135, v131
	v_and_b32_e32 v131, 0xffff0000, v130
	v_lshlrev_b32_e32 v130, 16, v130
	v_pk_fma_f32 v[130:131], v[16:17], v[130:131], v[138:139]
	v_add_f32_e32 v135, 1.0, v135
	v_rcp_f32_e32 v143, v135
	v_and_b32_e32 v135, 0xffff0000, v134
	v_lshlrev_b32_e32 v134, 16, v134
	v_pk_fma_f32 v[130:131], v[20:21], v[134:135], v[130:131]
	v_pk_fma_f32 v[134:135], v[142:143], 2.0, 1.0 op_sel_hi:[1,0,0] neg_lo:[1,0,0] neg_hi:[1,0,0]
	v_pk_mul_f32 v[138:139], v[166:167], 0.5 op_sel_hi:[1,0]
	v_pk_add_f32 v[134:135], v[134:135], 1.0 op_sel_hi:[1,0]
	v_lshlrev_b32_e32 v142, 16, v141
	v_pk_mul_f32 v[134:135], v[138:139], v[134:135]
	v_and_b32_e32 v143, 0xffff0000, v141
	v_mul_f32_e32 v138, 0x3d372713, v142
	v_pk_mul_f32 v[166:167], v[130:131], v[134:135]
	v_mul_f32_e32 v131, 0x3d372713, v143
	v_mul_f32_e32 v138, v138, v142
	v_mov_b32_e32 v139, v142
	v_and_b32_e32 v135, 0xffff0000, v137
	v_lshlrev_b32_e32 v134, 16, v137
	v_mul_f32_e32 v131, v131, v143
	v_mov_b32_e32 v137, v143
	v_fmac_f32_e32 v139, v138, v139
	v_fmac_f32_e32 v137, v131, v137
	v_mul_f32_e32 v138, 0x40135761, v139
	v_mul_f32_e32 v131, 0x40135761, v137
	v_exp_f32_e32 v170, v138
	v_exp_f32_e32 v131, v131
	v_lshlrev_b32_e32 v178, 16, v140
	v_pk_mul_f32 v[142:143], v[142:143], 0.5 op_sel_hi:[1,0]
	v_add_f32_e32 v130, 1.0, v170
	v_lshlrev_b32_e32 v170, 16, v129
	v_add_f32_e32 v129, 1.0, v131
	v_rcp_f32_e32 v131, v129
	v_mul_f32_e32 v129, 0x3d372713, v178
	v_pk_fma_f32 v[134:135], v[10:11], v[170:171], v[134:135]
	v_and_b32_e32 v171, 0xffff0000, v133
	v_lshlrev_b32_e32 v170, 16, v133
	v_mul_f32_e32 v129, v129, v178
	v_fma_f32 v133, v129, v178, v178
	v_mul_f32_e32 v129, 0x40135761, v133
	v_rcp_f32_e32 v130, v130
	v_exp_f32_e32 v129, v129
	v_pk_fma_f32 v[130:131], v[130:131], 2.0, 1.0 op_sel_hi:[1,0,0] neg_lo:[1,0,0] neg_hi:[1,0,0]
	v_pk_fma_f32 v[134:135], v[14:15], v[170:171], v[134:135]
	v_pk_add_f32 v[130:131], v[130:131], 1.0 op_sel_hi:[1,0]
	v_and_b32_e32 v179, 0xffff0000, v140
	v_pk_mul_f32 v[130:131], v[142:143], v[130:131]
	v_add_f32_e32 v129, 1.0, v129
	v_pk_mul_f32 v[170:171], v[134:135], v[130:131]
	v_rcp_f32_e32 v130, v129
	v_mul_f32_e32 v129, 0x3d372713, v179
	v_mul_f32_e32 v129, v129, v179
	v_fma_f32 v131, v129, v179, v179
	v_mul_f32_e32 v129, 0x40135761, v131
	v_and_b32_e32 v135, 0xffff0000, v136
	v_lshlrev_b32_e32 v134, 16, v136
	v_exp_f32_e32 v131, v129
	v_and_b32_e32 v129, 0xffff0000, v128
	v_lshlrev_b32_e32 v128, 16, v128
	v_pk_fma_f32 v[128:129], v[8:9], v[128:129], v[134:135]
	s_waitcnt vmcnt(18)
; __device__ __forceinline__ float bf2f(bf16_t b) { return __uint_as_float(((unsigned)b) << 16); }
; __device__ __forceinline__ unsigned cvtpk(float lo, float hi) { const f32x2 v = (f32x2){lo, hi}; const bf16v2 b = __builtin_convertvector(v, bf16v2); return __builtin_bit_cast(unsigned, b); }
; __device__ __forceinline__ float geluf_(float x) { const float y = 0.7978845608028654f * (x + 0.044715f * x * x * x); const float t = 1.0f - 2.0f * __builtin_amdgcn_rcpf(__expf(2.0f * y) + 1.0f); return 0.5f * x * (1.0f + t); }
; template <int MODE> __device__ void mixer_lru(const Params& p, int l, int n, LAS unsigned char* lds) {
;     ...
;             for (int i = 0; i < 8; ++i) { const size_t row = (size_t)(t0 + wave * 8 + i);
;                 float v[8]; float ss = 0.f;
; #pragma unroll
;                 for (int k = 0; k < 8; ++k) { v[k] = (bf2f((bf16_t)h0[i][k]) + bf2f((bf16_t)pf[i][k]) * cf[k] + bf2f((bf16_t)pb[i][k]) * cb[k]) * geluf_(bf2f((bf16_t)gt[i][k])); ss += v[k] * v[k]; }
; #pragma unroll
;                 for (int o = 32; o >= 1; o >>= 1) ss += __shfl_xor(ss, o);
;                 const float rs = rsqrtf(ss * (1.0f / 512.0f) + EPS);
;                 *(u32x4*)(y + row * D + ch0) = (u32x4){cvtpk(v[0] * rs * gg[0], v[1] * rs * gg[1]), cvtpk(v[2] * rs * gg[2], v[3] * rs * gg[3]), cvtpk(v[4] * rs * gg[4], v[5] * rs * gg[5]), cvtpk(v[6] * rs * gg[6], v[7] * rs * gg[7])}; }
	v_lshlrev_b32_e32 v134, 16, v127
	v_mul_f32_e32 v135, 0x3d372713, v134
	v_mul_f32_e32 v135, v135, v134
	v_fma_f32 v136, v135, v134, v134
	v_add_f32_e32 v131, 1.0, v131
	v_mul_f32_e32 v135, 0x40135761, v136
	v_rcp_f32_e32 v131, v131
	v_exp_f32_e32 v136, v135
	v_and_b32_e32 v133, 0xffff0000, v132
	v_lshlrev_b32_e32 v132, 16, v132
	v_pk_fma_f32 v[130:131], v[130:131], 2.0, 1.0 op_sel_hi:[1,0,0] neg_lo:[1,0,0] neg_hi:[1,0,0]
	v_pk_fma_f32 v[128:129], v[12:13], v[132:133], v[128:129]
	v_pk_mul_f32 v[132:133], v[178:179], 0.5 op_sel_hi:[1,0]
	v_pk_add_f32 v[130:131], v[130:131], 1.0 op_sel_hi:[1,0]
	v_and_b32_e32 v135, 0xffff0000, v127
	v_pk_mul_f32 v[130:131], v[132:133], v[130:131]
	v_add_f32_e32 v127, 1.0, v136
	v_and_b32_e32 v133, 0xffff0000, v123
	v_lshlrev_b32_e32 v132, 16, v123
	v_mul_f32_e32 v123, 0x3d372713, v135
	v_pk_mul_f32 v[128:129], v[128:129], v[130:131]
	v_rcp_f32_e32 v130, v127
	v_mul_f32_e32 v123, v123, v135
	v_fma_f32 v127, v123, v135, v135
	v_mul_f32_e32 v123, 0x40135761, v127
	v_exp_f32_e32 v123, v123
	v_and_b32_e32 v137, 0xffff0000, v67
	v_lshlrev_b32_e32 v136, 16, v67
	v_pk_mul_f32 v[134:135], v[134:135], 0.5 op_sel_hi:[1,0]
	v_add_f32_e32 v67, 1.0, v123
	v_rcp_f32_e32 v131, v67
	v_pk_fma_f32 v[132:133], v[18:19], v[136:137], v[132:133]
	v_and_b32_e32 v137, 0xffff0000, v71
	v_lshlrev_b32_e32 v136, 16, v71
	v_pk_fma_f32 v[130:131], v[130:131], 2.0, 1.0 op_sel_hi:[1,0,0] neg_lo:[1,0,0] neg_hi:[1,0,0]
	v_and_b32_e32 v123, 0xffff0000, v122
	v_pk_add_f32 v[130:131], v[130:131], 1.0 op_sel_hi:[1,0]
	v_lshlrev_b32_e32 v122, 16, v122
	v_pk_mul_f32 v[130:131], v[134:135], v[130:131]
	v_lshlrev_b32_e32 v134, 16, v126
	v_mul_f32_e32 v67, 0x3d372713, v134
	v_mul_f32_e32 v67, v67, v134
	v_fma_f32 v71, v67, v134, v134
	v_mul_f32_e32 v67, 0x40135761, v71
	v_exp_f32_e32 v67, v67
	v_and_b32_e32 v135, 0xffff0000, v126
	v_mov_b32_e32 v71, v135
	v_pk_fma_f32 v[132:133], v[22:23], v[136:137], v[132:133]
	v_add_f32_e32 v67, 1.0, v67
	v_rcp_f32_e32 v126, v67
	v_mul_f32_e32 v67, 0x3d372713, v135
	v_mul_f32_e32 v67, v67, v135
	v_fmac_f32_e32 v71, v67, v71
	v_mul_f32_e32 v67, 0x40135761, v71
	v_exp_f32_e32 v71, v67
	v_and_b32_e32 v67, 0xffff0000, v66
	v_lshlrev_b32_e32 v66, 16, v66
	v_pk_fma_f32 v[66:67], v[16:17], v[66:67], v[122:123]
	v_add_f32_e32 v71, 1.0, v71
	v_rcp_f32_e32 v127, v71
	v_and_b32_e32 v71, 0xffff0000, v70
	v_lshlrev_b32_e32 v70, 16, v70
	v_pk_fma_f32 v[66:67], v[20:21], v[70:71], v[66:67]
	v_pk_fma_f32 v[70:71], v[126:127], 2.0, 1.0 op_sel_hi:[1,0,0] neg_lo:[1,0,0] neg_hi:[1,0,0]
	v_pk_mul_f32 v[122:123], v[134:135], 0.5 op_sel_hi:[1,0]
	v_pk_add_f32 v[70:71], v[70:71], 1.0 op_sel_hi:[1,0]
	v_pk_mul_f32 v[130:131], v[132:133], v[130:131]
	v_pk_mul_f32 v[70:71], v[122:123], v[70:71]
	v_lshlrev_b32_e32 v122, 16, v125
	v_mul_f32_e32 v123, 0x3d372713, v122
	v_mul_f32_e32 v123, v123, v122
	v_fma_f32 v126, v123, v122, v122
	v_mul_f32_e32 v123, 0x40135761, v126
	v_exp_f32_e32 v126, v123
	v_and_b32_e32 v123, 0xffff0000, v125
	v_pk_mul_f32 v[132:133], v[66:67], v[70:71]
	v_mul_f32_e32 v71, 0x3d372713, v123
	v_add_f32_e32 v70, 1.0, v126
	v_and_b32_e32 v127, 0xffff0000, v121
	v_lshlrev_b32_e32 v126, 16, v121
	v_mul_f32_e32 v71, v71, v123
	v_fma_f32 v121, v71, v123, v123
	v_mul_f32_e32 v71, 0x40135761, v121
	v_exp_f32_e32 v71, v71
	v_and_b32_e32 v135, 0xffff0000, v65
	v_lshlrev_b32_e32 v134, 16, v65
	v_lshlrev_b32_e32 v136, 16, v124
	v_add_f32_e32 v65, 1.0, v71
	v_rcp_f32_e32 v71, v65
	v_mul_f32_e32 v65, 0x3d372713, v136
	v_pk_fma_f32 v[126:127], v[10:11], v[134:135], v[126:127]
	v_and_b32_e32 v135, 0xffff0000, v69
	v_lshlrev_b32_e32 v134, 16, v69
	v_mul_f32_e32 v65, v65, v136
	v_fma_f32 v69, v65, v136, v136
	v_mul_f32_e32 v65, 0x40135761, v69
	v_rcp_f32_e32 v70, v70
	v_exp_f32_e32 v65, v65
	v_pk_fma_f32 v[70:71], v[70:71], 2.0, 1.0 op_sel_hi:[1,0,0] neg_lo:[1,0,0] neg_hi:[1,0,0]
	v_pk_mul_f32 v[122:123], v[122:123], 0.5 op_sel_hi:[1,0]
	v_pk_add_f32 v[70:71], v[70:71], 1.0 op_sel_hi:[1,0]
	v_pk_fma_f32 v[126:127], v[14:15], v[134:135], v[126:127]
	v_pk_mul_f32 v[70:71], v[122:123], v[70:71]
	v_and_b32_e32 v137, 0xffff0000, v124
	v_add_f32_e32 v65, 1.0, v65
	v_pk_mul_f32 v[134:135], v[126:127], v[70:71]
	v_rcp_f32_e32 v70, v65
	v_mul_f32_e32 v65, 0x3d372713, v137
	v_mul_f32_e32 v65, v65, v137
	v_fma_f32 v69, v65, v137, v137
	v_mul_f32_e32 v65, 0x40135761, v69
	v_exp_f32_e32 v69, v65
	v_and_b32_e32 v121, 0xffff0000, v120
	v_lshlrev_b32_e32 v120, 16, v120
	v_and_b32_e32 v65, 0xffff0000, v64
	v_add_f32_e32 v69, 1.0, v69
	v_rcp_f32_e32 v71, v69
	v_lshlrev_b32_e32 v64, 16, v64
	v_pk_fma_f32 v[64:65], v[8:9], v[64:65], v[120:121]
	v_and_b32_e32 v69, 0xffff0000, v68
	v_lshlrev_b32_e32 v68, 16, v68
	v_pk_fma_f32 v[64:65], v[12:13], v[68:69], v[64:65]
	v_pk_fma_f32 v[68:69], v[70:71], 2.0, 1.0 op_sel_hi:[1,0,0] neg_lo:[1,0,0] neg_hi:[1,0,0]
	v_pk_mul_f32 v[70:71], v[136:137], 0.5 op_sel_hi:[1,0]
	v_pk_add_f32 v[68:69], v[68:69], 1.0 op_sel_hi:[1,0]
	v_mov_b32_e32 v121, v129
	v_pk_mul_f32 v[68:69], v[70:71], v[68:69]
	v_mov_b32_e32 v71, v128
	v_pk_mul_f32 v[136:137], v[64:65], v[68:69]
	v_mov_b32_e32 v64, v134
	v_mov_b32_e32 v120, v137
	v_mov_b32_e32 v70, v136
	v_pk_mul_f32 v[120:121], v[120:121], v[120:121]
	v_mov_b32_e32 v65, v170
	v_pk_fma_f32 v[70:71], v[70:71], v[70:71], v[120:121]
	v_pk_mul_f32 v[138:139], v[166:167], v[166:167]
	v_pk_mul_f32 v[66:67], v[132:133], v[132:133]
	v_mov_b32_e32 v68, v135
	v_mov_b32_e32 v69, v171
	v_pk_fma_f32 v[64:65], v[64:65], v[64:65], v[70:71]
	v_pk_mul_f32 v[158:159], v[168:169], v[158:159]
	v_pk_fma_f32 v[64:65], v[68:69], v[68:69], v[64:65]
	v_mov_b32_e32 v68, v66
	v_mov_b32_e32 v69, v138
	v_pk_mul_f32 v[168:169], v[158:159], v[158:159]
	v_pk_mul_f32 v[140:141], v[130:131], v[130:131]
	v_pk_add_f32 v[64:65], v[68:69], v[64:65]
	v_mov_b32_e32 v138, v67
	v_pk_add_f32 v[64:65], v[138:139], v[64:65]
	v_mov_b32_e32 v66, v140
	v_mov_b32_e32 v67, v168
	v_pk_add_f32 v[64:65], v[66:67], v[64:65]
	v_mov_b32_e32 v168, v141
	v_pk_add_f32 v[64:65], v[168:169], v[64:65]
	ds_bpermute_b32 v67, v172, v65
	ds_bpermute_b32 v66, v172, v64
	v_xor_b32_e32 v68, 16, v228
	v_cmp_lt_i32_e32 vcc, v68, v174
	v_mov_b64_e32 v[126:127], s[90:91]
	v_lshl_add_u64 v[24:25], s[94:95], 0, v[144:145]
	v_cndmask_b32_e32 v68, v228, v68, vcc
	v_lshlrev_b32_e32 v143, 2, v68
	s_waitcnt lgkmcnt(0)
; __device__ __forceinline__ float bf2f(bf16_t b) { return __uint_as_float(((unsigned)b) << 16); }
; __device__ __forceinline__ unsigned cvtpk(float lo, float hi) { const f32x2 v = (f32x2){lo, hi}; const bf16v2 b = __builtin_convertvector(v, bf16v2); return __builtin_bit_cast(unsigned, b); }
; __device__ __forceinline__ float geluf_(float x) { const float y = 0.7978845608028654f * (x + 0.044715f * x * x * x); const float t = 1.0f - 2.0f * __builtin_amdgcn_rcpf(__expf(2.0f * y) + 1.0f); return 0.5f * x * (1.0f + t); }
; template <int MODE> __device__ void mixer_lru(const Params& p, int l, int n, LAS unsigned char* lds) {
;     ...
;             for (int i = 0; i < 8; ++i) { const size_t row = (size_t)(t0 + wave * 8 + i);
;                 float v[8]; float ss = 0.f;
; #pragma unroll
;                 for (int k = 0; k < 8; ++k) { v[k] = (bf2f((bf16_t)h0[i][k]) + bf2f((bf16_t)pf[i][k]) * cf[k] + bf2f((bf16_t)pb[i][k]) * cb[k]) * geluf_(bf2f((bf16_t)gt[i][k])); ss += v[k] * v[k]; }
; #pragma unroll
;                 for (int o = 32; o >= 1; o >>= 1) ss += __shfl_xor(ss, o);
;                 const float rs = rsqrtf(ss * (1.0f / 512.0f) + EPS);
;                 *(u32x4*)(y + row * D + ch0) = (u32x4){cvtpk(v[0] * rs * gg[0], v[1] * rs * gg[1]), cvtpk(v[2] * rs * gg[2], v[3] * rs * gg[3]), cvtpk(v[4] * rs * gg[4], v[5] * rs * gg[5]), cvtpk(v[6] * rs * gg[6], v[7] * rs * gg[7])}; }
	v_pk_add_f32 v[64:65], v[64:65], v[66:67]
	ds_bpermute_b32 v67, v143, v65
	ds_bpermute_b32 v66, v143, v64
	v_xor_b32_e32 v68, 8, v228
	v_cmp_lt_i32_e32 vcc, v68, v174
	v_lshl_add_u64 v[24:25], v[24:25], 0, v[176:177]
	global_load_dwordx4 v[36:39], v[28:29], off
	global_load_dwordx4 v[44:47], v[26:27], off offset:1024
	v_cndmask_b32_e32 v68, v228, v68, vcc
	v_lshlrev_b32_e32 v168, 2, v68
	s_waitcnt lgkmcnt(0)
	v_pk_add_f32 v[64:65], v[64:65], v[66:67]
	ds_bpermute_b32 v67, v168, v65
	ds_bpermute_b32 v66, v168, v64
	v_xor_b32_e32 v68, 4, v228
	v_cmp_lt_i32_e32 vcc, v68, v174
	global_load_dwordx4 v[28:31], v[24:25], off
	s_nop 0
	global_load_dwordx4 v[24:27], v[24:25], off offset:1024
	v_cndmask_b32_e32 v68, v228, v68, vcc
	v_lshlrev_b32_e32 v169, 2, v68
	s_waitcnt lgkmcnt(0)
	v_pk_add_f32 v[64:65], v[64:65], v[66:67]
	ds_bpermute_b32 v67, v169, v65
	ds_bpermute_b32 v66, v169, v64
	v_xor_b32_e32 v68, 2, v228
	v_cmp_lt_i32_e32 vcc, v68, v174
	v_lshl_add_u64 v[124:125], s[94:95], 0, v[176:177]
	v_lshl_add_u64 v[140:141], v[124:125], 0, v[160:161]
	v_cndmask_b32_e32 v68, v228, v68, vcc
	v_lshlrev_b32_e32 v173, 2, v68
	s_waitcnt lgkmcnt(0)
	v_pk_add_f32 v[64:65], v[64:65], v[66:67]
	ds_bpermute_b32 v67, v173, v65
	ds_bpermute_b32 v66, v173, v64
	v_xor_b32_e32 v68, 1, v228
	v_cmp_lt_i32_e32 vcc, v68, v174
	s_waitcnt lgkmcnt(0)
	v_pk_add_f32 v[64:65], v[64:65], v[66:67]
	v_cndmask_b32_e32 v68, v228, v68, vcc
	v_lshlrev_b32_e32 v174, 2, v68
	ds_bpermute_b32 v67, v174, v65
	ds_bpermute_b32 v66, v174, v64
	v_add_co_u32_e32 v68, vcc, s84, v164
	s_waitcnt vmcnt(20)
	v_lshlrev_b32_e32 v164, 16, v107
	v_addc_co_u32_e32 v69, vcc, 0, v165, vcc
	s_waitcnt lgkmcnt(0)
	v_pk_add_f32 v[64:65], v[64:65], v[66:67]
	v_and_b32_e32 v165, 0xffff0000, v107
	v_pk_fma_f32 v[138:139], v[64:65], s[88:89], v[126:127] op_sel_hi:[1,0,0]
	s_nop 0
	v_mul_f32_e32 v64, 0x4b800000, v139
	v_cmp_gt_f32_e32 vcc, s25, v139
	s_nop 1
	v_cndmask_b32_e32 v64, v139, v64, vcc
	v_rsq_f32_e32 v120, v64
	global_load_dwordx4 v[64:67], v[162:163], off
	s_nop 0
	global_load_dwordx4 v[68:71], v[68:69], off offset:1024
	v_and_b32_e32 v163, 0xffff0000, v115
	v_lshlrev_b32_e32 v162, 16, v115
	v_mul_f32_e32 v121, 0x45800000, v120
	v_cndmask_b32_e32 v142, v120, v121, vcc
	v_pk_mul_f32 v[120:121], v[128:129], v[142:143] op_sel_hi:[1,0]
	s_waitcnt vmcnt(20)
	v_lshlrev_b32_e32 v128, 16, v119
	v_pk_mul_f32 v[120:121], v[4:5], v[120:121]
	v_mov_b32_e32 v129, v128
	v_cvt_pk_bf16_f32 v120, v120, v121
	v_mul_f32_e32 v121, 0x3d372713, v128
	v_mul_f32_e32 v121, v121, v128
	v_fmac_f32_e32 v129, v121, v129
	v_mul_f32_e32 v121, 0x40135761, v129
	v_exp_f32_e32 v139, v121
	v_and_b32_e32 v129, 0xffff0000, v119
	v_mul_f32_e32 v115, 0x3d372713, v129
	v_mul_f32_e32 v115, v115, v129
	v_add_f32_e32 v119, 1.0, v139
	v_rcp_f32_e32 v160, v119
	v_fma_f32 v119, v115, v129, v129
	v_mul_f32_e32 v115, 0x40135761, v119
	v_exp_f32_e32 v115, v115
	v_pk_fma_f32 v[162:163], v[18:19], v[164:165], v[162:163]
	v_and_b32_e32 v165, 0xffff0000, v111
	v_lshlrev_b32_e32 v164, 16, v111
	v_add_f32_e32 v107, 1.0, v115
	v_pk_fma_f32 v[162:163], v[22:23], v[164:165], v[162:163]
	v_lshlrev_b32_e32 v164, 16, v118
	v_rcp_f32_e32 v161, v107
	v_mul_f32_e32 v107, 0x3d372713, v164
	v_mul_f32_e32 v107, v107, v164
	v_fma_f32 v111, v107, v164, v164
	v_mul_f32_e32 v107, 0x40135761, v111
	v_exp_f32_e32 v107, v107
	v_and_b32_e32 v165, 0xffff0000, v118
	v_mov_b32_e32 v111, v165
	v_and_b32_e32 v115, 0xffff0000, v114
	v_add_f32_e32 v107, 1.0, v107
	v_rcp_f32_e32 v118, v107
	v_mul_f32_e32 v107, 0x3d372713, v165
	v_mul_f32_e32 v107, v107, v165
	v_fmac_f32_e32 v111, v107, v111
	v_mul_f32_e32 v107, 0x40135761, v111
	v_exp_f32_e32 v111, v107
	v_lshlrev_b32_e32 v114, 16, v114
	v_and_b32_e32 v107, 0xffff0000, v106
	v_lshlrev_b32_e32 v106, 16, v106
	v_add_f32_e32 v111, 1.0, v111
	v_rcp_f32_e32 v119, v111
	v_pk_fma_f32 v[106:107], v[16:17], v[106:107], v[114:115]
	v_and_b32_e32 v111, 0xffff0000, v110
	v_lshlrev_b32_e32 v110, 16, v110
	v_pk_fma_f32 v[106:107], v[20:21], v[110:111], v[106:107]
	v_pk_fma_f32 v[110:111], v[118:119], 2.0, 1.0 op_sel_hi:[1,0,0] neg_lo:[1,0,0] neg_hi:[1,0,0]
	v_pk_mul_f32 v[114:115], v[164:165], 0.5 op_sel_hi:[1,0]
	v_pk_add_f32 v[110:111], v[110:111], 1.0 op_sel_hi:[1,0]
	v_pk_fma_f32 v[160:161], v[160:161], 2.0, 1.0 op_sel_hi:[1,0,0] neg_lo:[1,0,0] neg_hi:[1,0,0]
	v_pk_mul_f32 v[110:111], v[114:115], v[110:111]
	v_lshlrev_b32_e32 v114, 16, v117
	v_mul_f32_e32 v115, 0x3d372713, v114
	v_mul_f32_e32 v115, v115, v114
	v_fma_f32 v118, v115, v114, v114
	v_mul_f32_e32 v115, 0x40135761, v118
	v_exp_f32_e32 v118, v115
	v_pk_mul_f32 v[128:129], v[128:129], 0.5 op_sel_hi:[1,0]
	v_pk_add_f32 v[160:161], v[160:161], 1.0 op_sel_hi:[1,0]
	v_and_b32_e32 v115, 0xffff0000, v117
	v_pk_mul_f32 v[128:129], v[128:129], v[160:161]
	v_add_f32_e32 v117, 1.0, v118
	v_pk_mul_f32 v[128:129], v[162:163], v[128:129]
	v_and_b32_e32 v163, 0xffff0000, v113
	v_lshlrev_b32_e32 v162, 16, v113
	v_mul_f32_e32 v113, 0x3d372713, v115
	v_rcp_f32_e32 v118, v117
	v_mul_f32_e32 v113, v113, v115
	v_fma_f32 v117, v113, v115, v115
	v_mul_f32_e32 v113, 0x40135761, v117
	v_exp_f32_e32 v113, v113
	v_and_b32_e32 v165, 0xffff0000, v105
	v_lshlrev_b32_e32 v164, 16, v105
	v_pk_fma_f32 v[162:163], v[10:11], v[164:165], v[162:163]
	v_and_b32_e32 v165, 0xffff0000, v109
	v_lshlrev_b32_e32 v164, 16, v109
	v_add_f32_e32 v105, 1.0, v113
	v_pk_fma_f32 v[162:163], v[14:15], v[164:165], v[162:163]
	v_lshlrev_b32_e32 v164, 16, v116
	v_rcp_f32_e32 v119, v105
	v_mul_f32_e32 v105, 0x3d372713, v164
	v_mul_f32_e32 v105, v105, v164
	v_fma_f32 v109, v105, v164, v164
	v_mul_f32_e32 v105, 0x40135761, v109
	v_exp_f32_e32 v105, v105
	v_and_b32_e32 v165, 0xffff0000, v116
	v_mov_b32_e32 v109, v165
	v_and_b32_e32 v113, 0xffff0000, v112
	v_add_f32_e32 v105, 1.0, v105
	v_rcp_f32_e32 v116, v105
	v_mul_f32_e32 v105, 0x3d372713, v165
	v_mul_f32_e32 v105, v105, v165
	v_fmac_f32_e32 v109, v105, v109
	v_mul_f32_e32 v105, 0x40135761, v109
	v_exp_f32_e32 v109, v105
	v_lshlrev_b32_e32 v112, 16, v112
	v_and_b32_e32 v105, 0xffff0000, v104
	v_lshlrev_b32_e32 v104, 16, v104
	v_add_f32_e32 v109, 1.0, v109
	v_rcp_f32_e32 v117, v109
	v_pk_fma_f32 v[104:105], v[8:9], v[104:105], v[112:113]
	v_and_b32_e32 v109, 0xffff0000, v108
	v_lshlrev_b32_e32 v108, 16, v108
	v_pk_fma_f32 v[118:119], v[118:119], 2.0, 1.0 op_sel_hi:[1,0,0] neg_lo:[1,0,0] neg_hi:[1,0,0]
	v_pk_fma_f32 v[104:105], v[12:13], v[108:109], v[104:105]
	v_pk_fma_f32 v[108:109], v[116:117], 2.0, 1.0 op_sel_hi:[1,0,0] neg_lo:[1,0,0] neg_hi:[1,0,0]
	s_waitcnt vmcnt(16)
; __device__ __forceinline__ float bf2f(bf16_t b) { return __uint_as_float(((unsigned)b) << 16); }
; __device__ __forceinline__ unsigned cvtpk(float lo, float hi) { const f32x2 v = (f32x2){lo, hi}; const bf16v2 b = __builtin_convertvector(v, bf16v2); return __builtin_bit_cast(unsigned, b); }
; __device__ __forceinline__ float geluf_(float x) { const float y = 0.7978845608028654f * (x + 0.044715f * x * x * x); const float t = 1.0f - 2.0f * __builtin_amdgcn_rcpf(__expf(2.0f * y) + 1.0f); return 0.5f * x * (1.0f + t); }
; template <int MODE> __device__ void mixer_lru(const Params& p, int l, int n, LAS unsigned char* lds) {
;     ...
;             for (int i = 0; i < 8; ++i) { const size_t row = (size_t)(t0 + wave * 8 + i);
;                 float v[8]; float ss = 0.f;
; #pragma unroll
;                 for (int k = 0; k < 8; ++k) { v[k] = (bf2f((bf16_t)h0[i][k]) + bf2f((bf16_t)pf[i][k]) * cf[k] + bf2f((bf16_t)pb[i][k]) * cb[k]) * geluf_(bf2f((bf16_t)gt[i][k])); ss += v[k] * v[k]; }
; #pragma unroll
;                 for (int o = 32; o >= 1; o >>= 1) ss += __shfl_xor(ss, o);
;                 const float rs = rsqrtf(ss * (1.0f / 512.0f) + EPS);
;                 *(u32x4*)(y + row * D + ch0) = (u32x4){cvtpk(v[0] * rs * gg[0], v[1] * rs * gg[1]), cvtpk(v[2] * rs * gg[2], v[3] * rs * gg[3]), cvtpk(v[4] * rs * gg[4], v[5] * rs * gg[5]), cvtpk(v[6] * rs * gg[6], v[7] * rs * gg[7])}; }
	v_lshlrev_b32_e32 v116, 16, v103
	v_pk_mul_f32 v[114:115], v[114:115], 0.5 op_sel_hi:[1,0]
	v_pk_add_f32 v[118:119], v[118:119], 1.0 op_sel_hi:[1,0]
	v_mul_f32_e32 v117, 0x3d372713, v116
	v_pk_mul_f32 v[114:115], v[114:115], v[118:119]
	v_mul_f32_e32 v117, v117, v116
	v_fma_f32 v118, v117, v116, v116
	v_mul_f32_e32 v117, 0x40135761, v118
	v_exp_f32_e32 v118, v117
	v_pk_mul_f32 v[112:113], v[164:165], 0.5 op_sel_hi:[1,0]
	v_pk_add_f32 v[108:109], v[108:109], 1.0 op_sel_hi:[1,0]
	v_and_b32_e32 v117, 0xffff0000, v103
	v_pk_mul_f32 v[108:109], v[112:113], v[108:109]
	v_add_f32_e32 v103, 1.0, v118
	v_and_b32_e32 v113, 0xffff0000, v99
	v_lshlrev_b32_e32 v112, 16, v99
	v_mul_f32_e32 v99, 0x3d372713, v117
	v_pk_mul_f32 v[108:109], v[104:105], v[108:109]
	v_rcp_f32_e32 v104, v103
	v_mul_f32_e32 v99, v99, v117
	v_fma_f32 v103, v99, v117, v117
	v_mul_f32_e32 v99, 0x40135761, v103
	v_exp_f32_e32 v99, v99
	v_and_b32_e32 v119, 0xffff0000, v91
	v_lshlrev_b32_e32 v118, 16, v91
	v_pk_mul_f32 v[116:117], v[116:117], 0.5 op_sel_hi:[1,0]
	v_add_f32_e32 v91, 1.0, v99
	v_rcp_f32_e32 v105, v91
	v_pk_fma_f32 v[112:113], v[18:19], v[118:119], v[112:113]
	v_and_b32_e32 v119, 0xffff0000, v95
	v_lshlrev_b32_e32 v118, 16, v95
	v_pk_fma_f32 v[104:105], v[104:105], 2.0, 1.0 op_sel_hi:[1,0,0] neg_lo:[1,0,0] neg_hi:[1,0,0]
	v_and_b32_e32 v99, 0xffff0000, v98
	v_pk_add_f32 v[104:105], v[104:105], 1.0 op_sel_hi:[1,0]
	v_lshlrev_b32_e32 v98, 16, v98
	v_pk_mul_f32 v[104:105], v[116:117], v[104:105]
	v_lshlrev_b32_e32 v116, 16, v102
	v_mul_f32_e32 v91, 0x3d372713, v116
	v_mul_f32_e32 v91, v91, v116
	v_fma_f32 v95, v91, v116, v116
	v_mul_f32_e32 v91, 0x40135761, v95
	v_exp_f32_e32 v91, v91
	v_and_b32_e32 v117, 0xffff0000, v102
	v_mov_b32_e32 v95, v117
	v_pk_fma_f32 v[112:113], v[22:23], v[118:119], v[112:113]
	v_add_f32_e32 v91, 1.0, v91
	v_rcp_f32_e32 v102, v91
	v_mul_f32_e32 v91, 0x3d372713, v117
	v_mul_f32_e32 v91, v91, v117
	v_fmac_f32_e32 v95, v91, v95
	v_mul_f32_e32 v91, 0x40135761, v95
	v_exp_f32_e32 v95, v91
	v_and_b32_e32 v91, 0xffff0000, v90
	v_lshlrev_b32_e32 v90, 16, v90
	v_pk_fma_f32 v[90:91], v[16:17], v[90:91], v[98:99]
	v_add_f32_e32 v95, 1.0, v95
	v_rcp_f32_e32 v103, v95
	v_and_b32_e32 v95, 0xffff0000, v94
	v_lshlrev_b32_e32 v94, 16, v94
	v_pk_fma_f32 v[90:91], v[20:21], v[94:95], v[90:91]
	v_pk_fma_f32 v[94:95], v[102:103], 2.0, 1.0 op_sel_hi:[1,0,0] neg_lo:[1,0,0] neg_hi:[1,0,0]
	v_pk_mul_f32 v[98:99], v[116:117], 0.5 op_sel_hi:[1,0]
	v_pk_add_f32 v[94:95], v[94:95], 1.0 op_sel_hi:[1,0]
	v_and_b32_e32 v117, 0xffff0000, v97
	v_pk_mul_f32 v[94:95], v[98:99], v[94:95]
	v_lshlrev_b32_e32 v98, 16, v101
	v_mul_f32_e32 v99, 0x3d372713, v98
	v_mul_f32_e32 v99, v99, v98
	v_fma_f32 v102, v99, v98, v98
	v_mul_f32_e32 v99, 0x40135761, v102
	v_exp_f32_e32 v102, v99
	v_and_b32_e32 v99, 0xffff0000, v101
	v_lshlrev_b32_e32 v116, 16, v97
	v_mul_f32_e32 v97, 0x3d372713, v99
	v_add_f32_e32 v101, 1.0, v102
	v_rcp_f32_e32 v102, v101
	v_mul_f32_e32 v97, v97, v99
	v_fma_f32 v101, v97, v99, v99
	v_mul_f32_e32 v97, 0x40135761, v101
	v_exp_f32_e32 v97, v97
	v_and_b32_e32 v119, 0xffff0000, v89
	v_lshlrev_b32_e32 v118, 16, v89
	v_pk_fma_f32 v[116:117], v[10:11], v[118:119], v[116:117]
	v_and_b32_e32 v119, 0xffff0000, v93
	v_lshlrev_b32_e32 v118, 16, v93
	v_add_f32_e32 v89, 1.0, v97
	v_pk_fma_f32 v[116:117], v[14:15], v[118:119], v[116:117]
	v_lshlrev_b32_e32 v118, 16, v100
	v_rcp_f32_e32 v103, v89
	v_mul_f32_e32 v89, 0x3d372713, v118
	v_mul_f32_e32 v89, v89, v118
	v_fma_f32 v93, v89, v118, v118
	v_mul_f32_e32 v89, 0x40135761, v93
	v_exp_f32_e32 v89, v89
	v_and_b32_e32 v119, 0xffff0000, v100
	v_mov_b32_e32 v93, v119
	v_and_b32_e32 v97, 0xffff0000, v96
	v_add_f32_e32 v89, 1.0, v89
	v_rcp_f32_e32 v100, v89
	v_mul_f32_e32 v89, 0x3d372713, v119
	v_mul_f32_e32 v89, v89, v119
	v_fmac_f32_e32 v93, v89, v93
	v_mul_f32_e32 v89, 0x40135761, v93
	v_exp_f32_e32 v93, v89
	v_lshlrev_b32_e32 v96, 16, v96
	v_and_b32_e32 v89, 0xffff0000, v88
	v_lshlrev_b32_e32 v88, 16, v88
	v_add_f32_e32 v93, 1.0, v93
	v_rcp_f32_e32 v101, v93
	v_pk_fma_f32 v[88:89], v[8:9], v[88:89], v[96:97]
	v_and_b32_e32 v93, 0xffff0000, v92
	v_lshlrev_b32_e32 v92, 16, v92
	v_pk_fma_f32 v[88:89], v[12:13], v[92:93], v[88:89]
	v_pk_fma_f32 v[92:93], v[100:101], 2.0, 1.0 op_sel_hi:[1,0,0] neg_lo:[1,0,0] neg_hi:[1,0,0]
	v_pk_mul_f32 v[96:97], v[118:119], 0.5 op_sel_hi:[1,0]
	v_pk_add_f32 v[92:93], v[92:93], 1.0 op_sel_hi:[1,0]
	v_pk_fma_f32 v[102:103], v[102:103], 2.0, 1.0 op_sel_hi:[1,0,0] neg_lo:[1,0,0] neg_hi:[1,0,0]
	v_pk_mul_f32 v[92:93], v[96:97], v[92:93]
	v_pk_mul_f32 v[98:99], v[98:99], 0.5 op_sel_hi:[1,0]
	v_pk_add_f32 v[102:103], v[102:103], 1.0 op_sel_hi:[1,0]
	v_pk_mul_f32 v[96:97], v[88:89], v[92:93]
	v_pk_mul_f32 v[98:99], v[98:99], v[102:103]
	v_mov_b32_e32 v102, v97
	v_mov_b32_e32 v103, v109
	v_pk_mul_f32 v[114:115], v[162:163], v[114:115]
	v_pk_mul_f32 v[98:99], v[116:117], v[98:99]
	v_mov_b32_e32 v100, v96
	v_mov_b32_e32 v101, v108
	v_pk_mul_f32 v[102:103], v[102:103], v[102:103]
	v_pk_mul_f32 v[110:111], v[106:107], v[110:111]
	v_pk_mul_f32 v[94:95], v[90:91], v[94:95]
	v_mov_b32_e32 v88, v98
	v_mov_b32_e32 v89, v114
	v_pk_fma_f32 v[100:101], v[100:101], v[100:101], v[102:103]
	v_pk_mul_f32 v[106:107], v[110:111], v[110:111]
	v_pk_mul_f32 v[90:91], v[94:95], v[94:95]
	v_mov_b32_e32 v92, v99
	v_mov_b32_e32 v93, v115
	v_pk_fma_f32 v[88:89], v[88:89], v[88:89], v[100:101]
	v_pk_mul_f32 v[104:105], v[112:113], v[104:105]
	v_pk_fma_f32 v[88:89], v[92:93], v[92:93], v[88:89]
	v_mov_b32_e32 v92, v90
	v_mov_b32_e32 v93, v106
	v_pk_mul_f32 v[160:161], v[128:129], v[128:129]
	v_pk_mul_f32 v[112:113], v[104:105], v[104:105]
	v_pk_add_f32 v[88:89], v[92:93], v[88:89]
	v_mov_b32_e32 v106, v91
	v_pk_add_f32 v[88:89], v[106:107], v[88:89]
	v_mov_b32_e32 v90, v112
	v_mov_b32_e32 v91, v160
	v_pk_add_f32 v[88:89], v[90:91], v[88:89]
	v_mov_b32_e32 v160, v113
	v_pk_add_f32 v[88:89], v[160:161], v[88:89]
	ds_bpermute_b32 v91, v172, v89
	ds_bpermute_b32 v90, v172, v88
	v_pk_mul_f32 v[122:123], v[170:171], v[142:143] op_sel_hi:[1,0]
	v_mul_f32_e32 v100, 0x4b800000, v138
	v_cmp_gt_f32_e32 vcc, s25, v138
	v_pk_mul_f32 v[122:123], v[6:7], v[122:123]
	s_waitcnt lgkmcnt(0)
; __device__ __forceinline__ float bf2f(bf16_t b) { return __uint_as_float(((unsigned)b) << 16); }
; __device__ __forceinline__ unsigned cvtpk(float lo, float hi) { const f32x2 v = (f32x2){lo, hi}; const bf16v2 b = __builtin_convertvector(v, bf16v2); return __builtin_bit_cast(unsigned, b); }
; __device__ __forceinline__ float geluf_(float x) { const float y = 0.7978845608028654f * (x + 0.044715f * x * x * x); const float t = 1.0f - 2.0f * __builtin_amdgcn_rcpf(__expf(2.0f * y) + 1.0f); return 0.5f * x * (1.0f + t); }
; template <int MODE> __device__ void mixer_lru(const Params& p, int l, int n, LAS unsigned char* lds) {
;     ...
;             for (int i = 0; i < 8; ++i) { const size_t row = (size_t)(t0 + wave * 8 + i);
;                 float v[8]; float ss = 0.f;
; #pragma unroll
;                 for (int k = 0; k < 8; ++k) { v[k] = (bf2f((bf16_t)h0[i][k]) + bf2f((bf16_t)pf[i][k]) * cf[k] + bf2f((bf16_t)pb[i][k]) * cb[k]) * geluf_(bf2f((bf16_t)gt[i][k])); ss += v[k] * v[k]; }
; #pragma unroll
;                 for (int o = 32; o >= 1; o >>= 1) ss += __shfl_xor(ss, o);
;                 const float rs = rsqrtf(ss * (1.0f / 512.0f) + EPS);
;                 *(u32x4*)(y + row * D + ch0) = (u32x4){cvtpk(v[0] * rs * gg[0], v[1] * rs * gg[1]), cvtpk(v[2] * rs * gg[2], v[3] * rs * gg[3]), cvtpk(v[4] * rs * gg[4], v[5] * rs * gg[5]), cvtpk(v[6] * rs * gg[6], v[7] * rs * gg[7])}; }
	v_pk_add_f32 v[88:89], v[88:89], v[90:91]
	ds_bpermute_b32 v91, v143, v89
	ds_bpermute_b32 v90, v143, v88
	v_cndmask_b32_e32 v100, v138, v100, vcc
	v_cvt_pk_bf16_f32 v121, v122, v123
	v_pk_mul_f32 v[122:123], v[166:167], v[142:143] op_sel_hi:[1,0]
	v_rsq_f32_e32 v100, v100
	s_waitcnt lgkmcnt(0)
	v_pk_add_f32 v[88:89], v[88:89], v[90:91]
	ds_bpermute_b32 v91, v168, v89
	ds_bpermute_b32 v90, v168, v88
	v_pk_mul_f32 v[92:93], v[0:1], v[122:123]
	s_waitcnt vmcnt(14)
	v_and_b32_e32 v113, 0xffff0000, v75
	v_cvt_pk_bf16_f32 v122, v92, v93
	v_pk_mul_f32 v[92:93], v[158:159], v[142:143] op_sel_hi:[1,0]
	s_waitcnt lgkmcnt(0)
	v_pk_add_f32 v[90:91], v[88:89], v[90:91]
	v_pk_mul_f32 v[92:93], v[2:3], v[92:93]
	ds_bpermute_b32 v101, v169, v91
	v_cvt_pk_bf16_f32 v123, v92, v93
	v_mul_f32_e32 v92, 0x45800000, v100
	v_cndmask_b32_e32 v92, v100, v92, vcc
	ds_bpermute_b32 v100, v169, v90
	v_pk_mul_f32 v[88:89], v[136:137], v[92:93] op_sel_hi:[1,0]
	v_pk_mul_f32 v[102:103], v[134:135], v[92:93] op_sel_hi:[1,0]
	v_pk_mul_f32 v[88:89], v[4:5], v[88:89]
	v_pk_mul_f32 v[102:103], v[6:7], v[102:103]
	s_waitcnt lgkmcnt(0)
	v_pk_add_f32 v[90:91], v[90:91], v[100:101]
	ds_bpermute_b32 v101, v173, v91
	ds_bpermute_b32 v100, v173, v90
	v_cvt_pk_bf16_f32 v88, v88, v89
	v_cvt_pk_bf16_f32 v89, v102, v103
	v_pk_mul_f32 v[102:103], v[132:133], v[92:93] op_sel_hi:[1,0]
	v_pk_mul_f32 v[92:93], v[130:131], v[92:93] op_sel_hi:[1,0]
	s_waitcnt lgkmcnt(0)
	v_pk_add_f32 v[100:101], v[90:91], v[100:101]
	ds_bpermute_b32 v107, v174, v101
	ds_bpermute_b32 v106, v174, v100
	v_pk_mul_f32 v[92:93], v[2:3], v[92:93]
	v_pk_mul_f32 v[102:103], v[0:1], v[102:103]
	v_cvt_pk_bf16_f32 v91, v92, v93
	v_cvt_pk_bf16_f32 v90, v102, v103
	s_waitcnt lgkmcnt(0)
	v_pk_add_f32 v[92:93], v[100:101], v[106:107]
	v_lshlrev_b32_e32 v112, 16, v75
	v_pk_fma_f32 v[102:103], v[92:93], s[88:89], v[126:127] op_sel_hi:[1,0,0]
	v_lshl_add_u64 v[100:101], v[124:125], 0, v[156:157]
	v_mul_f32_e32 v92, 0x4b800000, v103
	v_cmp_gt_f32_e32 vcc, s25, v103
	global_store_dwordx4 v[140:141], v[120:123], off
	s_nop 0
	v_cndmask_b32_e32 v92, v103, v92, vcc
	v_rsq_f32_e32 v103, v92
	v_lshl_add_u64 v[92:93], v[124:125], 0, v[154:155]
	global_store_dwordx4 v[92:93], v[88:91], off
	s_waitcnt vmcnt(14)
	v_lshlrev_b32_e32 v92, 16, v87
	v_mov_b32_e32 v93, v92
	v_mul_f32_e32 v88, 0x45800000, v103
	v_cndmask_b32_e32 v106, v103, v88, vcc
	v_pk_mul_f32 v[88:89], v[108:109], v[106:107] op_sel_hi:[1,0]
	v_pk_mul_f32 v[90:91], v[114:115], v[106:107] op_sel_hi:[1,0]
	v_pk_mul_f32 v[88:89], v[4:5], v[88:89]
	v_pk_mul_f32 v[90:91], v[6:7], v[90:91]
	v_cvt_pk_bf16_f32 v88, v88, v89
	v_mul_f32_e32 v89, 0x3d372713, v92
	v_mul_f32_e32 v89, v89, v92
	v_fmac_f32_e32 v93, v89, v93
	v_mul_f32_e32 v89, 0x40135761, v93
	v_exp_f32_e32 v103, v89
	v_and_b32_e32 v93, 0xffff0000, v87
	v_cvt_pk_bf16_f32 v89, v90, v91
	v_pk_mul_f32 v[90:91], v[110:111], v[106:107] op_sel_hi:[1,0]
	v_add_f32_e32 v87, 1.0, v103
	v_and_b32_e32 v111, 0xffff0000, v83
	v_lshlrev_b32_e32 v110, 16, v83
	v_mul_f32_e32 v83, 0x3d372713, v93
	v_rcp_f32_e32 v108, v87
	v_mul_f32_e32 v83, v83, v93
	v_fma_f32 v87, v83, v93, v93
	v_mul_f32_e32 v83, 0x40135761, v87
	v_exp_f32_e32 v83, v83
	v_pk_fma_f32 v[110:111], v[18:19], v[112:113], v[110:111]
	v_and_b32_e32 v113, 0xffff0000, v79
	v_lshlrev_b32_e32 v112, 16, v79
	v_add_f32_e32 v75, 1.0, v83
	v_pk_fma_f32 v[110:111], v[22:23], v[112:113], v[110:111]
	v_lshlrev_b32_e32 v112, 16, v86
	v_rcp_f32_e32 v109, v75
	v_mul_f32_e32 v75, 0x3d372713, v112
	v_mul_f32_e32 v75, v75, v112
	v_fma_f32 v79, v75, v112, v112
	v_mul_f32_e32 v75, 0x40135761, v79
	v_exp_f32_e32 v75, v75
	v_and_b32_e32 v113, 0xffff0000, v86
	v_mov_b32_e32 v79, v113
	v_and_b32_e32 v83, 0xffff0000, v82
	v_add_f32_e32 v75, 1.0, v75
	v_rcp_f32_e32 v86, v75
	v_mul_f32_e32 v75, 0x3d372713, v113
	v_mul_f32_e32 v75, v75, v113
	v_fmac_f32_e32 v79, v75, v79
	v_mul_f32_e32 v75, 0x40135761, v79
	v_exp_f32_e32 v79, v75
	v_lshlrev_b32_e32 v82, 16, v82
	v_and_b32_e32 v75, 0xffff0000, v74
	v_lshlrev_b32_e32 v74, 16, v74
	v_add_f32_e32 v79, 1.0, v79
	v_rcp_f32_e32 v87, v79
	v_pk_fma_f32 v[74:75], v[16:17], v[74:75], v[82:83]
	v_and_b32_e32 v79, 0xffff0000, v78
	v_lshlrev_b32_e32 v78, 16, v78
	v_pk_fma_f32 v[74:75], v[20:21], v[78:79], v[74:75]
	v_pk_fma_f32 v[78:79], v[86:87], 2.0, 1.0 op_sel_hi:[1,0,0] neg_lo:[1,0,0] neg_hi:[1,0,0]
	v_pk_fma_f32 v[108:109], v[108:109], 2.0, 1.0 op_sel_hi:[1,0,0] neg_lo:[1,0,0] neg_hi:[1,0,0]
	v_pk_mul_f32 v[82:83], v[112:113], 0.5 op_sel_hi:[1,0]
	v_pk_add_f32 v[78:79], v[78:79], 1.0 op_sel_hi:[1,0]
	v_pk_mul_f32 v[92:93], v[92:93], 0.5 op_sel_hi:[1,0]
	v_pk_add_f32 v[108:109], v[108:109], 1.0 op_sel_hi:[1,0]
	v_pk_mul_f32 v[78:79], v[82:83], v[78:79]
	v_and_b32_e32 v87, 0xffff0000, v85
	v_pk_mul_f32 v[92:93], v[92:93], v[108:109]
	v_pk_mul_f32 v[74:75], v[74:75], v[78:79]
	v_mul_f32_e32 v79, 0x3d372713, v87
	v_pk_mul_f32 v[92:93], v[110:111], v[92:93]
	v_and_b32_e32 v111, 0xffff0000, v81
	v_lshlrev_b32_e32 v110, 16, v81
	v_mul_f32_e32 v79, v79, v87
	v_fma_f32 v81, v79, v87, v87
	v_mul_f32_e32 v79, 0x40135761, v81
	v_exp_f32_e32 v79, v79
	v_and_b32_e32 v113, 0xffff0000, v73
	v_lshlrev_b32_e32 v112, 16, v73
	v_pk_fma_f32 v[110:111], v[10:11], v[112:113], v[110:111]
	v_and_b32_e32 v113, 0xffff0000, v77
	v_lshlrev_b32_e32 v112, 16, v77
	v_add_f32_e32 v73, 1.0, v79
	v_pk_fma_f32 v[110:111], v[14:15], v[112:113], v[110:111]
	v_lshlrev_b32_e32 v112, 16, v84
	v_rcp_f32_e32 v79, v73
	v_mul_f32_e32 v73, 0x3d372713, v112
	v_mul_f32_e32 v73, v73, v112
	v_fma_f32 v77, v73, v112, v112
	v_mul_f32_e32 v73, 0x40135761, v77
	v_exp_f32_e32 v73, v73
	v_lshlrev_b32_e32 v86, 16, v85
	v_and_b32_e32 v113, 0xffff0000, v84
	v_mul_f32_e32 v82, 0x3d372713, v86
	v_add_f32_e32 v73, 1.0, v73
	v_rcp_f32_e32 v84, v73
	v_mul_f32_e32 v73, 0x3d372713, v113
	v_mul_f32_e32 v82, v82, v86
	v_mov_b32_e32 v83, v86
	v_mul_f32_e32 v73, v73, v113
	v_mov_b32_e32 v77, v113
	v_fmac_f32_e32 v83, v82, v83
	v_fmac_f32_e32 v77, v73, v77
	v_mul_f32_e32 v82, 0x40135761, v83
	v_mul_f32_e32 v73, 0x40135761, v77
	v_exp_f32_e32 v103, v82
	v_exp_f32_e32 v77, v73
	v_and_b32_e32 v81, 0xffff0000, v80
	v_lshlrev_b32_e32 v80, 16, v80
	v_add_f32_e32 v78, 1.0, v103
	v_add_f32_e32 v77, 1.0, v77
	v_rcp_f32_e32 v78, v78
	v_rcp_f32_e32 v85, v77
	v_and_b32_e32 v73, 0xffff0000, v72
	v_lshlrev_b32_e32 v72, 16, v72
	v_pk_fma_f32 v[72:73], v[8:9], v[72:73], v[80:81]
	v_and_b32_e32 v77, 0xffff0000, v76
	v_lshlrev_b32_e32 v76, 16, v76
	v_pk_fma_f32 v[78:79], v[78:79], 2.0, 1.0 op_sel_hi:[1,0,0] neg_lo:[1,0,0] neg_hi:[1,0,0]
	v_pk_fma_f32 v[72:73], v[12:13], v[76:77], v[72:73]
	v_pk_fma_f32 v[76:77], v[84:85], 2.0, 1.0 op_sel_hi:[1,0,0] neg_lo:[1,0,0] neg_hi:[1,0,0]
	s_waitcnt vmcnt(10)
; __device__ __forceinline__ float bf2f(bf16_t b) { return __uint_as_float(((unsigned)b) << 16); }
; __device__ __forceinline__ unsigned cvtpk(float lo, float hi) { const f32x2 v = (f32x2){lo, hi}; const bf16v2 b = __builtin_convertvector(v, bf16v2); return __builtin_bit_cast(unsigned, b); }
; __device__ __forceinline__ float geluf_(float x) { const float y = 0.7978845608028654f * (x + 0.044715f * x * x * x); const float t = 1.0f - 2.0f * __builtin_amdgcn_rcpf(__expf(2.0f * y) + 1.0f); return 0.5f * x * (1.0f + t); }
; template <int MODE> __device__ void mixer_lru(const Params& p, int l, int n, LAS unsigned char* lds) {
;     ...
;             for (int i = 0; i < 8; ++i) { const size_t row = (size_t)(t0 + wave * 8 + i);
;                 float v[8]; float ss = 0.f;
; #pragma unroll
;                 for (int k = 0; k < 8; ++k) { v[k] = (bf2f((bf16_t)h0[i][k]) + bf2f((bf16_t)pf[i][k]) * cf[k] + bf2f((bf16_t)pb[i][k]) * cb[k]) * geluf_(bf2f((bf16_t)gt[i][k])); ss += v[k] * v[k]; }
; #pragma unroll
;                 for (int o = 32; o >= 1; o >>= 1) ss += __shfl_xor(ss, o);
;                 const float rs = rsqrtf(ss * (1.0f / 512.0f) + EPS);
;                 *(u32x4*)(y + row * D + ch0) = (u32x4){cvtpk(v[0] * rs * gg[0], v[1] * rs * gg[1]), cvtpk(v[2] * rs * gg[2], v[3] * rs * gg[3]), cvtpk(v[4] * rs * gg[4], v[5] * rs * gg[5]), cvtpk(v[6] * rs * gg[6], v[7] * rs * gg[7])}; }
	v_lshlrev_b32_e32 v84, 16, v63
	v_pk_mul_f32 v[86:87], v[86:87], 0.5 op_sel_hi:[1,0]
	v_pk_add_f32 v[78:79], v[78:79], 1.0 op_sel_hi:[1,0]
	v_mul_f32_e32 v85, 0x3d372713, v84
	v_pk_mul_f32 v[78:79], v[86:87], v[78:79]
	v_mul_f32_e32 v85, v85, v84
	v_fma_f32 v86, v85, v84, v84
	v_mul_f32_e32 v85, 0x40135761, v86
	v_exp_f32_e32 v86, v85
	v_pk_mul_f32 v[80:81], v[112:113], 0.5 op_sel_hi:[1,0]
	v_pk_add_f32 v[76:77], v[76:77], 1.0 op_sel_hi:[1,0]
	v_and_b32_e32 v85, 0xffff0000, v63
	v_pk_mul_f32 v[76:77], v[80:81], v[76:77]
	v_add_f32_e32 v63, 1.0, v86
	v_and_b32_e32 v81, 0xffff0000, v59
	v_lshlrev_b32_e32 v80, 16, v59
	v_mul_f32_e32 v59, 0x3d372713, v85
	v_pk_mul_f32 v[76:77], v[72:73], v[76:77]
	v_rcp_f32_e32 v72, v63
	v_mul_f32_e32 v59, v59, v85
	v_fma_f32 v63, v59, v85, v85
	v_mul_f32_e32 v59, 0x40135761, v63
	v_exp_f32_e32 v59, v59
	v_and_b32_e32 v87, 0xffff0000, v51
	v_lshlrev_b32_e32 v86, 16, v51
	v_pk_mul_f32 v[84:85], v[84:85], 0.5 op_sel_hi:[1,0]
	v_add_f32_e32 v51, 1.0, v59
	v_rcp_f32_e32 v73, v51
	v_pk_fma_f32 v[80:81], v[18:19], v[86:87], v[80:81]
	v_and_b32_e32 v87, 0xffff0000, v55
	v_lshlrev_b32_e32 v86, 16, v55
	v_pk_fma_f32 v[72:73], v[72:73], 2.0, 1.0 op_sel_hi:[1,0,0] neg_lo:[1,0,0] neg_hi:[1,0,0]
	v_and_b32_e32 v59, 0xffff0000, v58
	v_pk_add_f32 v[72:73], v[72:73], 1.0 op_sel_hi:[1,0]
	v_lshlrev_b32_e32 v58, 16, v58
	v_pk_mul_f32 v[72:73], v[84:85], v[72:73]
	v_lshlrev_b32_e32 v84, 16, v62
	v_mul_f32_e32 v51, 0x3d372713, v84
	v_mul_f32_e32 v51, v51, v84
	v_fma_f32 v55, v51, v84, v84
	v_mul_f32_e32 v51, 0x40135761, v55
	v_exp_f32_e32 v51, v51
	v_and_b32_e32 v85, 0xffff0000, v62
	v_mov_b32_e32 v55, v85
	v_pk_fma_f32 v[80:81], v[22:23], v[86:87], v[80:81]
	v_add_f32_e32 v51, 1.0, v51
	v_rcp_f32_e32 v62, v51
	v_mul_f32_e32 v51, 0x3d372713, v85
	v_mul_f32_e32 v51, v51, v85
	v_fmac_f32_e32 v55, v51, v55
	v_mul_f32_e32 v51, 0x40135761, v55
	v_exp_f32_e32 v55, v51
	v_and_b32_e32 v51, 0xffff0000, v50
	v_lshlrev_b32_e32 v50, 16, v50
	v_pk_fma_f32 v[50:51], v[16:17], v[50:51], v[58:59]
	v_add_f32_e32 v55, 1.0, v55
	v_rcp_f32_e32 v63, v55
	v_and_b32_e32 v55, 0xffff0000, v54
	v_lshlrev_b32_e32 v54, 16, v54
	v_pk_fma_f32 v[50:51], v[20:21], v[54:55], v[50:51]
	v_pk_fma_f32 v[54:55], v[62:63], 2.0, 1.0 op_sel_hi:[1,0,0] neg_lo:[1,0,0] neg_hi:[1,0,0]
	v_pk_mul_f32 v[58:59], v[84:85], 0.5 op_sel_hi:[1,0]
	v_pk_add_f32 v[54:55], v[54:55], 1.0 op_sel_hi:[1,0]
	v_and_b32_e32 v85, 0xffff0000, v57
	v_pk_mul_f32 v[54:55], v[58:59], v[54:55]
	v_lshlrev_b32_e32 v58, 16, v61
	v_mul_f32_e32 v59, 0x3d372713, v58
	v_mul_f32_e32 v59, v59, v58
	v_fma_f32 v62, v59, v58, v58
	v_mul_f32_e32 v59, 0x40135761, v62
	v_exp_f32_e32 v62, v59
	v_and_b32_e32 v59, 0xffff0000, v61
	v_lshlrev_b32_e32 v84, 16, v57
	v_mul_f32_e32 v57, 0x3d372713, v59
	v_add_f32_e32 v61, 1.0, v62
	v_rcp_f32_e32 v62, v61
	v_mul_f32_e32 v57, v57, v59
	v_fma_f32 v61, v57, v59, v59
	v_mul_f32_e32 v57, 0x40135761, v61
	v_exp_f32_e32 v57, v57
	v_and_b32_e32 v87, 0xffff0000, v49
	v_lshlrev_b32_e32 v86, 16, v49
	v_pk_fma_f32 v[84:85], v[10:11], v[86:87], v[84:85]
	v_and_b32_e32 v87, 0xffff0000, v53
	v_lshlrev_b32_e32 v86, 16, v53
	v_add_f32_e32 v49, 1.0, v57
	v_pk_fma_f32 v[84:85], v[14:15], v[86:87], v[84:85]
	v_lshlrev_b32_e32 v86, 16, v60
	v_rcp_f32_e32 v63, v49
	v_mul_f32_e32 v49, 0x3d372713, v86
	v_mul_f32_e32 v49, v49, v86
	v_fma_f32 v53, v49, v86, v86
	v_mul_f32_e32 v49, 0x40135761, v53
	v_exp_f32_e32 v49, v49
	v_and_b32_e32 v87, 0xffff0000, v60
	v_mov_b32_e32 v53, v87
	v_and_b32_e32 v57, 0xffff0000, v56
	v_add_f32_e32 v49, 1.0, v49
	v_rcp_f32_e32 v60, v49
	v_mul_f32_e32 v49, 0x3d372713, v87
	v_mul_f32_e32 v49, v49, v87
	v_fmac_f32_e32 v53, v49, v53
	v_mul_f32_e32 v49, 0x40135761, v53
	v_exp_f32_e32 v53, v49
	v_lshlrev_b32_e32 v56, 16, v56
	v_and_b32_e32 v49, 0xffff0000, v48
	v_lshlrev_b32_e32 v48, 16, v48
	v_add_f32_e32 v53, 1.0, v53
	v_rcp_f32_e32 v61, v53
	v_pk_fma_f32 v[48:49], v[8:9], v[48:49], v[56:57]
	v_and_b32_e32 v53, 0xffff0000, v52
	v_lshlrev_b32_e32 v52, 16, v52
	v_pk_fma_f32 v[48:49], v[12:13], v[52:53], v[48:49]
	v_pk_fma_f32 v[52:53], v[60:61], 2.0, 1.0 op_sel_hi:[1,0,0] neg_lo:[1,0,0] neg_hi:[1,0,0]
	v_pk_mul_f32 v[56:57], v[86:87], 0.5 op_sel_hi:[1,0]
	v_pk_add_f32 v[52:53], v[52:53], 1.0 op_sel_hi:[1,0]
	v_pk_fma_f32 v[62:63], v[62:63], 2.0, 1.0 op_sel_hi:[1,0,0] neg_lo:[1,0,0] neg_hi:[1,0,0]
	v_pk_mul_f32 v[52:53], v[56:57], v[52:53]
	v_pk_mul_f32 v[58:59], v[58:59], 0.5 op_sel_hi:[1,0]
	v_pk_add_f32 v[62:63], v[62:63], 1.0 op_sel_hi:[1,0]
	v_pk_mul_f32 v[52:53], v[48:49], v[52:53]
	v_pk_mul_f32 v[58:59], v[58:59], v[62:63]
	v_mov_b32_e32 v62, v53
	v_mov_b32_e32 v63, v77
	v_pk_mul_f32 v[78:79], v[110:111], v[78:79]
	v_pk_mul_f32 v[58:59], v[84:85], v[58:59]
	v_mov_b32_e32 v60, v52
	v_mov_b32_e32 v61, v76
	v_pk_mul_f32 v[62:63], v[62:63], v[62:63]
	v_pk_mul_f32 v[54:55], v[50:51], v[54:55]
	v_mov_b32_e32 v48, v58
	v_mov_b32_e32 v49, v78
	v_pk_fma_f32 v[60:61], v[60:61], v[60:61], v[62:63]
	v_pk_mul_f32 v[82:83], v[74:75], v[74:75]
	v_pk_mul_f32 v[50:51], v[54:55], v[54:55]
	v_mov_b32_e32 v56, v59
	v_mov_b32_e32 v57, v79
	v_pk_fma_f32 v[48:49], v[48:49], v[48:49], v[60:61]
	v_pk_mul_f32 v[72:73], v[80:81], v[72:73]
	v_pk_fma_f32 v[48:49], v[56:57], v[56:57], v[48:49]
	v_mov_b32_e32 v56, v50
	v_mov_b32_e32 v57, v82
	v_pk_mul_f32 v[108:109], v[92:93], v[92:93]
	v_pk_mul_f32 v[80:81], v[72:73], v[72:73]
	v_pk_add_f32 v[48:49], v[56:57], v[48:49]
	v_mov_b32_e32 v82, v51
	v_pk_add_f32 v[48:49], v[82:83], v[48:49]
	v_mov_b32_e32 v50, v80
	v_mov_b32_e32 v51, v108
	v_pk_add_f32 v[48:49], v[50:51], v[48:49]
	v_mov_b32_e32 v108, v81
	v_pk_add_f32 v[48:49], v[108:109], v[48:49]
	ds_bpermute_b32 v51, v172, v49
	ds_bpermute_b32 v50, v172, v48
	v_mul_f32_e32 v60, 0x4b800000, v102
	v_cmp_gt_f32_e32 vcc, s25, v102
	v_pk_mul_f32 v[56:57], v[0:1], v[90:91]
	s_waitcnt lgkmcnt(0)
; __device__ __forceinline__ float bf2f(bf16_t b) { return __uint_as_float(((unsigned)b) << 16); }
; __device__ __forceinline__ unsigned cvtpk(float lo, float hi) { const f32x2 v = (f32x2){lo, hi}; const bf16v2 b = __builtin_convertvector(v, bf16v2); return __builtin_bit_cast(unsigned, b); }
; __device__ __forceinline__ float geluf_(float x) { const float y = 0.7978845608028654f * (x + 0.044715f * x * x * x); const float t = 1.0f - 2.0f * __builtin_amdgcn_rcpf(__expf(2.0f * y) + 1.0f); return 0.5f * x * (1.0f + t); }
; template <int MODE> __device__ void mixer_lru(const Params& p, int l, int n, LAS unsigned char* lds) {
;     ...
;             for (int i = 0; i < 8; ++i) { const size_t row = (size_t)(t0 + wave * 8 + i);
;                 float v[8]; float ss = 0.f;
; #pragma unroll
;                 for (int k = 0; k < 8; ++k) { v[k] = (bf2f((bf16_t)h0[i][k]) + bf2f((bf16_t)pf[i][k]) * cf[k] + bf2f((bf16_t)pb[i][k]) * cb[k]) * geluf_(bf2f((bf16_t)gt[i][k])); ss += v[k] * v[k]; }
; #pragma unroll
;                 for (int o = 32; o >= 1; o >>= 1) ss += __shfl_xor(ss, o);
;                 const float rs = rsqrtf(ss * (1.0f / 512.0f) + EPS);
;                 *(u32x4*)(y + row * D + ch0) = (u32x4){cvtpk(v[0] * rs * gg[0], v[1] * rs * gg[1]), cvtpk(v[2] * rs * gg[2], v[3] * rs * gg[3]), cvtpk(v[4] * rs * gg[4], v[5] * rs * gg[5]), cvtpk(v[6] * rs * gg[6], v[7] * rs * gg[7])}; }
	v_pk_add_f32 v[48:49], v[48:49], v[50:51]
	ds_bpermute_b32 v51, v143, v49
	ds_bpermute_b32 v50, v143, v48
	v_cndmask_b32_e32 v60, v102, v60, vcc
	v_rsq_f32_e32 v60, v60
	v_cvt_pk_bf16_f32 v90, v56, v57
	v_pk_mul_f32 v[56:57], v[128:129], v[106:107] op_sel_hi:[1,0]
	s_waitcnt lgkmcnt(0)
	v_pk_add_f32 v[48:49], v[48:49], v[50:51]
	ds_bpermute_b32 v51, v168, v49
	ds_bpermute_b32 v50, v168, v48
	v_pk_mul_f32 v[56:57], v[2:3], v[56:57]
	s_waitcnt lgkmcnt(0)
	v_pk_add_f32 v[50:51], v[48:49], v[50:51]
	v_cvt_pk_bf16_f32 v91, v56, v57
	v_mul_f32_e32 v56, 0x45800000, v60
	v_cndmask_b32_e32 v56, v60, v56, vcc
	ds_bpermute_b32 v61, v169, v51
	ds_bpermute_b32 v60, v169, v50
	v_pk_mul_f32 v[48:49], v[96:97], v[56:57] op_sel_hi:[1,0]
	v_pk_mul_f32 v[62:63], v[98:99], v[56:57] op_sel_hi:[1,0]
	v_pk_mul_f32 v[48:49], v[4:5], v[48:49]
	v_pk_mul_f32 v[62:63], v[6:7], v[62:63]
	s_waitcnt lgkmcnt(0)
	v_pk_add_f32 v[50:51], v[50:51], v[60:61]
	ds_bpermute_b32 v61, v173, v51
	ds_bpermute_b32 v60, v173, v50
	v_cvt_pk_bf16_f32 v48, v48, v49
	v_cvt_pk_bf16_f32 v49, v62, v63
	v_pk_mul_f32 v[62:63], v[94:95], v[56:57] op_sel_hi:[1,0]
	v_pk_mul_f32 v[56:57], v[104:105], v[56:57] op_sel_hi:[1,0]
	s_waitcnt lgkmcnt(0)
	v_pk_add_f32 v[60:61], v[50:51], v[60:61]
	ds_bpermute_b32 v81, v174, v61
	ds_bpermute_b32 v80, v174, v60
	v_pk_mul_f32 v[56:57], v[2:3], v[56:57]
	v_pk_mul_f32 v[62:63], v[0:1], v[62:63]
	v_cvt_pk_bf16_f32 v51, v56, v57
	v_cvt_pk_bf16_f32 v50, v62, v63
	s_waitcnt lgkmcnt(0)
	v_pk_add_f32 v[56:57], v[60:61], v[80:81]
	s_waitcnt vmcnt(8)
	v_and_b32_e32 v81, 0xffff0000, v35
	v_pk_fma_f32 v[60:61], v[56:57], s[88:89], v[126:127] op_sel_hi:[1,0,0]
	v_lshlrev_b32_e32 v80, 16, v35
	v_mul_f32_e32 v56, 0x4b800000, v61
	v_cmp_gt_f32_e32 vcc, s25, v61
	global_store_dwordx4 v[100:101], v[88:91], off
	s_nop 0
	v_cndmask_b32_e32 v56, v61, v56, vcc
	v_rsq_f32_e32 v61, v56
	v_lshl_add_u64 v[56:57], v[124:125], 0, v[150:151]
	global_store_dwordx4 v[56:57], v[48:51], off
	v_lshl_add_u64 v[56:57], v[124:125], 0, v[152:153]
	s_nop 0
	v_mul_f32_e32 v48, 0x45800000, v61
	v_cndmask_b32_e32 v62, v61, v48, vcc
	v_pk_mul_f32 v[48:49], v[76:77], v[62:63] op_sel_hi:[1,0]
	s_waitcnt vmcnt(8)
	v_lshlrev_b32_e32 v76, 16, v47
	v_pk_mul_f32 v[48:49], v[4:5], v[48:49]
	v_mov_b32_e32 v61, v76
	v_cvt_pk_bf16_f32 v48, v48, v49
	v_mul_f32_e32 v49, 0x3d372713, v76
	v_mul_f32_e32 v49, v49, v76
	v_fmac_f32_e32 v61, v49, v61
	v_mul_f32_e32 v49, 0x40135761, v61
	v_exp_f32_e32 v61, v49
	v_pk_mul_f32 v[50:51], v[78:79], v[62:63] op_sel_hi:[1,0]
	v_and_b32_e32 v77, 0xffff0000, v47
	v_pk_mul_f32 v[50:51], v[6:7], v[50:51]
	v_add_f32_e32 v47, 1.0, v61
	v_and_b32_e32 v79, 0xffff0000, v43
	v_lshlrev_b32_e32 v78, 16, v43
	v_mul_f32_e32 v43, 0x3d372713, v77
	v_cvt_pk_bf16_f32 v49, v50, v51
	v_pk_mul_f32 v[50:51], v[74:75], v[62:63] op_sel_hi:[1,0]
	v_rcp_f32_e32 v74, v47
	v_mul_f32_e32 v43, v43, v77
	v_fma_f32 v47, v43, v77, v77
	v_mul_f32_e32 v43, 0x40135761, v47
	v_exp_f32_e32 v43, v43
	v_pk_fma_f32 v[78:79], v[18:19], v[80:81], v[78:79]
	v_and_b32_e32 v81, 0xffff0000, v39
	v_lshlrev_b32_e32 v80, 16, v39
	v_add_f32_e32 v35, 1.0, v43
	v_pk_fma_f32 v[78:79], v[22:23], v[80:81], v[78:79]
	v_lshlrev_b32_e32 v80, 16, v46
	v_rcp_f32_e32 v75, v35
	v_mul_f32_e32 v35, 0x3d372713, v80
	v_mul_f32_e32 v35, v35, v80
	v_fma_f32 v39, v35, v80, v80
	v_mul_f32_e32 v35, 0x40135761, v39
	v_exp_f32_e32 v35, v35
	v_and_b32_e32 v81, 0xffff0000, v46
	v_mov_b32_e32 v39, v81
	v_and_b32_e32 v43, 0xffff0000, v42
	v_add_f32_e32 v35, 1.0, v35
	v_rcp_f32_e32 v46, v35
	v_mul_f32_e32 v35, 0x3d372713, v81
	v_mul_f32_e32 v35, v35, v81
	v_fmac_f32_e32 v39, v35, v39
	v_mul_f32_e32 v35, 0x40135761, v39
	v_exp_f32_e32 v39, v35
	v_lshlrev_b32_e32 v42, 16, v42
	v_and_b32_e32 v35, 0xffff0000, v34
	v_lshlrev_b32_e32 v34, 16, v34
	v_add_f32_e32 v39, 1.0, v39
	v_rcp_f32_e32 v47, v39
	v_pk_fma_f32 v[34:35], v[16:17], v[34:35], v[42:43]
	v_and_b32_e32 v39, 0xffff0000, v38
	v_lshlrev_b32_e32 v38, 16, v38
	v_pk_fma_f32 v[34:35], v[20:21], v[38:39], v[34:35]
	v_pk_fma_f32 v[38:39], v[46:47], 2.0, 1.0 op_sel_hi:[1,0,0] neg_lo:[1,0,0] neg_hi:[1,0,0]
	v_pk_fma_f32 v[74:75], v[74:75], 2.0, 1.0 op_sel_hi:[1,0,0] neg_lo:[1,0,0] neg_hi:[1,0,0]
	v_pk_mul_f32 v[42:43], v[80:81], 0.5 op_sel_hi:[1,0]
	v_pk_add_f32 v[38:39], v[38:39], 1.0 op_sel_hi:[1,0]
	v_pk_mul_f32 v[76:77], v[76:77], 0.5 op_sel_hi:[1,0]
	v_pk_add_f32 v[74:75], v[74:75], 1.0 op_sel_hi:[1,0]
	v_pk_mul_f32 v[38:39], v[42:43], v[38:39]
	v_and_b32_e32 v47, 0xffff0000, v45
	v_pk_mul_f32 v[74:75], v[76:77], v[74:75]
	v_pk_mul_f32 v[34:35], v[34:35], v[38:39]
	v_mul_f32_e32 v39, 0x3d372713, v47
	v_pk_mul_f32 v[74:75], v[78:79], v[74:75]
	v_and_b32_e32 v79, 0xffff0000, v41
	v_lshlrev_b32_e32 v78, 16, v41
	v_mul_f32_e32 v39, v39, v47
	v_fma_f32 v41, v39, v47, v47
	v_mul_f32_e32 v39, 0x40135761, v41
	v_exp_f32_e32 v39, v39
	v_and_b32_e32 v81, 0xffff0000, v33
	v_lshlrev_b32_e32 v80, 16, v33
	v_pk_fma_f32 v[78:79], v[10:11], v[80:81], v[78:79]
	v_and_b32_e32 v81, 0xffff0000, v37
	v_lshlrev_b32_e32 v80, 16, v37
	v_add_f32_e32 v33, 1.0, v39
	v_pk_fma_f32 v[78:79], v[14:15], v[80:81], v[78:79]
	v_lshlrev_b32_e32 v80, 16, v44
	v_rcp_f32_e32 v39, v33
	v_mul_f32_e32 v33, 0x3d372713, v80
	v_mul_f32_e32 v33, v33, v80
	v_fma_f32 v37, v33, v80, v80
	v_mul_f32_e32 v33, 0x40135761, v37
	v_exp_f32_e32 v33, v33
	v_lshlrev_b32_e32 v46, 16, v45
	v_and_b32_e32 v81, 0xffff0000, v44
	v_mul_f32_e32 v42, 0x3d372713, v46
	v_add_f32_e32 v33, 1.0, v33
	v_rcp_f32_e32 v44, v33
	v_mul_f32_e32 v33, 0x3d372713, v81
	v_mul_f32_e32 v42, v42, v46
	v_mov_b32_e32 v43, v46
	v_mul_f32_e32 v33, v33, v81
	v_mov_b32_e32 v37, v81
	v_fmac_f32_e32 v43, v42, v43
	v_fmac_f32_e32 v37, v33, v37
	v_mul_f32_e32 v42, 0x40135761, v43
	v_mul_f32_e32 v33, 0x40135761, v37
	v_exp_f32_e32 v61, v42
	v_exp_f32_e32 v37, v33
	v_and_b32_e32 v41, 0xffff0000, v40
	v_lshlrev_b32_e32 v40, 16, v40
	v_add_f32_e32 v38, 1.0, v61
	v_add_f32_e32 v37, 1.0, v37
	v_rcp_f32_e32 v38, v38
	v_rcp_f32_e32 v45, v37
	v_and_b32_e32 v33, 0xffff0000, v32
	v_lshlrev_b32_e32 v32, 16, v32
	v_pk_fma_f32 v[32:33], v[8:9], v[32:33], v[40:41]
	v_and_b32_e32 v37, 0xffff0000, v36
	v_lshlrev_b32_e32 v36, 16, v36
	v_pk_fma_f32 v[38:39], v[38:39], 2.0, 1.0 op_sel_hi:[1,0,0] neg_lo:[1,0,0] neg_hi:[1,0,0]
	v_pk_fma_f32 v[32:33], v[12:13], v[36:37], v[32:33]
	v_pk_fma_f32 v[36:37], v[44:45], 2.0, 1.0 op_sel_hi:[1,0,0] neg_lo:[1,0,0] neg_hi:[1,0,0]
	s_waitcnt vmcnt(4)
; __device__ __forceinline__ float bf2f(bf16_t b) { return __uint_as_float(((unsigned)b) << 16); }
; __device__ __forceinline__ unsigned cvtpk(float lo, float hi) { const f32x2 v = (f32x2){lo, hi}; const bf16v2 b = __builtin_convertvector(v, bf16v2); return __builtin_bit_cast(unsigned, b); }
; __device__ __forceinline__ float geluf_(float x) { const float y = 0.7978845608028654f * (x + 0.044715f * x * x * x); const float t = 1.0f - 2.0f * __builtin_amdgcn_rcpf(__expf(2.0f * y) + 1.0f); return 0.5f * x * (1.0f + t); }
; template <int MODE> __device__ void mixer_lru(const Params& p, int l, int n, LAS unsigned char* lds) {
;     ...
;             for (int i = 0; i < 8; ++i) { const size_t row = (size_t)(t0 + wave * 8 + i);
;                 float v[8]; float ss = 0.f;
; #pragma unroll
;                 for (int k = 0; k < 8; ++k) { v[k] = (bf2f((bf16_t)h0[i][k]) + bf2f((bf16_t)pf[i][k]) * cf[k] + bf2f((bf16_t)pb[i][k]) * cb[k]) * geluf_(bf2f((bf16_t)gt[i][k])); ss += v[k] * v[k]; }
; #pragma unroll
;                 for (int o = 32; o >= 1; o >>= 1) ss += __shfl_xor(ss, o);
;                 const float rs = rsqrtf(ss * (1.0f / 512.0f) + EPS);
;                 *(u32x4*)(y + row * D + ch0) = (u32x4){cvtpk(v[0] * rs * gg[0], v[1] * rs * gg[1]), cvtpk(v[2] * rs * gg[2], v[3] * rs * gg[3]), cvtpk(v[4] * rs * gg[4], v[5] * rs * gg[5]), cvtpk(v[6] * rs * gg[6], v[7] * rs * gg[7])}; }
	v_lshlrev_b32_e32 v44, 16, v71
	v_pk_mul_f32 v[46:47], v[46:47], 0.5 op_sel_hi:[1,0]
	v_pk_add_f32 v[38:39], v[38:39], 1.0 op_sel_hi:[1,0]
	v_mul_f32_e32 v45, 0x3d372713, v44
	v_pk_mul_f32 v[38:39], v[46:47], v[38:39]
	v_mul_f32_e32 v45, v45, v44
	v_fma_f32 v46, v45, v44, v44
	v_mul_f32_e32 v45, 0x40135761, v46
	v_pk_mul_f32 v[40:41], v[80:81], 0.5 op_sel_hi:[1,0]
	v_pk_add_f32 v[36:37], v[36:37], 1.0 op_sel_hi:[1,0]
	v_exp_f32_e32 v46, v45
	v_and_b32_e32 v45, 0xffff0000, v71
	v_pk_mul_f32 v[36:37], v[40:41], v[36:37]
	v_and_b32_e32 v41, 0xffff0000, v31
	v_lshlrev_b32_e32 v40, 16, v31
	v_mul_f32_e32 v31, 0x3d372713, v45
	v_pk_mul_f32 v[32:33], v[32:33], v[36:37]
	v_mul_f32_e32 v31, v31, v45
	v_fma_f32 v37, v31, v45, v45
	v_mul_f32_e32 v31, 0x40135761, v37
	v_exp_f32_e32 v31, v31
	v_add_f32_e32 v36, 1.0, v46
	v_and_b32_e32 v47, 0xffff0000, v27
	v_lshlrev_b32_e32 v46, 16, v27
	v_add_f32_e32 v27, 1.0, v31
	v_rcp_f32_e32 v36, v36
	v_rcp_f32_e32 v37, v27
	v_pk_fma_f32 v[18:19], v[18:19], v[46:47], v[40:41]
	v_and_b32_e32 v41, 0xffff0000, v67
	v_lshlrev_b32_e32 v40, 16, v67
	v_pk_fma_f32 v[18:19], v[22:23], v[40:41], v[18:19]
	v_pk_fma_f32 v[22:23], v[36:37], 2.0, 1.0 op_sel_hi:[1,0,0] neg_lo:[1,0,0] neg_hi:[1,0,0]
	v_pk_mul_f32 v[36:37], v[44:45], 0.5 op_sel_hi:[1,0]
	v_pk_add_f32 v[22:23], v[22:23], 1.0 op_sel_hi:[1,0]
	v_pk_mul_f32 v[38:39], v[78:79], v[38:39]
	v_pk_mul_f32 v[22:23], v[36:37], v[22:23]
	v_lshlrev_b32_e32 v36, 16, v70
	v_mul_f32_e32 v27, 0x3d372713, v36
	v_mul_f32_e32 v27, v27, v36
	v_fma_f32 v31, v27, v36, v36
	v_mul_f32_e32 v27, 0x40135761, v31
	v_exp_f32_e32 v27, v27
	v_and_b32_e32 v37, 0xffff0000, v70
	v_mov_b32_e32 v41, v37
	v_and_b32_e32 v31, 0xffff0000, v30
	v_add_f32_e32 v27, 1.0, v27
	v_rcp_f32_e32 v40, v27
	v_mul_f32_e32 v27, 0x3d372713, v37
	v_mul_f32_e32 v27, v27, v37
	v_fmac_f32_e32 v41, v27, v41
	v_mul_f32_e32 v27, 0x40135761, v41
	v_exp_f32_e32 v41, v27
	v_lshlrev_b32_e32 v30, 16, v30
	v_and_b32_e32 v27, 0xffff0000, v26
	v_lshlrev_b32_e32 v26, 16, v26
	v_pk_fma_f32 v[16:17], v[16:17], v[26:27], v[30:31]
	v_add_f32_e32 v26, 1.0, v41
	v_rcp_f32_e32 v41, v26
	v_and_b32_e32 v27, 0xffff0000, v66
	v_lshlrev_b32_e32 v26, 16, v66
	v_pk_fma_f32 v[16:17], v[20:21], v[26:27], v[16:17]
	v_pk_fma_f32 v[20:21], v[40:41], 2.0, 1.0 op_sel_hi:[1,0,0] neg_lo:[1,0,0] neg_hi:[1,0,0]
	v_pk_mul_f32 v[26:27], v[36:37], 0.5 op_sel_hi:[1,0]
	v_pk_add_f32 v[20:21], v[20:21], 1.0 op_sel_hi:[1,0]
	v_and_b32_e32 v37, 0xffff0000, v29
	v_pk_mul_f32 v[20:21], v[26:27], v[20:21]
	v_lshlrev_b32_e32 v26, 16, v69
	v_mul_f32_e32 v27, 0x3d372713, v26
	v_mul_f32_e32 v27, v27, v26
	v_fma_f32 v30, v27, v26, v26
	v_mul_f32_e32 v27, 0x40135761, v30
	v_exp_f32_e32 v30, v27
	v_and_b32_e32 v27, 0xffff0000, v69
	v_lshlrev_b32_e32 v36, 16, v29
	v_mul_f32_e32 v29, 0x3d372713, v27
	v_mul_f32_e32 v29, v29, v27
	v_fma_f32 v31, v29, v27, v27
	v_mul_f32_e32 v29, 0x40135761, v31
	v_exp_f32_e32 v29, v29
	v_add_f32_e32 v30, 1.0, v30
	v_and_b32_e32 v41, 0xffff0000, v25
	v_lshlrev_b32_e32 v40, 16, v25
	v_add_f32_e32 v25, 1.0, v29
	v_rcp_f32_e32 v30, v30
	v_rcp_f32_e32 v31, v25
	v_pk_fma_f32 v[10:11], v[10:11], v[40:41], v[36:37]
	v_and_b32_e32 v37, 0xffff0000, v65
	v_lshlrev_b32_e32 v36, 16, v65
	v_pk_fma_f32 v[10:11], v[14:15], v[36:37], v[10:11]
	v_pk_fma_f32 v[14:15], v[30:31], 2.0, 1.0 op_sel_hi:[1,0,0] neg_lo:[1,0,0] neg_hi:[1,0,0]
	v_lshlrev_b32_e32 v30, 16, v68
	v_mul_f32_e32 v25, 0x3d372713, v30
	v_mul_f32_e32 v25, v25, v30
	v_fma_f32 v29, v25, v30, v30
	v_mul_f32_e32 v25, 0x40135761, v29
	v_exp_f32_e32 v25, v25
	v_pk_mul_f32 v[26:27], v[26:27], 0.5 op_sel_hi:[1,0]
	v_pk_add_f32 v[14:15], v[14:15], 1.0 op_sel_hi:[1,0]
	v_and_b32_e32 v31, 0xffff0000, v68
	v_pk_mul_f32 v[14:15], v[26:27], v[14:15]
	v_and_b32_e32 v27, 0xffff0000, v28
	v_pk_mul_f32 v[14:15], v[10:11], v[14:15]
	v_mul_f32_e32 v11, 0x3d372713, v31
	v_add_f32_e32 v10, 1.0, v25
	v_mul_f32_e32 v11, v11, v31
	v_fma_f32 v25, v11, v31, v31
	v_mul_f32_e32 v11, 0x40135761, v25
	v_exp_f32_e32 v11, v11
	v_rcp_f32_e32 v10, v10
	v_lshlrev_b32_e32 v26, 16, v28
	v_and_b32_e32 v25, 0xffff0000, v24
	v_add_f32_e32 v11, 1.0, v11
	v_rcp_f32_e32 v11, v11
	v_lshlrev_b32_e32 v24, 16, v24
	v_pk_fma_f32 v[8:9], v[8:9], v[24:25], v[26:27]
	v_and_b32_e32 v25, 0xffff0000, v64
	v_lshlrev_b32_e32 v24, 16, v64
	v_pk_fma_f32 v[10:11], v[10:11], 2.0, 1.0 op_sel_hi:[1,0,0] neg_lo:[1,0,0] neg_hi:[1,0,0]
	v_pk_fma_f32 v[8:9], v[12:13], v[24:25], v[8:9]
	v_pk_mul_f32 v[12:13], v[30:31], 0.5 op_sel_hi:[1,0]
	v_pk_add_f32 v[10:11], v[10:11], 1.0 op_sel_hi:[1,0]
	v_mov_b32_e32 v27, v33
	v_pk_mul_f32 v[10:11], v[12:13], v[10:11]
	v_mov_b32_e32 v25, v32
	v_pk_mul_f32 v[12:13], v[8:9], v[10:11]
	v_pk_mul_f32 v[16:17], v[16:17], v[20:21]
	v_mov_b32_e32 v26, v13
	v_mov_b32_e32 v24, v12
	v_pk_mul_f32 v[26:27], v[26:27], v[26:27]
	v_mov_b32_e32 v8, v14
	v_mov_b32_e32 v9, v38
	v_pk_fma_f32 v[24:25], v[24:25], v[24:25], v[26:27]
	v_pk_mul_f32 v[42:43], v[34:35], v[34:35]
	v_pk_mul_f32 v[20:21], v[16:17], v[16:17]
	v_mov_b32_e32 v10, v15
	v_mov_b32_e32 v11, v39
	v_pk_fma_f32 v[8:9], v[8:9], v[8:9], v[24:25]
	v_pk_mul_f32 v[18:19], v[18:19], v[22:23]
	v_pk_fma_f32 v[8:9], v[10:11], v[10:11], v[8:9]
	v_mov_b32_e32 v10, v20
	v_mov_b32_e32 v11, v42
	v_pk_mul_f32 v[76:77], v[74:75], v[74:75]
	v_pk_mul_f32 v[22:23], v[18:19], v[18:19]
	v_pk_add_f32 v[8:9], v[10:11], v[8:9]
	v_mov_b32_e32 v42, v21
	v_pk_add_f32 v[8:9], v[42:43], v[8:9]
	v_mov_b32_e32 v10, v22
	v_mov_b32_e32 v11, v76
	v_pk_add_f32 v[8:9], v[10:11], v[8:9]
	v_mov_b32_e32 v76, v23
	v_pk_add_f32 v[8:9], v[76:77], v[8:9]
	ds_bpermute_b32 v11, v172, v9
	ds_bpermute_b32 v10, v172, v8
	v_mul_f32_e32 v22, 0x4b800000, v60
	v_cmp_gt_f32_e32 vcc, s25, v60
	v_pk_mul_f32 v[20:21], v[0:1], v[50:51]
	s_waitcnt lgkmcnt(0)
; __device__ __forceinline__ unsigned cvtpk(float lo, float hi) { const f32x2 v = (f32x2){lo, hi}; const bf16v2 b = __builtin_convertvector(v, bf16v2); return __builtin_bit_cast(unsigned, b); }
; template <int MODE> __device__ void mixer_lru(const Params& p, int l, int n, LAS unsigned char* lds) {
;     ...
; #pragma unroll
;                 for (int o = 32; o >= 1; o >>= 1) ss += __shfl_xor(ss, o);
;                 const float rs = rsqrtf(ss * (1.0f / 512.0f) + EPS);
;                 *(u32x4*)(y + row * D + ch0) = (u32x4){cvtpk(v[0] * rs * gg[0], v[1] * rs * gg[1]), cvtpk(v[2] * rs * gg[2], v[3] * rs * gg[3]), cvtpk(v[4] * rs * gg[4], v[5] * rs * gg[5]), cvtpk(v[6] * rs * gg[6], v[7] * rs * gg[7])}; }
	v_pk_add_f32 v[8:9], v[8:9], v[10:11]
	ds_bpermute_b32 v11, v143, v9
	ds_bpermute_b32 v10, v143, v8
	v_cndmask_b32_e32 v22, v60, v22, vcc
	v_rsq_f32_e32 v22, v22
	v_cvt_pk_bf16_f32 v50, v20, v21
	v_pk_mul_f32 v[20:21], v[92:93], v[62:63] op_sel_hi:[1,0]
	s_waitcnt lgkmcnt(0)
	v_pk_add_f32 v[8:9], v[8:9], v[10:11]
	ds_bpermute_b32 v11, v168, v9
	ds_bpermute_b32 v10, v168, v8
	v_pk_mul_f32 v[20:21], v[2:3], v[20:21]
	s_waitcnt lgkmcnt(0)
	v_pk_add_f32 v[10:11], v[8:9], v[10:11]
	v_cvt_pk_bf16_f32 v51, v20, v21
	v_mul_f32_e32 v20, 0x45800000, v22
	v_cndmask_b32_e32 v20, v22, v20, vcc
	ds_bpermute_b32 v23, v169, v11
	ds_bpermute_b32 v22, v169, v10
	v_pk_mul_f32 v[8:9], v[52:53], v[20:21] op_sel_hi:[1,0]
	v_pk_mul_f32 v[24:25], v[58:59], v[20:21] op_sel_hi:[1,0]
	v_pk_mul_f32 v[8:9], v[4:5], v[8:9]
	v_pk_mul_f32 v[24:25], v[6:7], v[24:25]
	s_waitcnt lgkmcnt(0)
	v_pk_add_f32 v[10:11], v[10:11], v[22:23]
	ds_bpermute_b32 v23, v173, v11
	ds_bpermute_b32 v22, v173, v10
	v_cvt_pk_bf16_f32 v8, v8, v9
	v_cvt_pk_bf16_f32 v9, v24, v25
	v_pk_mul_f32 v[24:25], v[54:55], v[20:21] op_sel_hi:[1,0]
	v_pk_mul_f32 v[20:21], v[72:73], v[20:21] op_sel_hi:[1,0]
	s_waitcnt lgkmcnt(0)
	v_pk_add_f32 v[22:23], v[10:11], v[22:23]
	ds_bpermute_b32 v27, v174, v23
	ds_bpermute_b32 v26, v174, v22
	v_pk_mul_f32 v[20:21], v[2:3], v[20:21]
	v_pk_mul_f32 v[24:25], v[0:1], v[24:25]
	v_cvt_pk_bf16_f32 v11, v20, v21
	v_cvt_pk_bf16_f32 v10, v24, v25
	s_waitcnt lgkmcnt(0)
	v_pk_add_f32 v[20:21], v[22:23], v[26:27]
	global_store_dwordx4 v[56:57], v[48:51], off
	v_pk_fma_f32 v[20:21], v[20:21], s[88:89], v[126:127] op_sel_hi:[1,0,0]
	s_nop 0
	v_mul_f32_e32 v22, 0x4b800000, v21
	v_cmp_gt_f32_e32 vcc, s25, v21
	s_nop 1
	v_cndmask_b32_e32 v21, v21, v22, vcc
	v_rsq_f32_e32 v21, v21
	v_lshl_add_u64 v[22:23], v[124:125], 0, v[146:147]
	global_store_dwordx4 v[22:23], v[8:11], off
	v_lshl_add_u64 v[22:23], v[124:125], 0, v[148:149]
	s_nop 0
	v_mul_f32_e32 v8, 0x45800000, v21
	v_cndmask_b32_e32 v24, v21, v8, vcc
	v_pk_mul_f32 v[8:9], v[32:33], v[24:25] op_sel_hi:[1,0]
	v_pk_mul_f32 v[10:11], v[38:39], v[24:25] op_sel_hi:[1,0]
	v_pk_mul_f32 v[8:9], v[4:5], v[8:9]
	v_pk_mul_f32 v[10:11], v[6:7], v[10:11]
	v_cvt_pk_bf16_f32 v8, v8, v9
	v_cvt_pk_bf16_f32 v9, v10, v11
	v_pk_mul_f32 v[10:11], v[34:35], v[24:25] op_sel_hi:[1,0]
	v_cmp_gt_f32_e32 vcc, s25, v20
	v_pk_mul_f32 v[10:11], v[0:1], v[10:11]
	v_pk_mul_f32 v[24:25], v[74:75], v[24:25] op_sel_hi:[1,0]
	v_cvt_pk_bf16_f32 v10, v10, v11
	v_mul_f32_e32 v11, 0x4b800000, v20
	v_cndmask_b32_e32 v11, v20, v11, vcc
	v_rsq_f32_e32 v26, v11
	v_pk_mul_f32 v[20:21], v[2:3], v[24:25]
	s_nop 0
	v_cvt_pk_bf16_f32 v11, v20, v21
	global_store_dwordx4 v[22:23], v[8:11], off
	s_nop 1
	v_mul_f32_e32 v8, 0x45800000, v26
	v_cndmask_b32_e32 v8, v26, v8, vcc
	v_pk_mul_f32 v[10:11], v[12:13], v[8:9] op_sel_hi:[1,0]
	s_nop 0
	v_pk_mul_f32 v[4:5], v[4:5], v[10:11]
	v_pk_mul_f32 v[10:11], v[14:15], v[8:9] op_sel_hi:[1,0]
	v_cvt_pk_bf16_f32 v4, v4, v5
	v_pk_mul_f32 v[6:7], v[6:7], v[10:11]
	s_nop 0
	v_cvt_pk_bf16_f32 v5, v6, v7
	v_pk_mul_f32 v[6:7], v[16:17], v[8:9] op_sel_hi:[1,0]
	s_nop 0
	v_pk_mul_f32 v[0:1], v[0:1], v[6:7]
	s_nop 0
	v_cvt_pk_bf16_f32 v6, v0, v1
	v_pk_mul_f32 v[0:1], v[18:19], v[8:9] op_sel_hi:[1,0]
	s_nop 0
	v_pk_mul_f32 v[0:1], v[2:3], v[0:1]
	s_nop 0
	v_cvt_pk_bf16_f32 v7, v0, v1
	v_lshl_add_u64 v[0:1], v[124:125], 0, v[144:145]
	global_store_dwordx4 v[0:1], v[4:7], off
	s_barrier
	s_load_dword s1, s[52:53], 0x0
	s_waitcnt lgkmcnt(0)
	s_add_i32 s0, s1, s0
	s_cmpk_gt_i32 s0, 0xff
	s_cbranch_scc0 .LBB0_146

; __device__ __forceinline__ float bf2f(bf16_t b) { return __uint_as_float(((unsigned)b) << 16); }
; __device__ __forceinline__ f32x4 mfma16(bf16x8 a, bf16x8 b, f32x4 c) { return __builtin_amdgcn_mfma_f32_16x16x32_bf16(a, b, c, 0, 0, 0); }
; template <int MODE> __device__ void mixer_gla(const Params& p, int l, int n, LAS unsigned char* lds) {
;     ...
;             for (int tj = 0; tj < 4; ++tj)
; #pragma unroll
;                 for (int ks = 0; ks < 2; ++ks) { const bf16_t* rp = proj + (size_t)(t0 + 16 * tj + c) * DINP + 64 * h + 32 * ks + 8 * q; qn[tj][ks] = *(const bf16x8*)(rp + 1024); kn1[tj][ks] = *(const bf16x8*)(rp + 1280); }
;             __builtin_amdgcn_sched_barrier(0);
; #pragma unroll
;             for (int tj = 0; tj < 4; ++tj) {
;                 const int t = 16 * tj + c;
;                 bf16x8 mk[2];
; #pragma unroll
;                 for (int ks = 0; ks < 2; ++ks)
; #pragma unroll
;                     for (int jj = 0; jj < 8; ++jj) { const int sidx = SLOT(ks, q, jj); const bool on = dir == 0 ? sidx <= t : sidx >= t; mk[ks][jj] = on ? (short)0x3F80 : (short)0; }
; #pragma unroll
;                 for (int ks2 = 0; ks2 < 2; ++ks2) { f32x4 qe2[2], ke2[2];
; #pragma unroll
;                     for (int e2 = 0; e2 < 2; ++e2) { const int ef = 2 * ks2 + e2;
;                         f32x4 b = mfma16(laop[ef][0], mk[0], zero4); b = mfma16(laop[ef][1], mk[1], b);
; #pragma unroll
;                         for (int r = 0; r < 4; ++r) { qe2[e2][r] = bf2f((bf16_t)qn[tj][ks2][4 * e2 + r]) * 0.125f * __expf(b[r]); ke2[e2][r] = bf2f((bf16_t)kn1[tj][ks2][4 * e2 + r]) * __expf(-b[r]); } }
;                     QEop[tj][ks2] = pack8(qe2[0], qe2[1]); KEop[tj][ks2] = pack8(ke2[0], ke2[1]); }
.LBB0_151:
	s_or_b64 exec, exec, s[0:1]
	s_lshl_b32 s34, s4, 8
	s_xor_b64 s[30:31], s[26:27], -1
	v_lshrrev_b32_e32 v116, 7, v245
	v_and_b32_e32 v117, 63, v245
	v_lshlrev_b32_e32 v116, 14, v116
	v_lshl_add_u32 v116, v117, 4, v116
	v_lshl_add_u32 v116, s4, 13, v116
	s_waitcnt vmcnt(0)
	ds_read_b128 v[76:79], v116
	ds_read_b128 v[84:87], v116 offset:1024
	ds_read_b128 v[96:99], v116 offset:2048
	ds_read_b128 v[100:103], v116 offset:3072
	ds_read_b128 v[104:107], v116 offset:4096
	ds_read_b128 v[92:95], v116 offset:5120
	ds_read_b128 v[80:83], v116 offset:6144
	ds_read_b128 v[112:115], v116 offset:7168
	s_waitcnt lgkmcnt(0)
	global_load_dwordx4 v[64:67], v[212:213], off offset:2048
	global_load_dwordx4 v[120:123], v[212:213], off offset:2112
	global_load_dwordx4 v[72:75], v[212:213], off offset:2560
	global_load_dwordx4 v[68:71], v[212:213], off offset:2624
	global_load_dwordx4 v[136:139], v[214:215], off offset:2048
	global_load_dwordx4 v[156:159], v[214:215], off offset:2112
	global_load_dwordx4 v[116:119], v[214:215], off offset:2560
	global_load_dwordx4 v[132:135], v[214:215], off offset:2624
	global_load_dwordx4 v[164:167], v[216:217], off offset:2048
	global_load_dwordx4 v[144:147], v[216:217], off offset:2112
	global_load_dwordx4 v[160:163], v[216:217], off offset:2560
	global_load_dwordx4 v[140:143], v[216:217], off offset:2624
	global_load_dwordx4 v[128:131], v[218:219], off offset:2048
	global_load_dwordx4 v[108:111], v[218:219], off offset:2112
	global_load_dwordx4 v[124:127], v[218:219], off offset:2560
	global_load_dwordx4 v[88:91], v[218:219], off offset:2624
	v_readlane_b32 s0, v255, 22
	v_readlane_b32 s1, v255, 23
	v_cndmask_b32_e64 v149, 0, 1, s[28:29]
	v_cndmask_b32_e64 v150, 0, 1, s[40:41]
	v_cndmask_b32_e64 v148, 0, 1, s[0:1]
	v_cndmask_b32_e64 v148, v149, v148, s[26:27]
	v_and_b32_e32 v148, 1, v148
	v_cmp_eq_u32_e64 s[16:17], 1, v148
	v_cndmask_b32_e64 v148, 0, 1, s[44:45]
	v_cndmask_b32_e64 v149, 0, 1, s[46:47]
	v_cndmask_b32_e64 v148, v149, v148, s[26:27]
	v_cndmask_b32_e64 v149, 0, 1, s[48:49]
	v_cndmask_b32_e64 v149, v150, v149, s[26:27]
	v_cndmask_b32_e64 v150, 0, 1, s[52:53]
	v_cndmask_b32_e64 v151, 0, 1, s[54:55]
	v_cndmask_b32_e64 v150, v151, v150, s[26:27]
	v_and_b32_e32 v148, 1, v148
	v_and_b32_e32 v149, 1, v149
	v_and_b32_e32 v150, 1, v150
	s_and_b64 s[0:1], s[26:27], exec
	v_cmp_eq_u32_e64 s[92:93], 1, v148
	v_cmp_eq_u32_e64 s[94:95], 1, v149
	v_cmp_eq_u32_e64 s[96:97], 1, v150
	s_cselect_b32 s0, 0, 0x3f80
	v_cndmask_b32_e64 v176, 0, v229, s[16:17]
	v_cndmask_b32_e64 v148, 0, v229, s[92:93]
	v_cndmask_b32_e64 v149, 0, v229, s[94:95]
	v_cndmask_b32_e64 v150, 0, v229, s[96:97]
	s_pack_ll_b32_b16 s4, s0, s0
	v_perm_b32 v148, v148, v176, s3
	v_perm_b32 v149, v150, v149, s3
	v_mov_b32_e32 v150, s4
	v_mov_b32_e32 v151, s4
	s_mov_b32 s6, s4
	s_mov_b32 s7, s4
	v_mfma_f32_16x16x32_bf16 v[152:155], v[76:79], v[148:151], 0
	s_mov_b32 s5, s4
	v_mov_b64_e32 v[170:171], s[6:7]
	v_mov_b64_e32 v[168:169], s[4:5]
	s_waitcnt vmcnt(15)
	v_and_b32_e32 v175, 0xffff0000, v64
	v_lshlrev_b32_e32 v174, 16, v64
	v_mfma_f32_16x16x32_bf16 v[152:155], v[84:87], v[168:171], v[152:155]
	v_mul_f32_e64 v174, v174, s24
	v_mul_f32_e64 v175, v175, s24
	v_and_b32_e32 v179, 0xffff0000, v65
	v_lshlrev_b32_e32 v178, 16, v65
	v_pk_mul_f32 v[178:179], v[178:179], s[24:25] op_sel_hi:[1,0]
	s_waitcnt vmcnt(13)
	v_and_b32_e32 v181, 0xffff0000, v73
	s_nop 0
	v_exp_f32_e32 v172, v152
	v_exp_f32_e32 v173, v153
	v_exp_f32_e64 v152, -v152
	v_exp_f32_e64 v153, -v153
	v_pk_mul_f32 v[172:173], v[174:175], v[172:173]
	v_and_b32_e32 v175, 0xffff0000, v72
	v_lshlrev_b32_e32 v174, 16, v72
	v_pk_mul_f32 v[174:175], v[152:153], v[174:175]
	v_exp_f32_e32 v152, v154
	v_exp_f32_e32 v153, v155
	v_exp_f32_e64 v65, -v155
	v_exp_f32_e64 v64, -v154
	v_pk_mul_f32 v[178:179], v[178:179], v[152:153]
	v_mfma_f32_16x16x32_bf16 v[152:155], v[96:99], v[148:151], 0
	v_lshlrev_b32_e32 v180, 16, v73
	v_and_b32_e32 v189, 0xffff0000, v66
	v_mfma_f32_16x16x32_bf16 v[152:155], v[100:103], v[168:171], v[152:155]
	v_mul_f32_e64 v180, v64, v180
	v_mul_f32_e64 v181, v65, v181
	v_lshlrev_b32_e32 v188, 16, v66
	v_pk_mul_f32 v[188:189], v[188:189], s[24:25] op_sel_hi:[1,0]
	s_nop 3
	v_exp_f32_e64 v72, -v152
	v_exp_f32_e32 v64, v152
	v_exp_f32_e32 v65, v153
	v_exp_f32_e64 v73, -v153
	v_pk_mul_f32 v[152:153], v[188:189], v[64:65]
	v_and_b32_e32 v65, 0xffff0000, v74
	v_lshlrev_b32_e32 v64, 16, v74
	v_pk_mul_f32 v[188:189], v[72:73], v[64:65]
	v_exp_f32_e64 v66, -v154
	v_exp_f32_e32 v64, v154
	v_exp_f32_e32 v65, v155
	v_and_b32_e32 v73, 0xffff0000, v67
	v_lshlrev_b32_e32 v72, 16, v67
	v_exp_f32_e64 v67, -v155
	v_pk_mul_f32 v[72:73], v[72:73], s[24:25] op_sel_hi:[1,0]
	v_cvt_pk_bf16_f32 v74, v188, v189
	v_pk_mul_f32 v[72:73], v[72:73], v[64:65]
	v_and_b32_e32 v65, 0xffff0000, v75
	v_lshlrev_b32_e32 v64, 16, v75
	v_pk_mul_f32 v[190:191], v[66:67], v[64:65]
	v_cvt_pk_bf16_f32 v66, v152, v153
	v_mfma_f32_16x16x32_bf16 v[152:155], v[104:107], v[148:151], 0
	v_cvt_pk_bf16_f32 v64, v172, v173
	v_cvt_pk_bf16_f32 v67, v72, v73
	v_cvt_pk_bf16_f32 v72, v174, v175
	v_mfma_f32_16x16x32_bf16 v[152:155], v[92:95], v[168:171], v[152:155]
	v_and_b32_e32 v175, 0xffff0000, v120
	v_lshlrev_b32_e32 v174, 16, v120
	v_pk_mul_f32 v[174:175], v[174:175], s[24:25] op_sel_hi:[1,0]
	v_cvt_pk_bf16_f32 v65, v178, v179
	v_and_b32_e32 v179, 0xffff0000, v121
	s_nop 2
	v_exp_f32_e32 v172, v152
	v_exp_f32_e32 v173, v153
	v_exp_f32_e64 v152, -v152
	v_exp_f32_e64 v153, -v153
	v_pk_mul_f32 v[172:173], v[174:175], v[172:173]
	s_waitcnt vmcnt(12)
; __device__ __forceinline__ float bf2f(bf16_t b) { return __uint_as_float(((unsigned)b) << 16); }
; __device__ __forceinline__ f32x4 mfma16(bf16x8 a, bf16x8 b, f32x4 c) { return __builtin_amdgcn_mfma_f32_16x16x32_bf16(a, b, c, 0, 0, 0); }
; template <int MODE> __device__ void mixer_gla(const Params& p, int l, int n, LAS unsigned char* lds) {
;     ...
;             for (int tj = 0; tj < 4; ++tj) {
;                 const int t = 16 * tj + c;
;                 bf16x8 mk[2];
; #pragma unroll
;                 for (int ks = 0; ks < 2; ++ks)
; #pragma unroll
;                     for (int jj = 0; jj < 8; ++jj) { const int sidx = SLOT(ks, q, jj); const bool on = dir == 0 ? sidx <= t : sidx >= t; mk[ks][jj] = on ? (short)0x3F80 : (short)0; }
; #pragma unroll
;                 for (int ks2 = 0; ks2 < 2; ++ks2) { f32x4 qe2[2], ke2[2];
; #pragma unroll
;                     for (int e2 = 0; e2 < 2; ++e2) { const int ef = 2 * ks2 + e2;
;                         f32x4 b = mfma16(laop[ef][0], mk[0], zero4); b = mfma16(laop[ef][1], mk[1], b);
; #pragma unroll
;                         for (int r = 0; r < 4; ++r) { qe2[e2][r] = bf2f((bf16_t)qn[tj][ks2][4 * e2 + r]) * 0.125f * __expf(b[r]); ke2[e2][r] = bf2f((bf16_t)kn1[tj][ks2][4 * e2 + r]) * __expf(-b[r]); } }
;                     QEop[tj][ks2] = pack8(qe2[0], qe2[1]); KEop[tj][ks2] = pack8(ke2[0], ke2[1]); }
	v_and_b32_e32 v175, 0xffff0000, v68
	v_lshlrev_b32_e32 v174, 16, v68
	v_pk_mul_f32 v[174:175], v[152:153], v[174:175]
	v_exp_f32_e32 v152, v154
	v_exp_f32_e64 v120, -v154
	v_exp_f32_e32 v153, v155
	v_lshlrev_b32_e32 v178, 16, v121
	v_pk_mul_f32 v[178:179], v[178:179], s[24:25] op_sel_hi:[1,0]
	v_exp_f32_e64 v121, -v155
	v_pk_mul_f32 v[178:179], v[178:179], v[152:153]
	v_mfma_f32_16x16x32_bf16 v[152:155], v[80:83], v[148:151], 0
	v_and_b32_e32 v149, 0xffff0000, v69
	v_lshlrev_b32_e32 v148, 16, v69
	v_mfma_f32_16x16x32_bf16 v[152:155], v[112:115], v[168:171], v[152:155]
	v_mul_f32_e64 v148, v120, v148
	v_mul_f32_e64 v149, v121, v149
	v_cvt_pk_bf16_f32 v73, v180, v181
	v_and_b32_e32 v181, 0xffff0000, v122
	v_lshlrev_b32_e32 v180, 16, v122
	v_pk_mul_f32 v[180:181], v[180:181], s[24:25] op_sel_hi:[1,0]
	s_nop 1
	v_exp_f32_e64 v120, -v152
	v_exp_f32_e32 v68, v152
	v_exp_f32_e32 v69, v153
	v_exp_f32_e64 v121, -v153
	v_and_b32_e32 v189, 0xffff0000, v123
	v_pk_mul_f32 v[152:153], v[180:181], v[68:69]
	v_and_b32_e32 v69, 0xffff0000, v70
	v_lshlrev_b32_e32 v68, 16, v70
	v_pk_mul_f32 v[180:181], v[120:121], v[68:69]
	v_exp_f32_e64 v120, -v154
	v_exp_f32_e32 v68, v154
	v_exp_f32_e32 v69, v155
	v_exp_f32_e64 v121, -v155
	v_lshlrev_b32_e32 v188, 16, v123
	v_pk_mul_f32 v[122:123], v[188:189], s[24:25] op_sel_hi:[1,0]
	v_cvt_pk_bf16_f32 v75, v190, v191
	v_pk_mul_f32 v[122:123], v[122:123], v[68:69]
	v_and_b32_e32 v69, 0xffff0000, v71
	v_lshlrev_b32_e32 v68, 16, v71
	v_pk_mul_f32 v[154:155], v[120:121], v[68:69]
	v_cvt_pk_bf16_f32 v68, v172, v173
	v_cvt_pk_bf16_f32 v69, v178, v179
	v_cvt_pk_bf16_f32 v70, v152, v153
	v_cvt_pk_bf16_f32 v71, v122, v123
	v_cvt_pk_bf16_f32 v120, v174, v175
	v_cvt_pk_bf16_f32 v121, v148, v149
	v_cvt_pk_bf16_f32 v122, v180, v181
	v_cvt_pk_bf16_f32 v123, v154, v155
	v_cndmask_b32_e64 v148, 0, 1, s[56:57]
	v_cndmask_b32_e64 v149, 0, 1, s[58:59]
	v_cndmask_b32_e64 v148, v149, v148, s[26:27]
	v_and_b32_e32 v148, 1, v148
	v_cmp_eq_u32_e64 s[20:21], 1, v148
	v_cndmask_b32_e64 v149, 0, 1, s[62:63]
	v_cndmask_b32_e64 v151, 0, 1, s[66:67]
	v_cndmask_b32_e64 v148, 0, v229, s[20:21]
	v_perm_b32 v154, v148, v176, s3
	v_cndmask_b32_e64 v148, 0, 1, s[60:61]
	v_cndmask_b32_e64 v148, v149, v148, s[26:27]
	v_cndmask_b32_e64 v149, 0, 1, s[64:65]
	v_cndmask_b32_e64 v149, v151, v149, s[26:27]
	v_and_b32_e32 v148, 1, v148
	v_and_b32_e32 v149, 1, v149
	s_cselect_b32 s0, 0x3f80, 0
	v_cmp_eq_u32_e64 s[4:5], 1, v148
	v_cmp_eq_u32_e64 s[6:7], 1, v149
	s_pack_ll_b32_b16 s12, s0, s0
	v_cndmask_b32_e64 v148, 0, v229, s[4:5]
	v_cndmask_b32_e64 v149, 0, v229, s[6:7]
	v_perm_b32 v155, v149, v148, s3
	v_mov_b32_e32 v152, s12
	v_mov_b32_e32 v153, s12
	s_waitcnt vmcnt(11)
	v_and_b32_e32 v179, 0xffff0000, v136
	v_lshlrev_b32_e32 v178, 16, v136
	v_mfma_f32_16x16x32_bf16 v[172:175], v[76:79], v[152:155], 0
	v_mul_f32_e64 v178, v178, s24
	v_mul_f32_e64 v179, v179, s24
	v_and_b32_e32 v181, 0xffff0000, v137
	v_lshlrev_b32_e32 v180, 16, v137
	v_mfma_f32_16x16x32_bf16 v[172:175], v[84:87], v[168:171], v[172:175]
	v_mul_f32_e64 v180, v180, s24
	v_mul_f32_e64 v181, v181, s24
	s_waitcnt vmcnt(9)
	v_and_b32_e32 v189, 0xffff0000, v117
	v_lshlrev_b32_e32 v188, 16, v117
	v_and_b32_e32 v191, 0xffff0000, v138
	v_lshlrev_b32_e32 v190, 16, v138
	s_nop 0
	v_exp_f32_e32 v148, v172
	v_exp_f32_e64 v172, -v172
	v_exp_f32_e32 v149, v173
	v_exp_f32_e64 v173, -v173
	v_pk_mul_f32 v[190:191], v[190:191], s[24:25] op_sel_hi:[1,0]
	v_pk_mul_f32 v[148:149], v[178:179], v[148:149]
	v_and_b32_e32 v179, 0xffff0000, v116
	v_lshlrev_b32_e32 v178, 16, v116
	v_pk_mul_f32 v[178:179], v[172:173], v[178:179]
	v_exp_f32_e32 v172, v174
	v_exp_f32_e64 v136, -v174
	v_exp_f32_e32 v173, v175
	v_exp_f32_e64 v137, -v175
	v_and_b32_e32 v247, 0xffff0000, v139
	v_pk_mul_f32 v[180:181], v[180:181], v[172:173]
	v_mfma_f32_16x16x32_bf16 v[172:175], v[96:99], v[152:155], 0
	v_mul_f32_e64 v188, v136, v188
	v_mul_f32_e64 v189, v137, v189
	v_lshlrev_b32_e32 v246, 16, v139
	v_pk_mul_f32 v[138:139], v[246:247], s[24:25] op_sel_hi:[1,0]
	v_mfma_f32_16x16x32_bf16 v[172:175], v[100:103], v[168:171], v[172:175]
	s_nop 7
	v_exp_f32_e64 v136, -v172
	v_exp_f32_e32 v116, v172
	v_exp_f32_e32 v117, v173
	v_exp_f32_e64 v137, -v173
	v_pk_mul_f32 v[172:173], v[190:191], v[116:117]
	v_and_b32_e32 v117, 0xffff0000, v118
	v_lshlrev_b32_e32 v116, 16, v118
	v_pk_mul_f32 v[190:191], v[136:137], v[116:117]
	v_exp_f32_e32 v116, v174
	v_exp_f32_e64 v136, -v174
	v_exp_f32_e32 v117, v175
	v_exp_f32_e64 v137, -v175
	v_cvt_pk_bf16_f32 v118, v172, v173
	v_mfma_f32_16x16x32_bf16 v[172:175], v[104:107], v[152:155], 0
	v_mfma_f32_16x16x32_bf16 v[172:175], v[92:95], v[168:171], v[172:175]
	v_mul_f32_e64 v138, v138, v116
	v_mul_f32_e64 v139, v139, v117
	v_and_b32_e32 v117, 0xffff0000, v119
	v_lshlrev_b32_e32 v116, 16, v119
	v_pk_mul_f32 v[246:247], v[136:137], v[116:117]
	v_cvt_pk_bf16_f32 v116, v148, v149
	s_nop 1
	v_exp_f32_e32 v148, v172
	v_exp_f32_e64 v172, -v172
	v_exp_f32_e32 v149, v173
	v_exp_f32_e64 v173, -v173
	v_cvt_pk_bf16_f32 v136, v178, v179
	v_and_b32_e32 v179, 0xffff0000, v156
	v_lshlrev_b32_e32 v178, 16, v156
	v_pk_mul_f32 v[178:179], v[178:179], s[24:25] op_sel_hi:[1,0]
	v_cvt_pk_bf16_f32 v117, v180, v181
	v_pk_mul_f32 v[148:149], v[178:179], v[148:149]
	s_waitcnt vmcnt(8)
; __device__ __forceinline__ float bf2f(bf16_t b) { return __uint_as_float(((unsigned)b) << 16); }
; __device__ __forceinline__ f32x4 mfma16(bf16x8 a, bf16x8 b, f32x4 c) { return __builtin_amdgcn_mfma_f32_16x16x32_bf16(a, b, c, 0, 0, 0); }
; template <int MODE> __device__ void mixer_gla(const Params& p, int l, int n, LAS unsigned char* lds) {
;     ...
;                     for (int jj = 0; jj < 8; ++jj) { const int sidx = SLOT(ks, q, jj); const bool on = dir == 0 ? sidx <= t : sidx >= t; mk[ks][jj] = on ? (short)0x3F80 : (short)0; }
; #pragma unroll
;                 for (int ks2 = 0; ks2 < 2; ++ks2) { f32x4 qe2[2], ke2[2];
; #pragma unroll
;                     for (int e2 = 0; e2 < 2; ++e2) { const int ef = 2 * ks2 + e2;
;                         f32x4 b = mfma16(laop[ef][0], mk[0], zero4); b = mfma16(laop[ef][1], mk[1], b);
; #pragma unroll
;                         for (int r = 0; r < 4; ++r) { qe2[e2][r] = bf2f((bf16_t)qn[tj][ks2][4 * e2 + r]) * 0.125f * __expf(b[r]); ke2[e2][r] = bf2f((bf16_t)kn1[tj][ks2][4 * e2 + r]) * __expf(-b[r]); } }
;                     QEop[tj][ks2] = pack8(qe2[0], qe2[1]); KEop[tj][ks2] = pack8(ke2[0], ke2[1]); }
	v_and_b32_e32 v179, 0xffff0000, v132
	v_lshlrev_b32_e32 v178, 16, v132
	v_pk_mul_f32 v[172:173], v[172:173], v[178:179]
	v_exp_f32_e32 v178, v174
	v_exp_f32_e64 v174, -v174
	v_exp_f32_e32 v179, v175
	v_and_b32_e32 v181, 0xffff0000, v157
	v_lshlrev_b32_e32 v180, 16, v157
	v_pk_mul_f32 v[156:157], v[180:181], s[24:25] op_sel_hi:[1,0]
	v_pk_mul_f32 v[178:179], v[156:157], v[178:179]
	v_mfma_f32_16x16x32_bf16 v[154:157], v[80:83], v[152:155], 0
	v_and_b32_e32 v181, 0xffff0000, v133
	v_lshlrev_b32_e32 v180, 16, v133
	v_exp_f32_e64 v175, -v175
	v_mfma_f32_16x16x32_bf16 v[154:157], v[112:115], v[168:171], v[154:157]
	v_and_b32_e32 v169, 0xffff0000, v158
	v_lshlrev_b32_e32 v168, 16, v158
	v_pk_mul_f32 v[168:169], v[168:169], s[24:25] op_sel_hi:[1,0]
	v_and_b32_e32 v171, 0xffff0000, v159
	v_lshlrev_b32_e32 v170, 16, v159
	s_nop 2
	v_exp_f32_e32 v132, v154
	v_exp_f32_e64 v154, -v154
	v_exp_f32_e32 v133, v155
	v_exp_f32_e64 v155, -v155
	v_pk_mul_f32 v[158:159], v[170:171], s[24:25] op_sel_hi:[1,0]
	v_pk_mul_f32 v[168:169], v[168:169], v[132:133]
	v_and_b32_e32 v133, 0xffff0000, v134
	v_lshlrev_b32_e32 v132, 16, v134
	v_pk_mul_f32 v[154:155], v[154:155], v[132:133]
	v_exp_f32_e32 v132, v156
	v_exp_f32_e64 v156, -v156
	v_exp_f32_e32 v133, v157
	v_exp_f32_e64 v157, -v157
	v_pk_mul_f32 v[174:175], v[174:175], v[180:181]
	v_pk_mul_f32 v[158:159], v[158:159], v[132:133]
	v_and_b32_e32 v133, 0xffff0000, v135
	v_lshlrev_b32_e32 v132, 16, v135
	v_pk_mul_f32 v[170:171], v[156:157], v[132:133]
	v_cvt_pk_bf16_f32 v119, v138, v139
	v_cvt_pk_bf16_f32 v137, v188, v189
	v_cvt_pk_bf16_f32 v138, v190, v191
	v_cvt_pk_bf16_f32 v139, v246, v247
	v_cvt_pk_bf16_f32 v132, v148, v149
	v_cvt_pk_bf16_f32 v133, v178, v179
	v_cvt_pk_bf16_f32 v134, v168, v169
	v_cvt_pk_bf16_f32 v135, v158, v159
	v_cvt_pk_bf16_f32 v156, v172, v173
	v_cvt_pk_bf16_f32 v157, v174, v175
	v_cvt_pk_bf16_f32 v158, v154, v155
	v_cvt_pk_bf16_f32 v159, v170, v171
	v_cndmask_b32_e64 v148, 0, 1, s[68:69]
	v_cndmask_b32_e64 v149, 0, 1, s[70:71]
	v_cndmask_b32_e64 v148, v149, v148, s[26:27]
	v_cndmask_b32_e64 v149, 0, 1, s[72:73]
	v_cndmask_b32_e64 v151, 0, 1, s[74:75]
	s_mov_b32 s14, s12
	s_mov_b32 s15, s12
	v_cndmask_b32_e64 v149, v151, v149, s[26:27]
	v_cndmask_b32_e64 v151, 0, 1, s[76:77]
	v_cndmask_b32_e64 v153, 0, 1, s[78:79]
	s_mov_b32 s13, s12
	v_mov_b64_e32 v[248:249], s[14:15]
	v_cndmask_b32_e64 v151, v153, v151, s[26:27]
	v_mov_b64_e32 v[246:247], s[12:13]
	v_and_b32_e32 v148, 1, v148
	v_and_b32_e32 v149, 1, v149
	v_and_b32_e32 v151, 1, v151
	v_mfma_f32_16x16x32_bf16 v[168:171], v[76:79], v[246:249], 0
	v_cmp_eq_u32_e64 s[8:9], 1, v148
	v_cmp_eq_u32_e64 s[10:11], 1, v149
	v_cmp_eq_u32_e64 s[12:13], 1, v151
	v_cndmask_b32_e64 v148, 0, v229, s[8:9]
	v_cndmask_b32_e64 v149, 0, v229, s[10:11]
	v_cndmask_b32_e64 v76, 0, v229, s[12:13]
	v_perm_b32 v148, v148, v176, s3
	v_perm_b32 v149, v76, v149, s3
	v_mov_b32_e32 v151, v150
	s_waitcnt vmcnt(7)
	v_and_b32_e32 v173, 0xffff0000, v164
	v_lshlrev_b32_e32 v172, 16, v164
	v_mfma_f32_16x16x32_bf16 v[76:79], v[84:87], v[148:151], v[168:171]
	v_mul_f32_e64 v172, v172, s24
	v_mul_f32_e64 v173, v173, s24
	s_nop 5
	v_exp_f32_e32 v154, v76
	v_exp_f32_e32 v155, v77
	v_exp_f32_e64 v76, -v76
	v_exp_f32_e64 v77, -v77
	v_pk_mul_f32 v[154:155], v[172:173], v[154:155]
	s_waitcnt vmcnt(5)
	v_and_b32_e32 v173, 0xffff0000, v160
	v_lshlrev_b32_e32 v172, 16, v160
	v_pk_mul_f32 v[178:179], v[76:77], v[172:173]
	v_exp_f32_e32 v76, v78
	v_exp_f32_e64 v78, -v78
	v_exp_f32_e32 v77, v79
	v_and_b32_e32 v173, 0xffff0000, v165
	v_lshlrev_b32_e32 v172, 16, v165
	v_pk_mul_f32 v[164:165], v[172:173], s[24:25] op_sel_hi:[1,0]
	v_mfma_f32_16x16x32_bf16 v[172:175], v[96:99], v[246:249], 0
	v_mul_f32_e64 v164, v164, v76
	v_mul_f32_e64 v165, v165, v77
	v_exp_f32_e64 v79, -v79
	v_and_b32_e32 v77, 0xffff0000, v161
	v_lshlrev_b32_e32 v76, 16, v161
	v_and_b32_e32 v161, 0xffff0000, v166
	v_pk_mul_f32 v[98:99], v[78:79], v[76:77]
	v_mfma_f32_16x16x32_bf16 v[76:79], v[100:103], v[148:151], v[172:175]
	v_lshlrev_b32_e32 v160, 16, v166
	v_pk_mul_f32 v[160:161], v[160:161], s[24:25] op_sel_hi:[1,0]
	s_nop 5
	v_exp_f32_e32 v96, v76
	v_exp_f32_e32 v97, v77
	v_exp_f32_e64 v76, -v76
	v_exp_f32_e64 v77, -v77
	v_pk_mul_f32 v[96:97], v[160:161], v[96:97]
	v_and_b32_e32 v161, 0xffff0000, v162
	v_lshlrev_b32_e32 v160, 16, v162
	v_pk_mul_f32 v[180:181], v[76:77], v[160:161]
	v_exp_f32_e32 v76, v78
	v_exp_f32_e64 v78, -v78
	v_exp_f32_e32 v77, v79
	v_exp_f32_e64 v79, -v79
	v_and_b32_e32 v161, 0xffff0000, v167
	v_lshlrev_b32_e32 v160, 16, v167
	v_pk_mul_f32 v[160:161], v[160:161], s[24:25] op_sel_hi:[1,0]
	s_nop 0
	v_pk_mul_f32 v[160:161], v[160:161], v[76:77]
	v_and_b32_e32 v77, 0xffff0000, v163
	v_lshlrev_b32_e32 v76, 16, v163
	v_pk_mul_f32 v[166:167], v[78:79], v[76:77]
	v_cvt_pk_bf16_f32 v79, v160, v161
	v_mfma_f32_16x16x32_bf16 v[160:163], v[104:107], v[246:249], 0
	v_cvt_pk_bf16_f32 v76, v154, v155
	v_cvt_pk_bf16_f32 v77, v164, v165
	v_and_b32_e32 v165, 0xffff0000, v144
	v_mfma_f32_16x16x32_bf16 v[104:107], v[92:95], v[148:151], v[160:163]
	v_lshlrev_b32_e32 v164, 16, v144
	v_pk_mul_f32 v[164:165], v[164:165], s[24:25] op_sel_hi:[1,0]
	v_cvt_pk_bf16_f32 v78, v96, v97
	v_cvt_pk_bf16_f32 v97, v98, v99
	v_cvt_pk_bf16_f32 v99, v166, v167
	s_nop 2
	v_exp_f32_e32 v154, v104
	v_exp_f32_e32 v155, v105
	v_exp_f32_e64 v104, -v104
	v_exp_f32_e64 v105, -v105
	v_pk_mul_f32 v[154:155], v[164:165], v[154:155]
	s_waitcnt vmcnt(4)
; __device__ __forceinline__ float bf2f(bf16_t b) { return __uint_as_float(((unsigned)b) << 16); }
; __device__ __forceinline__ f32x4 mfma16(bf16x8 a, bf16x8 b, f32x4 c) { return __builtin_amdgcn_mfma_f32_16x16x32_bf16(a, b, c, 0, 0, 0); }
; template <int MODE> __device__ void mixer_gla(const Params& p, int l, int n, LAS unsigned char* lds) {
;     ...
;                     for (int jj = 0; jj < 8; ++jj) { const int sidx = SLOT(ks, q, jj); const bool on = dir == 0 ? sidx <= t : sidx >= t; mk[ks][jj] = on ? (short)0x3F80 : (short)0; }
; #pragma unroll
;                 for (int ks2 = 0; ks2 < 2; ++ks2) { f32x4 qe2[2], ke2[2];
; #pragma unroll
;                     for (int e2 = 0; e2 < 2; ++e2) { const int ef = 2 * ks2 + e2;
;                         f32x4 b = mfma16(laop[ef][0], mk[0], zero4); b = mfma16(laop[ef][1], mk[1], b);
; #pragma unroll
;                         for (int r = 0; r < 4; ++r) { qe2[e2][r] = bf2f((bf16_t)qn[tj][ks2][4 * e2 + r]) * 0.125f * __expf(b[r]); ke2[e2][r] = bf2f((bf16_t)kn1[tj][ks2][4 * e2 + r]) * __expf(-b[r]); } }
;                     QEop[tj][ks2] = pack8(qe2[0], qe2[1]); KEop[tj][ks2] = pack8(ke2[0], ke2[1]); }
	v_and_b32_e32 v165, 0xffff0000, v140
	v_lshlrev_b32_e32 v164, 16, v140
	v_pk_mul_f32 v[104:105], v[104:105], v[164:165]
	v_exp_f32_e32 v164, v106
	v_exp_f32_e32 v165, v107
	v_and_b32_e32 v167, 0xffff0000, v145
	v_lshlrev_b32_e32 v166, 16, v145
	v_pk_mul_f32 v[144:145], v[166:167], s[24:25] op_sel_hi:[1,0]
	v_exp_f32_e64 v106, -v106
	v_pk_mul_f32 v[144:145], v[144:145], v[164:165]
	v_exp_f32_e64 v107, -v107
	v_mfma_f32_16x16x32_bf16 v[164:167], v[80:83], v[246:249], 0
	v_and_b32_e32 v81, 0xffff0000, v141
	v_lshlrev_b32_e32 v80, 16, v141
	v_pk_mul_f32 v[106:107], v[106:107], v[80:81]
	v_mfma_f32_16x16x32_bf16 v[80:83], v[112:115], v[148:151], v[164:167]
	v_and_b32_e32 v149, 0xffff0000, v146
	v_lshlrev_b32_e32 v148, 16, v146
	v_pk_mul_f32 v[148:149], v[148:149], s[24:25] op_sel_hi:[1,0]
	v_and_b32_e32 v151, 0xffff0000, v147
	v_lshlrev_b32_e32 v150, 16, v147
	s_nop 2
	v_exp_f32_e32 v140, v80
	v_exp_f32_e32 v141, v81
	v_exp_f32_e64 v80, -v80
	v_exp_f32_e64 v81, -v81
	v_pk_mul_f32 v[140:141], v[148:149], v[140:141]
	v_and_b32_e32 v149, 0xffff0000, v142
	v_lshlrev_b32_e32 v148, 16, v142
	v_pk_mul_f32 v[148:149], v[80:81], v[148:149]
	v_exp_f32_e32 v80, v82
	v_exp_f32_e64 v82, -v82
	v_exp_f32_e32 v81, v83
	v_exp_f32_e64 v83, -v83
	v_pk_mul_f32 v[146:147], v[150:151], s[24:25] op_sel_hi:[1,0]
	v_cvt_pk_bf16_f32 v96, v178, v179
	v_pk_mul_f32 v[146:147], v[146:147], v[80:81]
	v_and_b32_e32 v81, 0xffff0000, v143
	v_lshlrev_b32_e32 v80, 16, v143
	v_pk_mul_f32 v[142:143], v[82:83], v[80:81]
	v_cvt_pk_bf16_f32 v98, v180, v181
	v_cvt_pk_bf16_f32 v80, v154, v155
	v_cvt_pk_bf16_f32 v81, v144, v145
	v_cvt_pk_bf16_f32 v82, v140, v141
	v_cvt_pk_bf16_f32 v83, v146, v147
	v_cvt_pk_bf16_f32 v104, v104, v105
	v_cvt_pk_bf16_f32 v105, v106, v107
	v_cvt_pk_bf16_f32 v106, v148, v149
	v_cvt_pk_bf16_f32 v107, v142, v143
	v_cndmask_b32_e64 v140, 0, 1, s[80:81]
	v_cndmask_b32_e64 v141, 0, 1, s[82:83]
	v_cndmask_b32_e64 v140, v141, v140, s[26:27]
	v_and_b32_e32 v140, 1, v140
	v_cmp_eq_u32_e64 s[0:1], 1, v140
	v_cndmask_b32_e64 v141, 0, 1, s[86:87]
	v_cndmask_b32_e64 v142, 0, 1, s[90:91]
	v_cndmask_b32_e64 v140, 0, v229, s[0:1]
	v_perm_b32 v154, v140, v176, s3
	v_cndmask_b32_e64 v140, 0, 1, s[84:85]
	v_cndmask_b32_e64 v140, v141, v140, s[26:27]
	v_cndmask_b32_e64 v141, 0, 1, s[88:89]
	v_cndmask_b32_e64 v141, v142, v141, s[26:27]
	v_and_b32_e32 v140, 1, v140
	v_and_b32_e32 v141, 1, v141
	v_cmp_eq_u32_e64 s[18:19], 1, v140
	v_cmp_eq_u32_e64 s[22:23], 1, v141
	v_mov_b32_e32 v153, v152
	v_cndmask_b32_e64 v140, 0, v229, s[18:19]
	v_cndmask_b32_e64 v141, 0, v229, s[22:23]
	v_perm_b32 v155, v141, v140, s3
	s_waitcnt vmcnt(3)
	v_and_b32_e32 v143, 0xffff0000, v128
	v_lshlrev_b32_e32 v142, 16, v128
	v_mfma_f32_16x16x32_bf16 v[84:87], v[84:87], v[152:155], v[168:171]
	v_mul_f32_e64 v142, v142, s24
	v_mul_f32_e64 v143, v143, s24
	v_and_b32_e32 v145, 0xffff0000, v129
	v_lshlrev_b32_e32 v144, 16, v129
	v_pk_mul_f32 v[128:129], v[144:145], s[24:25] op_sel_hi:[1,0]
	v_mfma_f32_16x16x32_bf16 v[92:95], v[92:95], v[152:155], v[160:163]
	s_nop 1
	v_exp_f32_e32 v140, v84
	v_exp_f32_e32 v141, v85
	v_exp_f32_e64 v84, -v84
	v_exp_f32_e64 v85, -v85
	v_pk_mul_f32 v[140:141], v[142:143], v[140:141]
	s_waitcnt vmcnt(1)
	v_and_b32_e32 v143, 0xffff0000, v124
	v_lshlrev_b32_e32 v142, 16, v124
	v_pk_mul_f32 v[142:143], v[84:85], v[142:143]
	v_exp_f32_e32 v84, v86
	v_exp_f32_e64 v86, -v86
	v_exp_f32_e32 v85, v87
	v_exp_f32_e64 v87, -v87
	v_and_b32_e32 v145, 0xffff0000, v131
	v_pk_mul_f32 v[128:129], v[128:129], v[84:85]
	v_and_b32_e32 v85, 0xffff0000, v125
	v_lshlrev_b32_e32 v84, 16, v125
	v_pk_mul_f32 v[124:125], v[86:87], v[84:85]
	v_mfma_f32_16x16x32_bf16 v[84:87], v[100:103], v[152:155], v[172:175]
	v_and_b32_e32 v103, 0xffff0000, v130
	v_lshlrev_b32_e32 v102, 16, v130
	v_pk_mul_f32 v[102:103], v[102:103], s[24:25] op_sel_hi:[1,0]
	v_lshlrev_b32_e32 v144, 16, v131
	v_pk_mul_f32 v[130:131], v[144:145], s[24:25] op_sel_hi:[1,0]
	s_nop 2
	v_exp_f32_e32 v100, v84
	v_exp_f32_e32 v101, v85
	v_exp_f32_e64 v84, -v84
	v_exp_f32_e64 v85, -v85
	v_pk_mul_f32 v[100:101], v[102:103], v[100:101]
	v_and_b32_e32 v103, 0xffff0000, v126
	v_lshlrev_b32_e32 v102, 16, v126
	v_pk_mul_f32 v[102:103], v[84:85], v[102:103]
	v_exp_f32_e32 v84, v86
	v_exp_f32_e64 v86, -v86
	v_exp_f32_e32 v85, v87
	v_exp_f32_e64 v87, -v87
	v_cvt_pk_bf16_f32 v102, v102, v103
	v_pk_mul_f32 v[130:131], v[130:131], v[84:85]
	v_and_b32_e32 v85, 0xffff0000, v127
	v_lshlrev_b32_e32 v84, 16, v127
	v_pk_mul_f32 v[126:127], v[86:87], v[84:85]
	v_cvt_pk_bf16_f32 v86, v100, v101
	v_cvt_pk_bf16_f32 v101, v124, v125
	v_exp_f32_e32 v124, v92
	v_exp_f32_e32 v125, v93
	v_exp_f32_e64 v92, -v92
	v_exp_f32_e64 v93, -v93
	v_cvt_pk_bf16_f32 v103, v126, v127
	v_and_b32_e32 v127, 0xffff0000, v108
	v_lshlrev_b32_e32 v126, 16, v108
	v_pk_mul_f32 v[126:127], v[126:127], s[24:25] op_sel_hi:[1,0]
	v_cvt_pk_bf16_f32 v85, v128, v129
	v_pk_mul_f32 v[124:125], v[126:127], v[124:125]
	s_waitcnt vmcnt(0)
; __device__ __forceinline__ float bf2f(bf16_t b) { return __uint_as_float(((unsigned)b) << 16); }
; __device__ __forceinline__ f32x4 mfma16(bf16x8 a, bf16x8 b, f32x4 c) { return __builtin_amdgcn_mfma_f32_16x16x32_bf16(a, b, c, 0, 0, 0); }
; template <int MODE> __device__ void mixer_gla(const Params& p, int l, int n, LAS unsigned char* lds) {
;     ...
;                     for (int e2 = 0; e2 < 2; ++e2) { const int ef = 2 * ks2 + e2;
;                         f32x4 b = mfma16(laop[ef][0], mk[0], zero4); b = mfma16(laop[ef][1], mk[1], b);
; #pragma unroll
;                         for (int r = 0; r < 4; ++r) { qe2[e2][r] = bf2f((bf16_t)qn[tj][ks2][4 * e2 + r]) * 0.125f * __expf(b[r]); ke2[e2][r] = bf2f((bf16_t)kn1[tj][ks2][4 * e2 + r]) * __expf(-b[r]); } }
;                     QEop[tj][ks2] = pack8(qe2[0], qe2[1]); KEop[tj][ks2] = pack8(ke2[0], ke2[1]); }
;                 __builtin_amdgcn_sched_barrier(0);
;             }
;             const bf16_t* SP = spT + ((size_t)(dir * NCH + n) * 4 + h) * 8192 + (size_t)(64 * vh) * 64;
;             bf16x8 spf[4][2];
; #pragma unroll
;             for (int vf = 0; vf < 4; ++vf)
; #pragma unroll
;                 for (int ks = 0; ks < 2; ++ks) spf[vf][ks] = *(const bf16x8*)(SP + (16 * vf + c) * 64 + 32 * ks + 8 * q);
;             __builtin_amdgcn_sched_barrier(0);
;             bf16x8 Pop[4][2];
; #pragma unroll
;             for (int ti = 0; ti < 4; ++ti)
; #pragma unroll
;                 for (int ksp = 0; ksp < 2; ++ksp) { f32x4 pm[2];
; #pragma unroll
;                     for (int j2 = 0; j2 < 2; ++j2) { const int tjj = 2 * ksp + j2;
;                         f32x4 sc = mfma16(KEop[tjj][0], QEop[ti][0], zero4); sc = mfma16(KEop[tjj][1], QEop[ti][1], sc);
; #pragma unroll
;                         for (int r = 0; r < 4; ++r) { const int j = 16 * tjj + 4 * q + r, i = 16 * ti + c; const bool keep = dir == 0 ? j <= i : j >= i; pm[j2][r] = keep ? sc[r] : 0.f; } }
;                     Pop[ti][ksp] = pack8(pm[0], pm[1]); __builtin_amdgcn_sched_barrier(0); }
	v_and_b32_e32 v127, 0xffff0000, v88
	v_lshlrev_b32_e32 v126, 16, v88
	v_pk_mul_f32 v[126:127], v[92:93], v[126:127]
	v_exp_f32_e32 v92, v94
	v_exp_f32_e64 v94, -v94
	v_exp_f32_e32 v93, v95
	v_exp_f32_e64 v95, -v95
	v_and_b32_e32 v129, 0xffff0000, v109
	v_lshlrev_b32_e32 v128, 16, v109
	v_pk_mul_f32 v[108:109], v[128:129], s[24:25] op_sel_hi:[1,0]
	v_cvt_pk_bf16_f32 v84, v140, v141
	v_pk_mul_f32 v[108:109], v[108:109], v[92:93]
	v_and_b32_e32 v93, 0xffff0000, v89
	v_lshlrev_b32_e32 v92, 16, v89
	v_pk_mul_f32 v[128:129], v[94:95], v[92:93]
	v_mfma_f32_16x16x32_bf16 v[92:95], v[112:115], v[152:155], v[164:167]
	v_and_b32_e32 v113, 0xffff0000, v110
	v_lshlrev_b32_e32 v112, 16, v110
	v_pk_mul_f32 v[112:113], v[112:113], s[24:25] op_sel_hi:[1,0]
	v_and_b32_e32 v115, 0xffff0000, v111
	v_lshlrev_b32_e32 v114, 16, v111
	s_nop 2
	v_exp_f32_e32 v88, v92
	v_exp_f32_e64 v92, -v92
	v_exp_f32_e32 v89, v93
	v_exp_f32_e64 v93, -v93
	v_pk_mul_f32 v[110:111], v[114:115], s[24:25] op_sel_hi:[1,0]
	v_pk_mul_f32 v[112:113], v[112:113], v[88:89]
	v_and_b32_e32 v89, 0xffff0000, v90
	v_lshlrev_b32_e32 v88, 16, v90
	v_pk_mul_f32 v[92:93], v[92:93], v[88:89]
	v_exp_f32_e32 v88, v94
	v_exp_f32_e64 v94, -v94
	v_exp_f32_e32 v89, v95
	v_exp_f32_e64 v95, -v95
	v_cvt_pk_bf16_f32 v87, v130, v131
	v_pk_mul_f32 v[110:111], v[110:111], v[88:89]
	v_and_b32_e32 v89, 0xffff0000, v91
	v_lshlrev_b32_e32 v88, 16, v91
	v_pk_mul_f32 v[94:95], v[94:95], v[88:89]
	v_cvt_pk_bf16_f32 v100, v142, v143
	v_cvt_pk_bf16_f32 v88, v124, v125
	v_cvt_pk_bf16_f32 v89, v108, v109
	v_cvt_pk_bf16_f32 v90, v112, v113
	v_cvt_pk_bf16_f32 v91, v110, v111
	v_cvt_pk_bf16_f32 v148, v126, v127
	v_cvt_pk_bf16_f32 v149, v128, v129
	v_cvt_pk_bf16_f32 v150, v92, v93
	v_cvt_pk_bf16_f32 v151, v94, v95
	s_add_i32 s14, s34, s43
	s_ashr_i32 s15, s14, 31
	s_lshl_b64 s[14:15], s[14:15], 16
	v_lshl_add_u64 v[92:93], v[220:221], 0, s[14:15]
	s_movk_i32 s2, 0x1000
	global_load_dwordx4 v[152:155], v[92:93], off
	global_load_dwordx4 v[160:163], v[92:93], off offset:64
	global_load_dwordx4 v[164:167], v[92:93], off offset:2048
	global_load_dwordx4 v[144:147], v[92:93], off offset:2112
	v_add_co_u32_e32 v92, vcc, s2, v92
	s_nop 1
	v_addc_co_u32_e32 v93, vcc, 0, v93, vcc
	global_load_dwordx4 v[128:131], v[92:93], off
	global_load_dwordx4 v[112:115], v[92:93], off offset:64
	global_load_dwordx4 v[108:111], v[92:93], off offset:2048
	s_nop 0
	global_load_dwordx4 v[92:95], v[92:93], off offset:2112
	v_mfma_f32_16x16x32_bf16 v[124:127], v[72:75], v[64:67], 0
	v_mfma_f32_16x16x32_bf16 v[124:127], v[120:123], v[68:71], v[124:127]
	v_mfma_f32_16x16x32_bf16 v[140:143], v[136:139], v[64:67], 0
	s_nop 6
	v_cndmask_b32_e64 v168, 0, v124, s[16:17]
	v_cndmask_b32_e64 v169, 0, v125, s[92:93]
	v_cndmask_b32_e64 v170, 0, v126, s[94:95]
	v_cndmask_b32_e64 v171, 0, v127, s[96:97]
	v_mfma_f32_16x16x32_bf16 v[124:127], v[156:159], v[68:71], v[140:143]
	s_nop 7
	v_cndmask_b32_e64 v140, v124, 0, s[26:27]
	v_cndmask_b32_e64 v141, v125, 0, s[26:27]
	v_cndmask_b32_e64 v142, v126, 0, s[26:27]
	v_cndmask_b32_e64 v127, v127, 0, s[26:27]
	v_cvt_pk_bf16_f32 v124, v168, v169
	v_cvt_pk_bf16_f32 v125, v170, v171
	v_cvt_pk_bf16_f32 v126, v140, v141
	v_cvt_pk_bf16_f32 v127, v142, v127
	v_mfma_f32_16x16x32_bf16 v[140:143], v[96:99], v[64:67], 0
	v_mfma_f32_16x16x32_bf16 v[140:143], v[104:107], v[68:71], v[140:143]
	v_mfma_f32_16x16x32_bf16 v[168:171], v[100:103], v[64:67], 0
	s_nop 6
	v_cndmask_b32_e64 v172, v140, 0, s[26:27]
	v_cndmask_b32_e64 v173, v141, 0, s[26:27]
	v_cndmask_b32_e64 v174, v142, 0, s[26:27]
	v_cndmask_b32_e64 v175, v143, 0, s[26:27]
	v_mfma_f32_16x16x32_bf16 v[140:143], v[148:151], v[68:71], v[168:171]
	s_nop 7
	v_cndmask_b32_e64 v168, v140, 0, s[26:27]
	v_cndmask_b32_e64 v169, v141, 0, s[26:27]
	v_cndmask_b32_e64 v170, v142, 0, s[26:27]
	v_cndmask_b32_e64 v143, v143, 0, s[26:27]
	v_cvt_pk_bf16_f32 v140, v172, v173
	v_cvt_pk_bf16_f32 v141, v174, v175
	v_cvt_pk_bf16_f32 v142, v168, v169
	v_cvt_pk_bf16_f32 v143, v170, v143
	v_mfma_f32_16x16x32_bf16 v[168:171], v[72:75], v[116:119], 0
	v_mfma_f32_16x16x32_bf16 v[168:171], v[120:123], v[132:135], v[168:171]
	v_mfma_f32_16x16x32_bf16 v[172:175], v[136:139], v[116:119], 0
	s_nop 6
	v_cndmask_b32_e64 v176, 0, v168, s[26:27]
	v_cndmask_b32_e64 v178, 0, v169, s[26:27]
	v_cndmask_b32_e64 v179, 0, v170, s[26:27]
	v_cndmask_b32_e64 v180, 0, v171, s[26:27]
	v_mfma_f32_16x16x32_bf16 v[168:171], v[156:159], v[132:135], v[172:175]
	s_nop 7
	v_cndmask_b32_e64 v172, 0, v168, s[16:17]
	v_cndmask_b32_e64 v173, 0, v169, s[20:21]
	v_cndmask_b32_e64 v174, 0, v170, s[4:5]
	v_cndmask_b32_e64 v171, 0, v171, s[6:7]
	v_cvt_pk_bf16_f32 v168, v176, v178
	v_cvt_pk_bf16_f32 v169, v179, v180
	v_cvt_pk_bf16_f32 v170, v172, v173
	v_cvt_pk_bf16_f32 v171, v174, v171
	v_mfma_f32_16x16x32_bf16 v[172:175], v[96:99], v[116:119], 0
	v_mfma_f32_16x16x32_bf16 v[172:175], v[104:107], v[132:135], v[172:175]
	v_mfma_f32_16x16x32_bf16 v[246:249], v[100:103], v[116:119], 0
	s_nop 6
	v_cndmask_b32_e64 v176, v172, 0, s[26:27]
	v_cndmask_b32_e64 v178, v173, 0, s[26:27]
	v_cndmask_b32_e64 v179, v174, 0, s[26:27]
	v_cndmask_b32_e64 v180, v175, 0, s[26:27]
	v_mfma_f32_16x16x32_bf16 v[172:175], v[148:151], v[132:135], v[246:249]
	s_nop 7
	v_cndmask_b32_e64 v181, v172, 0, s[26:27]
	v_cndmask_b32_e64 v188, v173, 0, s[26:27]
	v_cndmask_b32_e64 v189, v174, 0, s[26:27]
	v_cndmask_b32_e64 v175, v175, 0, s[26:27]
	v_cvt_pk_bf16_f32 v172, v176, v178
	v_cvt_pk_bf16_f32 v173, v179, v180
	v_cvt_pk_bf16_f32 v174, v181, v188
	v_cvt_pk_bf16_f32 v175, v189, v175
	v_mfma_f32_16x16x32_bf16 v[246:249], v[72:75], v[76:79], 0
	v_mfma_f32_16x16x32_bf16 v[178:181], v[136:139], v[76:79], 0
; #define LAS __attribute__((address_space(3)))
; __device__ __forceinline__ f32x4 mfma16(bf16x8 a, bf16x8 b, f32x4 c) { return __builtin_amdgcn_mfma_f32_16x16x32_bf16(a, b, c, 0, 0, 0); }
; template <int MODE> __device__ void mixer_gla(const Params& p, int l, int n, LAS unsigned char* lds) {
;     ...
;             for (int ti = 0; ti < 4; ++ti)
; #pragma unroll
;                 for (int ksp = 0; ksp < 2; ++ksp) { f32x4 pm[2];
; #pragma unroll
;                     for (int j2 = 0; j2 < 2; ++j2) { const int tjj = 2 * ksp + j2;
;                         f32x4 sc = mfma16(KEop[tjj][0], QEop[ti][0], zero4); sc = mfma16(KEop[tjj][1], QEop[ti][1], sc);
; #pragma unroll
;                         for (int r = 0; r < 4; ++r) { const int j = 16 * tjj + 4 * q + r, i = 16 * ti + c; const bool keep = dir == 0 ? j <= i : j >= i; pm[j2][r] = keep ? sc[r] : 0.f; } }
;                     Pop[ti][ksp] = pack8(pm[0], pm[1]); __builtin_amdgcn_sched_barrier(0); }
; #pragma unroll
;             for (int vf = 0; vf < 4; ++vf)
; #pragma unroll
;                 for (int ks = 0; ks < 2; ++ks) {
;                     const u32x2 v0 = *(const LAS u32x2*)(VTw + (16 * vf + c) * 72 + 32 * ks + 4 * q), v1 = *(const LAS u32x2*)(VTw + (16 * vf + c) * 72 + 32 * ks + 16 + 4 * q);
;                     const bf16x8 vtf = __builtin_bit_cast(bf16x8, (u32x4){v0.x, v0.y, v1.x, v1.y});
; #pragma unroll
;                     for (int ti = 0; ti < 4; ++ti) { acc[vf][ti] = mfma16(vtf, Pop[ti][ks], acc[vf][ti]); acc[vf][ti] = mfma16(spf[vf][ks], QEop[ti][ks], acc[vf][ti]); }
;                     if (ks == 1 && (vf & 1)) __builtin_amdgcn_sched_barrier(0);
	v_mfma_f32_16x16x32_bf16 v[246:249], v[120:123], v[80:83], v[246:249]
	v_mfma_f32_16x16x32_bf16 v[178:181], v[156:159], v[80:83], v[178:181]
	s_nop 6
	v_cndmask_b32_e64 v176, 0, v246, s[26:27]
	v_cndmask_b32_e64 v188, 0, v247, s[26:27]
	v_cndmask_b32_e64 v189, 0, v248, s[26:27]
	v_cndmask_b32_e64 v190, 0, v249, s[26:27]
	v_cndmask_b32_e64 v191, 0, v178, s[26:27]
	v_cndmask_b32_e64 v201, 0, v179, s[26:27]
	v_cndmask_b32_e64 v246, 0, v180, s[26:27]
	v_cndmask_b32_e64 v181, 0, v181, s[26:27]
	v_cvt_pk_bf16_f32 v178, v176, v188
	v_cvt_pk_bf16_f32 v179, v189, v190
	v_cvt_pk_bf16_f32 v180, v191, v201
	v_cvt_pk_bf16_f32 v181, v246, v181
	v_mfma_f32_16x16x32_bf16 v[246:249], v[96:99], v[76:79], 0
	v_mfma_f32_16x16x32_bf16 v[188:191], v[100:103], v[76:79], 0
	v_mfma_f32_16x16x32_bf16 v[246:249], v[104:107], v[80:83], v[246:249]
	v_mfma_f32_16x16x32_bf16 v[188:191], v[148:151], v[80:83], v[188:191]
	s_nop 6
	v_cndmask_b32_e64 v176, 0, v246, s[16:17]
	v_cndmask_b32_e64 v201, 0, v247, s[8:9]
	v_cndmask_b32_e64 v246, 0, v248, s[10:11]
	v_cndmask_b32_e64 v247, 0, v249, s[12:13]
	v_cndmask_b32_e64 v248, v188, 0, s[26:27]
	v_cndmask_b32_e64 v249, v189, 0, s[26:27]
	v_cndmask_b32_e64 v224, v190, 0, s[26:27]
	v_cndmask_b32_e64 v191, v191, 0, s[26:27]
	v_cvt_pk_bf16_f32 v188, v176, v201
	v_cvt_pk_bf16_f32 v189, v246, v247
	v_cvt_pk_bf16_f32 v190, v248, v249
	v_cvt_pk_bf16_f32 v191, v224, v191
	v_mfma_f32_16x16x32_bf16 v[72:75], v[72:75], v[84:87], 0
	v_mfma_f32_16x16x32_bf16 v[72:75], v[120:123], v[88:91], v[72:75]
	v_mfma_f32_16x16x32_bf16 v[120:123], v[136:139], v[84:87], 0
	s_nop 6
	v_cndmask_b32_e64 v176, 0, v72, s[26:27]
	v_cndmask_b32_e64 v136, 0, v73, s[26:27]
	v_cndmask_b32_e64 v137, 0, v74, s[26:27]
	v_cndmask_b32_e64 v138, 0, v75, s[26:27]
	v_mfma_f32_16x16x32_bf16 v[72:75], v[156:159], v[88:91], v[120:123]
	s_nop 7
	v_cndmask_b32_e64 v120, 0, v72, s[26:27]
	v_cndmask_b32_e64 v121, 0, v73, s[26:27]
	v_cndmask_b32_e64 v122, 0, v74, s[26:27]
	v_cndmask_b32_e64 v75, 0, v75, s[26:27]
	v_cvt_pk_bf16_f32 v72, v176, v136
	v_cvt_pk_bf16_f32 v73, v137, v138
	v_cvt_pk_bf16_f32 v74, v120, v121
	v_cvt_pk_bf16_f32 v75, v122, v75
	v_mfma_f32_16x16x32_bf16 v[96:99], v[96:99], v[84:87], 0
	v_mfma_f32_16x16x32_bf16 v[96:99], v[104:107], v[88:91], v[96:99]
	v_mfma_f32_16x16x32_bf16 v[100:103], v[100:103], v[84:87], 0
	s_nop 6
	v_cndmask_b32_e64 v104, 0, v96, s[26:27]
	v_cndmask_b32_e64 v105, 0, v97, s[26:27]
	v_cndmask_b32_e64 v106, 0, v98, s[26:27]
	v_cndmask_b32_e64 v107, 0, v99, s[26:27]
	v_mfma_f32_16x16x32_bf16 v[96:99], v[148:151], v[88:91], v[100:103]
	s_nop 7
	v_cndmask_b32_e64 v100, 0, v96, s[16:17]
	v_cndmask_b32_e64 v101, 0, v97, s[0:1]
	v_cndmask_b32_e64 v102, 0, v98, s[18:19]
	v_cndmask_b32_e64 v99, 0, v99, s[22:23]
	v_cvt_pk_bf16_f32 v96, v104, v105
	v_cvt_pk_bf16_f32 v97, v106, v107
	v_cvt_pk_bf16_f32 v98, v100, v101
	v_cvt_pk_bf16_f32 v99, v102, v99
	ds_read2_b64 v[100:103], v199 offset1:4
	s_waitcnt lgkmcnt(0)
	v_mfma_f32_16x16x32_bf16 v[60:63], v[100:103], v[124:127], v[60:63]
	v_mfma_f32_16x16x32_bf16 v[44:47], v[100:103], v[168:171], v[44:47]
	v_mfma_f32_16x16x32_bf16 v[28:31], v[100:103], v[178:181], v[28:31]
	v_mfma_f32_16x16x32_bf16 v[12:15], v[100:103], v[72:75], v[12:15]
	ds_read2_b64 v[100:103], v199 offset0:8 offset1:12
	s_waitcnt vmcnt(7)
	v_mfma_f32_16x16x32_bf16 v[60:63], v[152:155], v[64:67], v[60:63]
	v_mfma_f32_16x16x32_bf16 v[44:47], v[152:155], v[116:119], v[44:47]
	v_mfma_f32_16x16x32_bf16 v[28:31], v[152:155], v[76:79], v[28:31]
	v_mfma_f32_16x16x32_bf16 v[12:15], v[152:155], v[84:87], v[12:15]
	s_waitcnt lgkmcnt(0)
	v_mfma_f32_16x16x32_bf16 v[60:63], v[100:103], v[140:143], v[60:63]
	v_mfma_f32_16x16x32_bf16 v[44:47], v[100:103], v[172:175], v[44:47]
	v_mfma_f32_16x16x32_bf16 v[28:31], v[100:103], v[188:191], v[28:31]
	v_mfma_f32_16x16x32_bf16 v[12:15], v[100:103], v[96:99], v[12:15]
	ds_read2_b64 v[100:103], v242 offset1:4
	s_waitcnt lgkmcnt(0)
; #define LAS __attribute__((address_space(3)))
; __device__ __forceinline__ f32x4 mfma16(bf16x8 a, bf16x8 b, f32x4 c) { return __builtin_amdgcn_mfma_f32_16x16x32_bf16(a, b, c, 0, 0, 0); }
; template <int MODE> __device__ void mixer_gla(const Params& p, int l, int n, LAS unsigned char* lds) {
;     ...
; #pragma unroll
;             for (int vf = 0; vf < 4; ++vf)
; #pragma unroll
;                 for (int ks = 0; ks < 2; ++ks) {
;                     const u32x2 v0 = *(const LAS u32x2*)(VTw + (16 * vf + c) * 72 + 32 * ks + 4 * q), v1 = *(const LAS u32x2*)(VTw + (16 * vf + c) * 72 + 32 * ks + 16 + 4 * q);
;                     const bf16x8 vtf = __builtin_bit_cast(bf16x8, (u32x4){v0.x, v0.y, v1.x, v1.y});
; #pragma unroll
;                     for (int ti = 0; ti < 4; ++ti) { acc[vf][ti] = mfma16(vtf, Pop[ti][ks], acc[vf][ti]); acc[vf][ti] = mfma16(spf[vf][ks], QEop[ti][ks], acc[vf][ti]); }
;                     if (ks == 1 && (vf & 1)) __builtin_amdgcn_sched_barrier(0);
;                 }
	v_mfma_f32_16x16x32_bf16 v[56:59], v[100:103], v[124:127], v[56:59]
	v_mfma_f32_16x16x32_bf16 v[40:43], v[100:103], v[168:171], v[40:43]
	v_mfma_f32_16x16x32_bf16 v[24:27], v[100:103], v[178:181], v[24:27]
	v_mfma_f32_16x16x32_bf16 v[8:11], v[100:103], v[72:75], v[8:11]
	ds_read2_b64 v[100:103], v242 offset0:8 offset1:12
	s_waitcnt vmcnt(5)
	v_mfma_f32_16x16x32_bf16 v[56:59], v[164:167], v[64:67], v[56:59]
	v_mfma_f32_16x16x32_bf16 v[40:43], v[164:167], v[116:119], v[40:43]
	v_mfma_f32_16x16x32_bf16 v[24:27], v[164:167], v[76:79], v[24:27]
	v_mfma_f32_16x16x32_bf16 v[8:11], v[164:167], v[84:87], v[8:11]
	s_waitcnt lgkmcnt(0)
	v_mfma_f32_16x16x32_bf16 v[56:59], v[100:103], v[140:143], v[56:59]
	v_mfma_f32_16x16x32_bf16 v[40:43], v[100:103], v[172:175], v[40:43]
	v_mfma_f32_16x16x32_bf16 v[24:27], v[100:103], v[188:191], v[24:27]
	v_mfma_f32_16x16x32_bf16 v[8:11], v[100:103], v[96:99], v[8:11]
	v_mfma_f32_16x16x32_bf16 v[60:63], v[160:163], v[68:71], v[60:63]
	v_mfma_f32_16x16x32_bf16 v[44:47], v[160:163], v[132:135], v[44:47]
	v_mfma_f32_16x16x32_bf16 v[28:31], v[160:163], v[80:83], v[28:31]
	v_mfma_f32_16x16x32_bf16 v[12:15], v[160:163], v[88:91], v[12:15]
	s_waitcnt vmcnt(4)
	v_mfma_f32_16x16x32_bf16 v[56:59], v[144:147], v[68:71], v[56:59]
	v_mfma_f32_16x16x32_bf16 v[40:43], v[144:147], v[132:135], v[40:43]
	v_mfma_f32_16x16x32_bf16 v[24:27], v[144:147], v[80:83], v[24:27]
	v_mfma_f32_16x16x32_bf16 v[8:11], v[144:147], v[88:91], v[8:11]
	ds_read2_b64 v[100:103], v243 offset1:4
	s_waitcnt lgkmcnt(0)
	v_mfma_f32_16x16x32_bf16 v[52:55], v[100:103], v[124:127], v[52:55]
	v_mfma_f32_16x16x32_bf16 v[36:39], v[100:103], v[168:171], v[36:39]
	v_mfma_f32_16x16x32_bf16 v[20:23], v[100:103], v[178:181], v[20:23]
	v_mfma_f32_16x16x32_bf16 v[4:7], v[100:103], v[72:75], v[4:7]
	ds_read2_b64 v[100:103], v243 offset0:8 offset1:12
	s_waitcnt vmcnt(3)
	v_mfma_f32_16x16x32_bf16 v[52:55], v[128:131], v[64:67], v[52:55]
	v_mfma_f32_16x16x32_bf16 v[36:39], v[128:131], v[116:119], v[36:39]
	v_mfma_f32_16x16x32_bf16 v[20:23], v[128:131], v[76:79], v[20:23]
	v_mfma_f32_16x16x32_bf16 v[4:7], v[128:131], v[84:87], v[4:7]
	s_waitcnt lgkmcnt(0)
	v_mfma_f32_16x16x32_bf16 v[52:55], v[100:103], v[140:143], v[52:55]
	v_mfma_f32_16x16x32_bf16 v[36:39], v[100:103], v[172:175], v[36:39]
	v_mfma_f32_16x16x32_bf16 v[20:23], v[100:103], v[188:191], v[20:23]
	v_mfma_f32_16x16x32_bf16 v[4:7], v[100:103], v[96:99], v[4:7]
	ds_read2_b64 v[100:103], v244 offset1:4
	s_waitcnt lgkmcnt(0)
	v_mfma_f32_16x16x32_bf16 v[48:51], v[100:103], v[124:127], v[48:51]
	s_waitcnt vmcnt(1)
	v_mfma_f32_16x16x32_bf16 v[48:51], v[108:111], v[64:67], v[48:51]
	ds_read2_b64 v[64:67], v244 offset0:8 offset1:12
	v_mfma_f32_16x16x32_bf16 v[32:35], v[100:103], v[168:171], v[32:35]
	v_mfma_f32_16x16x32_bf16 v[16:19], v[100:103], v[178:181], v[16:19]
	v_mfma_f32_16x16x32_bf16 v[0:3], v[100:103], v[72:75], v[0:3]
	v_mfma_f32_16x16x32_bf16 v[32:35], v[108:111], v[116:119], v[32:35]
	v_mfma_f32_16x16x32_bf16 v[16:19], v[108:111], v[76:79], v[16:19]
	v_mfma_f32_16x16x32_bf16 v[0:3], v[108:111], v[84:87], v[0:3]
	s_waitcnt lgkmcnt(0)
	v_mfma_f32_16x16x32_bf16 v[48:51], v[64:67], v[140:143], v[48:51]
	v_mfma_f32_16x16x32_bf16 v[32:35], v[64:67], v[172:175], v[32:35]
	v_mfma_f32_16x16x32_bf16 v[16:19], v[64:67], v[188:191], v[16:19]
	v_mfma_f32_16x16x32_bf16 v[0:3], v[64:67], v[96:99], v[0:3]
	v_mfma_f32_16x16x32_bf16 v[52:55], v[112:115], v[68:71], v[52:55]
	v_mfma_f32_16x16x32_bf16 v[36:39], v[112:115], v[132:135], v[36:39]
	v_mfma_f32_16x16x32_bf16 v[20:23], v[112:115], v[80:83], v[20:23]
	v_mfma_f32_16x16x32_bf16 v[4:7], v[112:115], v[88:91], v[4:7]
	s_waitcnt vmcnt(0)
	v_mfma_f32_16x16x32_bf16 v[48:51], v[92:95], v[68:71], v[48:51]
	v_mfma_f32_16x16x32_bf16 v[32:35], v[92:95], v[132:135], v[32:35]
	v_mfma_f32_16x16x32_bf16 v[16:19], v[92:95], v[80:83], v[16:19]
	v_mfma_f32_16x16x32_bf16 v[0:3], v[92:95], v[88:91], v[0:3]
	s_mov_b32 s4, 1
	s_mov_b64 s[26:27], 0
	s_and_b64 vcc, exec, s[30:31]
	s_cbranch_vccnz .LBB0_160

; __device__ __forceinline__ f32x4 mfma16(bf16x8 a, bf16x8 b, f32x4 c) { return __builtin_amdgcn_mfma_f32_16x16x32_bf16(a, b, c, 0, 0, 0); }
; template <int MODE> __device__ void mixer_gla(const Params& p, int l, int n, LAS unsigned char* lds) {
;     ...
;             for (int ks = 0; ks < 2; ++ks) {
;                 bf16x8 mk[2][2];
; #pragma unroll
;                 for (int t2 = 0; t2 < 2; ++t2)
; #pragma unroll
;                     for (int k2 = 0; k2 < 2; ++k2)
; #pragma unroll
;                         for (int jj = 0; jj < 8; ++jj) { const int tp = 16 * (2 * ks + t2) + c, sidx = SLOT(k2, q, jj); const bool on = dir == 0 ? sidx > tp : sidx < tp; mk[t2][k2][jj] = on ? (short)0x3F80 : (short)0; }
; #pragma unroll
;                 for (int ef = 0; ef < 4; ++ef) { f32x4 kd2[2];
; #pragma unroll
;                     for (int t2 = 0; t2 < 2; ++t2) { const int tj = 2 * ks + t2;
;                         f32x4 E = mfma16(mk[t2][0], laop[ef][0], zero4); E = mfma16(mk[t2][1], laop[ef][1], E);
;                         const f32x4 kR = mfma16(kn[tj][ef >> 1], ident[ef & 1], zero4);
; #pragma unroll
;                         for (int r = 0; r < 4; ++r) kd2[t2][r] = kR[r] * __expf(E[r]); }
;                     kdop[ef][ks] = pack8(kd2[0], kd2[1]); __builtin_amdgcn_sched_barrier(0); }
.LBB0_329:
	s_or_b64 exec, exec, s[0:1]
	v_lshrrev_b32_e32 v134, 7, v245
	v_and_b32_e32 v135, 63, v245
	v_lshlrev_b32_e32 v134, 14, v134
	v_lshl_add_u32 v134, v135, 4, v134
	v_lshl_add_u32 v134, s5, 13, v134
	global_load_dwordx4 v[124:127], v[104:105], off offset:2560
	v_cvt_pk_bf16_f32 v76, v68, v69
	v_cvt_pk_bf16_f32 v78, v72, v73
	v_cvt_pk_bf16_f32 v79, v74, v75
	v_cvt_pk_bf16_f32 v68, v80, v81
	v_cvt_pk_bf16_f32 v69, v82, v83
	v_cvt_pk_bf16_f32 v60, v34, v35
	v_cvt_pk_bf16_f32 v61, v36, v37
	v_cvt_pk_bf16_f32 v63, v44, v45
	v_cvt_pk_bf16_f32 v52, v46, v47
	v_cvt_pk_bf16_f32 v55, v64, v65
	v_cvt_pk_bf16_f32 v44, v28, v29
	v_cvt_pk_bf16_f32 v46, v24, v25
	v_cvt_pk_bf16_f32 v47, v26, v27
	v_cvt_pk_bf16_f32 v36, v20, v21
	v_cvt_pk_bf16_f32 v37, v22, v23
	v_cvt_pk_bf16_f32 v28, v12, v13
	v_cvt_pk_bf16_f32 v29, v14, v15
	global_load_dwordx4 v[80:83], v[104:105], off offset:2624
	global_load_dwordx4 v[12:15], v[106:107], off offset:2560
	global_load_dwordx4 v[20:23], v[106:107], off offset:2624
	global_load_dwordx4 v[72:75], v[108:109], off offset:2560
	global_load_dwordx4 v[32:35], v[108:109], off offset:2624
	global_load_dwordx4 v[64:67], v[110:111], off offset:2560
	global_load_dwordx4 v[24:27], v[110:111], off offset:2624
	v_cvt_pk_bf16_f32 v45, v30, v31
	v_cvt_pk_bf16_f32 v30, v8, v9
	v_cndmask_b32_e64 v8, 0, 1, s[54:55]
	v_cndmask_b32_e64 v9, 0, 1, s[44:45]
	v_cndmask_b32_e64 v8, v9, v8, s[6:7]
	v_and_b32_e32 v8, 1, v8
	v_cmp_eq_u32_e32 vcc, 1, v8
	v_cndmask_b32_e64 v8, 0, 1, s[46:47]
	v_cndmask_b32_e64 v9, 0, 1, s[48:49]
	v_cndmask_b32_e64 v8, v9, v8, s[6:7]
	v_and_b32_e32 v8, 1, v8
	v_cndmask_b32_e32 v89, 0, v229, vcc
	v_cmp_eq_u32_e32 vcc, 1, v8
	v_cvt_pk_bf16_f32 v54, v58, v59
	v_cvt_pk_bf16_f32 v58, v40, v41
	v_cndmask_b32_e32 v8, 0, v229, vcc
	v_perm_b32 v40, v8, v89, s3
	v_cndmask_b32_e64 v8, 0, 1, s[14:15]
	v_cndmask_b32_e64 v9, 0, 1, s[20:21]
	v_cvt_pk_bf16_f32 v62, v38, v39
	v_cvt_pk_bf16_f32 v38, v16, v17
	v_cndmask_b32_e64 v8, v9, v8, s[6:7]
	v_cndmask_b32_e64 v9, 0, 1, s[28:29]
	v_cndmask_b32_e64 v16, 0, 1, s[30:31]
	v_and_b32_e32 v8, 1, v8
	v_cndmask_b32_e64 v9, v16, v9, s[6:7]
	v_cmp_eq_u32_e32 vcc, 1, v8
	v_and_b32_e32 v9, 1, v9
	s_xor_b64 s[0:1], s[6:7], -1
	v_cndmask_b32_e32 v8, 0, v229, vcc
	v_cmp_eq_u32_e32 vcc, 1, v9
	s_and_b64 s[4:5], s[6:7], exec
	s_cselect_b32 s4, 0x3f80, 0
	v_cndmask_b32_e32 v9, 0, v229, vcc
	v_perm_b32 v41, v9, v8, s3
	v_cndmask_b32_e64 v8, 0, 1, s[94:95]
	v_cndmask_b32_e64 v9, 0, 1, s[96:97]
	s_pack_ll_b32_b16 s16, s4, s4
	v_cndmask_b32_e64 v8, v9, v8, s[6:7]
	v_cvt_pk_bf16_f32 v59, v42, v43
	v_mov_b32_e32 v42, s16
	v_mov_b32_e32 v43, s16
	v_and_b32_e32 v8, 1, v8
	v_cmp_eq_u32_e32 vcc, 1, v8
	s_mov_b32 s18, s16
	s_mov_b32 s19, s16
	v_cndmask_b32_e32 v8, 0, v229, vcc
	v_cvt_pk_bf16_f32 v77, v70, v71
	v_cvt_pk_bf16_f32 v70, v84, v85
	v_cvt_pk_bf16_f32 v71, v86, v87
	s_waitcnt lgkmcnt(0)
	v_cvt_pk_bf16_f32 v53, v56, v57
	v_cvt_pk_bf16_f32 v57, v50, v51
	v_perm_b32 v50, v8, v89, s3
	v_cndmask_b32_e64 v8, 0, 1, s[22:23]
	v_cndmask_b32_e64 v9, 0, 1, s[26:27]
	s_mov_b32 s17, s16
	v_mov_b64_e32 v[86:87], s[18:19]
	v_cndmask_b32_e64 v8, v9, v8, s[6:7]
	v_cndmask_b32_e64 v9, 0, 1, s[10:11]
	v_cndmask_b32_e64 v16, 0, 1, s[68:69]
	v_mov_b64_e32 v[84:85], s[16:17]
	v_cvt_pk_bf16_f32 v39, v18, v19
	v_cndmask_b32_e64 v9, v16, v9, s[6:7]
	v_mfma_f32_16x16x32_bf16 v[16:19], v[40:43], v[76:79], 0
	v_and_b32_e32 v8, 1, v8
	v_cmp_eq_u32_e32 vcc, 1, v8
	v_and_b32_e32 v9, 1, v9
	s_cselect_b32 s4, 0, 0x3f80
	v_cndmask_b32_e32 v8, 0, v229, vcc
	v_cmp_eq_u32_e32 vcc, 1, v9
	s_pack_ll_b32_b16 s4, s4, s4
	v_mfma_f32_16x16x32_bf16 v[16:19], v[84:87], v[68:71], v[16:19]
	v_cndmask_b32_e32 v9, 0, v229, vcc
	v_cvt_pk_bf16_f32 v56, v48, v49
	v_perm_b32 v51, v9, v8, s3
	v_mov_b32_e32 v48, s4
	v_mov_b32_e32 v49, s4
	s_nop 2
	v_exp_f32_e32 v8, v16
	v_exp_f32_e32 v132, v18
	s_waitcnt vmcnt(7)
	v_mfma_f32_16x16x32_bf16 v[128:131], v[124:127], v[0:3], 0
	v_exp_f32_e32 v9, v17
	v_exp_f32_e32 v133, v19
	v_mfma_f32_16x16x32_bf16 v[16:19], v[48:51], v[76:79], 0
	v_cvt_pk_bf16_f32 v31, v10, v11
	ds_write_b128 v134, v[76:79]
	ds_write_b128 v134, v[68:71] offset:1024
	ds_write_b128 v134, v[60:63] offset:2048
	ds_write_b128 v134, v[52:55] offset:3072
	ds_write_b128 v134, v[56:59] offset:4096
	ds_write_b128 v134, v[44:47] offset:5120
	ds_write_b128 v134, v[36:39] offset:6144
	ds_write_b128 v134, v[28:31] offset:7168
	s_nop 2
	v_pk_mul_f32 v[128:129], v[128:129], v[8:9]
	v_pk_mul_f32 v[130:131], v[130:131], v[132:133]
	v_mfma_f32_16x16x32_bf16 v[8:11], v[84:87], v[68:71], v[16:19]
	s_nop 7
	v_exp_f32_e32 v16, v8
	v_exp_f32_e32 v17, v9
	v_exp_f32_e32 v18, v10
	v_exp_f32_e32 v19, v11
	s_waitcnt vmcnt(5)
	v_mfma_f32_16x16x32_bf16 v[8:11], v[12:15], v[0:3], 0
	s_nop 7
	v_pk_mul_f32 v[16:17], v[8:9], v[16:17]
	v_pk_mul_f32 v[18:19], v[10:11], v[18:19]
	v_cvt_pk_bf16_f32 v8, v128, v129
	v_cvt_pk_bf16_f32 v9, v130, v131
	v_cvt_pk_bf16_f32 v10, v16, v17
	v_cvt_pk_bf16_f32 v11, v18, v19
	v_mfma_f32_16x16x32_bf16 v[16:19], v[40:43], v[60:63], 0
	v_mfma_f32_16x16x32_bf16 v[16:19], v[84:87], v[52:55], v[16:19]
	v_mfma_f32_16x16x32_bf16 v[124:127], v[124:127], v[4:7], 0
	v_mfma_f32_16x16x32_bf16 v[12:15], v[12:15], v[4:7], 0
	s_nop 5
	v_exp_f32_e32 v16, v16
	v_exp_f32_e32 v17, v17
	s_nop 0
	v_pk_mul_f32 v[124:125], v[124:125], v[16:17]
	v_exp_f32_e32 v16, v18
	v_exp_f32_e32 v17, v19
	s_nop 0
	v_pk_mul_f32 v[126:127], v[126:127], v[16:17]
	v_mfma_f32_16x16x32_bf16 v[16:19], v[48:51], v[60:63], 0
	v_mfma_f32_16x16x32_bf16 v[16:19], v[84:87], v[52:55], v[16:19]
	s_nop 7
	v_exp_f32_e32 v16, v16
	v_exp_f32_e32 v17, v17
	s_nop 0
	v_pk_mul_f32 v[16:17], v[12:13], v[16:17]
	v_exp_f32_e32 v12, v18
	v_exp_f32_e32 v13, v19
	s_nop 0
	v_pk_mul_f32 v[18:19], v[14:15], v[12:13]
	v_cvt_pk_bf16_f32 v12, v124, v125
	v_cvt_pk_bf16_f32 v13, v126, v127
	v_cvt_pk_bf16_f32 v14, v16, v17
	v_cvt_pk_bf16_f32 v15, v18, v19
	v_mfma_f32_16x16x32_bf16 v[16:19], v[40:43], v[56:59], 0
	v_mfma_f32_16x16x32_bf16 v[16:19], v[84:87], v[44:47], v[16:19]
	v_mfma_f32_16x16x32_bf16 v[124:127], v[80:83], v[0:3], 0
	s_nop 6
	v_exp_f32_e32 v128, v16
	v_exp_f32_e32 v129, v17
	v_exp_f32_e32 v130, v18
	v_exp_f32_e32 v131, v19
	v_mfma_f32_16x16x32_bf16 v[16:19], v[48:51], v[56:59], 0
	v_pk_mul_f32 v[124:125], v[124:125], v[128:129]
	v_pk_mul_f32 v[126:127], v[126:127], v[130:131]
	v_mfma_f32_16x16x32_bf16 v[16:19], v[84:87], v[44:47], v[16:19]
	s_nop 7
	v_exp_f32_e32 v128, v16
	v_exp_f32_e32 v129, v17
	v_exp_f32_e32 v130, v18
	v_exp_f32_e32 v131, v19
	s_waitcnt vmcnt(4)
; __device__ __forceinline__ f32x4 mfma16(bf16x8 a, bf16x8 b, f32x4 c) { return __builtin_amdgcn_mfma_f32_16x16x32_bf16(a, b, c, 0, 0, 0); }
; template <int MODE> __device__ void mixer_gla(const Params& p, int l, int n, LAS unsigned char* lds) {
;     ...
;             for (int ks = 0; ks < 2; ++ks) {
;                 bf16x8 mk[2][2];
; #pragma unroll
;                 for (int t2 = 0; t2 < 2; ++t2)
; #pragma unroll
;                     for (int k2 = 0; k2 < 2; ++k2)
; #pragma unroll
;                         for (int jj = 0; jj < 8; ++jj) { const int tp = 16 * (2 * ks + t2) + c, sidx = SLOT(k2, q, jj); const bool on = dir == 0 ? sidx > tp : sidx < tp; mk[t2][k2][jj] = on ? (short)0x3F80 : (short)0; }
; #pragma unroll
;                 for (int ef = 0; ef < 4; ++ef) { f32x4 kd2[2];
; #pragma unroll
;                     for (int t2 = 0; t2 < 2; ++t2) { const int tj = 2 * ks + t2;
;                         f32x4 E = mfma16(mk[t2][0], laop[ef][0], zero4); E = mfma16(mk[t2][1], laop[ef][1], E);
;                         const f32x4 kR = mfma16(kn[tj][ef >> 1], ident[ef & 1], zero4);
; #pragma unroll
;                         for (int r = 0; r < 4; ++r) kd2[t2][r] = kR[r] * __expf(E[r]); }
;                     kdop[ef][ks] = pack8(kd2[0], kd2[1]); __builtin_amdgcn_sched_barrier(0); }
	v_mfma_f32_16x16x32_bf16 v[16:19], v[20:23], v[0:3], 0
	s_nop 7
	v_pk_mul_f32 v[128:129], v[16:17], v[128:129]
	v_pk_mul_f32 v[130:131], v[18:19], v[130:131]
	v_cvt_pk_bf16_f32 v16, v124, v125
	v_cvt_pk_bf16_f32 v17, v126, v127
	v_cvt_pk_bf16_f32 v18, v128, v129
	v_cvt_pk_bf16_f32 v19, v130, v131
	v_mfma_f32_16x16x32_bf16 v[124:127], v[40:43], v[36:39], 0
	v_mfma_f32_16x16x32_bf16 v[124:127], v[84:87], v[28:31], v[124:127]
	v_mfma_f32_16x16x32_bf16 v[80:83], v[80:83], v[4:7], 0
	v_mfma_f32_16x16x32_bf16 v[20:23], v[20:23], v[4:7], 0
	s_nop 5
	v_exp_f32_e32 v40, v124
	v_exp_f32_e32 v41, v125
	s_nop 0
	v_pk_mul_f32 v[40:41], v[80:81], v[40:41]
	v_exp_f32_e32 v80, v126
	v_exp_f32_e32 v81, v127
	s_nop 0
	v_pk_mul_f32 v[124:125], v[82:83], v[80:81]
	v_mfma_f32_16x16x32_bf16 v[80:83], v[48:51], v[36:39], 0
	v_mfma_f32_16x16x32_bf16 v[80:83], v[84:87], v[28:31], v[80:83]
	s_nop 7
	v_exp_f32_e32 v50, v80
	v_exp_f32_e32 v51, v81
	s_nop 0
	v_pk_mul_f32 v[50:51], v[20:21], v[50:51]
	v_exp_f32_e32 v20, v82
	v_exp_f32_e32 v21, v83
	s_nop 0
	v_pk_mul_f32 v[80:81], v[22:23], v[20:21]
	v_cvt_pk_bf16_f32 v20, v40, v41
	v_cvt_pk_bf16_f32 v21, v124, v125
	v_cvt_pk_bf16_f32 v22, v50, v51
	v_cvt_pk_bf16_f32 v23, v80, v81
	v_cndmask_b32_e64 v40, 0, 1, s[70:71]
	v_cndmask_b32_e64 v41, 0, 1, s[72:73]
	v_cndmask_b32_e64 v40, v41, v40, s[6:7]
	v_cndmask_b32_e64 v41, 0, 1, s[74:75]
	v_cndmask_b32_e64 v43, 0, 1, s[76:77]
	v_and_b32_e32 v40, 1, v40
	v_cndmask_b32_e64 v41, v43, v41, s[6:7]
	v_cndmask_b32_e64 v43, 0, 1, s[78:79]
	v_cndmask_b32_e64 v49, 0, 1, s[80:81]
	v_cmp_eq_u32_e32 vcc, 1, v40
	v_and_b32_e32 v41, 1, v41
	v_cndmask_b32_e64 v43, v49, v43, s[6:7]
	v_cndmask_b32_e64 v49, 0, 1, s[82:83]
	v_cndmask_b32_e64 v50, 0, 1, s[84:85]
	v_cndmask_b32_e32 v40, 0, v229, vcc
	v_cmp_eq_u32_e32 vcc, 1, v41
	v_and_b32_e32 v43, 1, v43
	v_cndmask_b32_e64 v49, v50, v49, s[6:7]
	v_cndmask_b32_e32 v41, 0, v229, vcc
	v_cmp_eq_u32_e32 vcc, 1, v43
	v_and_b32_e32 v49, 1, v49
	v_cndmask_b32_e64 v51, 0, 1, s[88:89]
	v_cndmask_b32_e32 v43, 0, v229, vcc
	v_cmp_eq_u32_e32 vcc, 1, v49
	v_cndmask_b32_e64 v80, 0, 1, s[92:93]
	s_mov_b32 s5, s4
	v_cndmask_b32_e32 v49, 0, v229, vcc
	v_perm_b32 v50, v49, v89, s3
	v_cndmask_b32_e64 v49, 0, 1, s[86:87]
	v_cndmask_b32_e64 v49, v51, v49, s[6:7]
	v_cndmask_b32_e64 v51, 0, 1, s[90:91]
	v_cndmask_b32_e64 v51, v80, v51, s[6:7]
	s_mov_b32 s6, s4
	s_mov_b32 s7, s4
	v_mov_b64_e32 v[82:83], s[6:7]
	v_and_b32_e32 v49, 1, v49
	v_mov_b64_e32 v[80:81], s[4:5]
	v_cmp_eq_u32_e32 vcc, 1, v49
	v_and_b32_e32 v51, 1, v51
	v_perm_b32 v40, v40, v89, s3
	v_cndmask_b32_e32 v49, 0, v229, vcc
	v_cmp_eq_u32_e32 vcc, 1, v51
	v_perm_b32 v41, v43, v41, s3
	v_mov_b32_e32 v43, s16
	v_cndmask_b32_e32 v51, 0, v229, vcc
	v_perm_b32 v51, v51, v49, s3
	v_mov_b32_e32 v49, s4
	v_mfma_f32_16x16x32_bf16 v[76:79], v[80:83], v[76:79], 0
	v_mfma_f32_16x16x32_bf16 v[84:87], v[40:43], v[68:71], v[76:79]
	v_mfma_f32_16x16x32_bf16 v[68:71], v[48:51], v[68:71], v[76:79]
	s_waitcnt vmcnt(1)
	v_mfma_f32_16x16x32_bf16 v[76:79], v[64:67], v[0:3], 0
	s_nop 4
	s_nop 0
	v_exp_f32_e32 v68, v68
	v_exp_f32_e32 v69, v69
	s_nop 0
	v_pk_mul_f32 v[76:77], v[76:77], v[68:69]
	v_mfma_f32_16x16x32_bf16 v[124:127], v[72:75], v[0:3], 0
	v_exp_f32_e32 v84, v84
	v_exp_f32_e32 v85, v85
	v_exp_f32_e32 v86, v86
	v_exp_f32_e32 v87, v87
	v_exp_f32_e32 v68, v70
	v_exp_f32_e32 v69, v71
	s_nop 1
	v_pk_mul_f32 v[84:85], v[124:125], v[84:85]
	v_pk_mul_f32 v[86:87], v[126:127], v[86:87]
	v_cvt_pk_bf16_f32 v70, v76, v77
	v_pk_mul_f32 v[78:79], v[78:79], v[68:69]
	v_cvt_pk_bf16_f32 v68, v84, v85
	v_cvt_pk_bf16_f32 v69, v86, v87
	v_cvt_pk_bf16_f32 v71, v78, v79
	v_mfma_f32_16x16x32_bf16 v[60:63], v[80:83], v[60:63], 0
	v_mfma_f32_16x16x32_bf16 v[76:79], v[40:43], v[52:55], v[60:63]
	v_mfma_f32_16x16x32_bf16 v[52:55], v[48:51], v[52:55], v[60:63]
	v_mfma_f32_16x16x32_bf16 v[72:75], v[72:75], v[4:7], 0
	s_nop 5
	s_nop 0
	v_exp_f32_e32 v60, v52
	v_exp_f32_e32 v61, v53
	v_exp_f32_e32 v62, v54
	v_exp_f32_e32 v76, v76
	v_exp_f32_e32 v77, v77
	v_exp_f32_e32 v78, v78
	v_exp_f32_e32 v79, v79
	v_exp_f32_e32 v63, v55
	v_mfma_f32_16x16x32_bf16 v[52:55], v[64:67], v[4:7], 0
	v_mul_f32_e64 v72, v72, v76
	v_mul_f32_e64 v73, v73, v77
	v_pk_mul_f32 v[74:75], v[74:75], v[78:79]
	s_nop 4
	v_pk_mul_f32 v[60:61], v[52:53], v[60:61]
	v_pk_mul_f32 v[62:63], v[54:55], v[62:63]
	v_cvt_pk_bf16_f32 v52, v72, v73
	v_cvt_pk_bf16_f32 v53, v74, v75
	v_cvt_pk_bf16_f32 v54, v60, v61
	v_cvt_pk_bf16_f32 v55, v62, v63
	v_mfma_f32_16x16x32_bf16 v[56:59], v[80:83], v[56:59], 0
	v_mfma_f32_16x16x32_bf16 v[60:63], v[40:43], v[44:47], v[56:59]
	v_mfma_f32_16x16x32_bf16 v[44:47], v[48:51], v[44:47], v[56:59]
	s_nop 6
	s_nop 0
	v_exp_f32_e32 v56, v44
	v_exp_f32_e32 v57, v45
	v_exp_f32_e32 v67, v63
	v_exp_f32_e32 v58, v46
	v_exp_f32_e32 v64, v60
	v_exp_f32_e32 v65, v61
	v_exp_f32_e32 v66, v62
	v_mfma_f32_16x16x32_bf16 v[60:63], v[32:35], v[0:3], 0
	v_exp_f32_e32 v59, v47
	s_waitcnt vmcnt(0)
; #define LAS __attribute__((address_space(3)))
; __device__ __forceinline__ unsigned cvtpk(float lo, float hi) { const f32x2 v = (f32x2){lo, hi}; const bf16v2 b = __builtin_convertvector(v, bf16v2); return __builtin_bit_cast(unsigned, b); }
; __device__ __forceinline__ f32x4 mfma16(bf16x8 a, bf16x8 b, f32x4 c) { return __builtin_amdgcn_mfma_f32_16x16x32_bf16(a, b, c, 0, 0, 0); }
; template <int MODE> __device__ void mixer_gla(const Params& p, int l, int n, LAS unsigned char* lds) {
;     ...
;                 for (int ef = 0; ef < 4; ++ef) { f32x4 kd2[2];
; #pragma unroll
;                     for (int t2 = 0; t2 < 2; ++t2) { const int tj = 2 * ks + t2;
;                         f32x4 E = mfma16(mk[t2][0], laop[ef][0], zero4); E = mfma16(mk[t2][1], laop[ef][1], E);
;                         const f32x4 kR = mfma16(kn[tj][ef >> 1], ident[ef & 1], zero4);
; #pragma unroll
;                         for (int r = 0; r < 4; ++r) kd2[t2][r] = kR[r] * __expf(E[r]); }
;                     kdop[ef][ks] = pack8(kd2[0], kd2[1]); __builtin_amdgcn_sched_barrier(0); }
;             }
;             bf16_t* U = uT + ((size_t)(dir * NCH + n) * 4 + h) * 8192 + (size_t)(64 * vh) * 64;
; #pragma unroll
;             for (int vf = 0; vf < 4; ++vf) { bf16x8 vtf[2];
; #pragma unroll
;                 for (int ks = 0; ks < 2; ++ks) { const u32x2 v0 = *(const LAS u32x2*)(VTw + (16 * vf + c) * 72 + 32 * ks + 4 * q), v1 = *(const LAS u32x2*)(VTw + (16 * vf + c) * 72 + 32 * ks + 16 + 4 * q);
;                     vtf[ks] = __builtin_bit_cast(bf16x8, (u32x4){v0.x, v0.y, v1.x, v1.y}); }
; #pragma unroll
;                 for (int ef = 0; ef < 4; ++ef) { f32x4 u = mfma16(kdop[ef][0], vtf[0], zero4); u = mfma16(kdop[ef][1], vtf[1], u);
;                     *(u32x2*)(U + (16 * vf + c) * 64 + 32 * (ef >> 1) + 8 * q + 4 * (ef & 1)) = (u32x2){cvtpk(u[0], u[1]), cvtpk(u[2], u[3])}; } }
	v_mfma_f32_16x16x32_bf16 v[44:47], v[24:27], v[0:3], 0
	s_nop 3
	s_nop 0
	v_mul_f32_e64 v60, v60, v64
	v_mul_f32_e64 v61, v61, v65
	v_pk_mul_f32 v[62:63], v[62:63], v[66:67]
	s_nop 0
	v_pk_mul_f32 v[56:57], v[44:45], v[56:57]
	v_pk_mul_f32 v[58:59], v[46:47], v[58:59]
	v_cvt_pk_bf16_f32 v44, v60, v61
	v_cvt_pk_bf16_f32 v45, v62, v63
	v_cvt_pk_bf16_f32 v46, v56, v57
	v_cvt_pk_bf16_f32 v47, v58, v59
	v_mfma_f32_16x16x32_bf16 v[36:39], v[80:83], v[36:39], 0
	v_mfma_f32_16x16x32_bf16 v[40:43], v[40:43], v[28:31], v[36:39]
	v_mfma_f32_16x16x32_bf16 v[28:31], v[48:51], v[28:31], v[36:39]
	v_mfma_f32_16x16x32_bf16 v[32:35], v[32:35], v[4:7], 0
	s_nop 5
	v_exp_f32_e32 v40, v40
	v_exp_f32_e32 v41, v41
	v_exp_f32_e32 v42, v42
	v_exp_f32_e32 v43, v43
	v_exp_f32_e32 v28, v28
	v_exp_f32_e32 v29, v29
	v_exp_f32_e32 v30, v30
	v_exp_f32_e32 v31, v31
	v_mfma_f32_16x16x32_bf16 v[24:27], v[24:27], v[4:7], 0
	v_mul_f32_e64 v32, v32, v40
	v_mul_f32_e64 v33, v33, v41
	v_pk_mul_f32 v[34:35], v[34:35], v[42:43]
	s_nop 4
	v_pk_mul_f32 v[28:29], v[24:25], v[28:29]
	v_pk_mul_f32 v[30:31], v[26:27], v[30:31]
	v_cvt_pk_bf16_f32 v24, v32, v33
	v_cvt_pk_bf16_f32 v25, v34, v35
	v_cvt_pk_bf16_f32 v26, v28, v29
	v_cvt_pk_bf16_f32 v27, v30, v31
	ds_read2_b64 v[28:31], v120 offset1:4
	ds_read2_b64 v[32:35], v120 offset0:8 offset1:12
	s_lshl_b64 s[4:5], s[8:9], 16
	v_lshl_add_u64 v[48:49], v[112:113], 0, s[4:5]
	s_movk_i32 s4, 0x1000
	s_waitcnt lgkmcnt(1)
	v_mfma_f32_16x16x32_bf16 v[36:39], v[8:11], v[28:31], 0
	s_mov_b32 s5, 1
	s_mov_b64 s[6:7], 0
	s_waitcnt lgkmcnt(0)
	v_mfma_f32_16x16x32_bf16 v[36:39], v[68:71], v[32:35], v[36:39]
	s_nop 7
	v_cvt_pk_bf16_f32 v36, v36, v37
	v_cvt_pk_bf16_f32 v37, v38, v39
	v_mfma_f32_16x16x32_bf16 v[38:41], v[12:15], v[28:31], 0
	v_mfma_f32_16x16x32_bf16 v[38:41], v[52:55], v[32:35], v[38:41]
	s_nop 7
	v_cvt_pk_bf16_f32 v38, v38, v39
	v_cvt_pk_bf16_f32 v39, v40, v41
	global_store_dwordx4 v[48:49], v[36:39], off
	s_nop 1
	v_mfma_f32_16x16x32_bf16 v[36:39], v[16:19], v[28:31], 0
	v_mfma_f32_16x16x32_bf16 v[28:31], v[20:23], v[28:31], 0
	v_mfma_f32_16x16x32_bf16 v[36:39], v[44:47], v[32:35], v[36:39]
	v_mfma_f32_16x16x32_bf16 v[28:31], v[24:27], v[32:35], v[28:31]
	s_nop 6
	v_cvt_pk_bf16_f32 v36, v36, v37
	v_cvt_pk_bf16_f32 v37, v38, v39
	v_cvt_pk_bf16_f32 v38, v28, v29
	v_cvt_pk_bf16_f32 v39, v30, v31
	global_store_dwordx4 v[48:49], v[36:39], off offset:64
	ds_read2_b64 v[28:31], v121 offset1:4
	ds_read2_b64 v[32:35], v121 offset0:8 offset1:12
	s_waitcnt lgkmcnt(1)
	v_mfma_f32_16x16x32_bf16 v[36:39], v[8:11], v[28:31], 0
	s_waitcnt lgkmcnt(0)
	v_mfma_f32_16x16x32_bf16 v[36:39], v[68:71], v[32:35], v[36:39]
	s_nop 7
	v_cvt_pk_bf16_f32 v36, v36, v37
	v_cvt_pk_bf16_f32 v37, v38, v39
	v_mfma_f32_16x16x32_bf16 v[38:41], v[12:15], v[28:31], 0
	v_mfma_f32_16x16x32_bf16 v[38:41], v[52:55], v[32:35], v[38:41]
	s_nop 7
	v_cvt_pk_bf16_f32 v38, v38, v39
	v_cvt_pk_bf16_f32 v39, v40, v41
	global_store_dwordx4 v[48:49], v[36:39], off offset:2048
	s_nop 1
	v_mfma_f32_16x16x32_bf16 v[36:39], v[16:19], v[28:31], 0
	v_mfma_f32_16x16x32_bf16 v[28:31], v[20:23], v[28:31], 0
	v_mfma_f32_16x16x32_bf16 v[36:39], v[44:47], v[32:35], v[36:39]
	v_mfma_f32_16x16x32_bf16 v[28:31], v[24:27], v[32:35], v[28:31]
	s_nop 6
	v_cvt_pk_bf16_f32 v36, v36, v37
	v_cvt_pk_bf16_f32 v37, v38, v39
	v_cvt_pk_bf16_f32 v38, v28, v29
	v_cvt_pk_bf16_f32 v39, v30, v31
	global_store_dwordx4 v[48:49], v[36:39], off offset:2112
	ds_read2_b64 v[30:33], v122 offset1:4
	ds_read2_b64 v[34:37], v122 offset0:8 offset1:12
	s_waitcnt lgkmcnt(1)
	v_mfma_f32_16x16x32_bf16 v[38:41], v[8:11], v[30:33], 0
	v_add_co_u32_e32 v28, vcc, s4, v48
	s_waitcnt lgkmcnt(0)
	v_mfma_f32_16x16x32_bf16 v[38:41], v[68:71], v[34:37], v[38:41]
	v_addc_co_u32_e32 v29, vcc, 0, v49, vcc
	s_andn2_b64 vcc, exec, s[0:1]
	s_nop 5
	v_cvt_pk_bf16_f32 v38, v38, v39
	v_cvt_pk_bf16_f32 v39, v40, v41
	v_mfma_f32_16x16x32_bf16 v[40:43], v[12:15], v[30:33], 0
	v_mfma_f32_16x16x32_bf16 v[40:43], v[52:55], v[34:37], v[40:43]
	s_nop 7
	v_cvt_pk_bf16_f32 v40, v40, v41
	v_cvt_pk_bf16_f32 v41, v42, v43
	global_store_dwordx4 v[28:29], v[38:41], off
	s_nop 1
	v_mfma_f32_16x16x32_bf16 v[38:41], v[16:19], v[30:33], 0
	v_mfma_f32_16x16x32_bf16 v[30:33], v[20:23], v[30:33], 0
	v_mfma_f32_16x16x32_bf16 v[38:41], v[44:47], v[34:37], v[38:41]
	v_mfma_f32_16x16x32_bf16 v[30:33], v[24:27], v[34:37], v[30:33]
	v_add_u32_e32 v34, 0x1800, v120
	s_nop 5
	v_cvt_pk_bf16_f32 v38, v38, v39
	v_cvt_pk_bf16_f32 v39, v40, v41
	v_cvt_pk_bf16_f32 v40, v30, v31
	v_cvt_pk_bf16_f32 v41, v32, v33
	global_store_dwordx4 v[28:29], v[38:41], off offset:64
	ds_read2_b64 v[30:33], v34 offset0:96 offset1:100
	ds_read2_b64 v[34:37], v34 offset0:104 offset1:108
	s_waitcnt lgkmcnt(1)
	v_mfma_f32_16x16x32_bf16 v[8:11], v[8:11], v[30:33], 0
	s_waitcnt lgkmcnt(0)
	v_mfma_f32_16x16x32_bf16 v[8:11], v[68:71], v[34:37], v[8:11]
	s_nop 7
	v_cvt_pk_bf16_f32 v8, v8, v9
	v_cvt_pk_bf16_f32 v9, v10, v11
	v_mfma_f32_16x16x32_bf16 v[10:13], v[12:15], v[30:33], 0
	v_mfma_f32_16x16x32_bf16 v[10:13], v[52:55], v[34:37], v[10:13]
	s_nop 7
	v_cvt_pk_bf16_f32 v10, v10, v11
	v_cvt_pk_bf16_f32 v11, v12, v13
	global_store_dwordx4 v[28:29], v[8:11], off offset:2048
	s_nop 1
	v_mfma_f32_16x16x32_bf16 v[8:11], v[16:19], v[30:33], 0
	v_mfma_f32_16x16x32_bf16 v[8:11], v[44:47], v[34:37], v[8:11]
	s_nop 7
	v_cvt_pk_bf16_f32 v8, v8, v9
	v_cvt_pk_bf16_f32 v9, v10, v11
	v_mfma_f32_16x16x32_bf16 v[10:13], v[20:23], v[30:33], 0
	v_mfma_f32_16x16x32_bf16 v[10:13], v[24:27], v[34:37], v[10:13]
	s_nop 7
	v_cvt_pk_bf16_f32 v10, v10, v11
	v_cvt_pk_bf16_f32 v11, v12, v13
	global_store_dwordx4 v[28:29], v[8:11], off offset:2112
	s_cbranch_vccz .LBB0_327

; __device__ __forceinline__ f32x4 mfma16(bf16x8 a, bf16x8 b, f32x4 c) { return __builtin_amdgcn_mfma_f32_16x16x32_bf16(a, b, c, 0, 0, 0); }
; template <int MODE> __device__ void mixer_gla(const Params& p, int l, int n, LAS unsigned char* lds) {
;     ...
; #pragma unroll
;             for (int tt = 0; tt < 4; ++tt) { lrf[tt] = (bf16x8){0, 0, 0, 0, 0, 0, 0, 0}; if (q < 2) lrf[tt] = *(const bf16x8*)(proj + (size_t)(t0 + 16 * tt + c) * DINP + 2560 + dir * 16 + 8 * q); }
; #pragma unroll
;             for (int ef = 0; ef < 4; ++ef) { gwf[ef] = *(const bf16x8*)(GW + (size_t)(dir * 256 + 64 * h + SIGC(ef, c)) * 32 + 8 * q); bgv[ef] = p.in[13][(size_t)(l * 2 + dir) * 256 + 64 * h + SIGC(ef, c)]; }
; #pragma unroll
;             for (int ef = 0; ef < 4; ++ef) { tot[ef] = 0.f;
; #pragma unroll
;                 for (int ks = 0; ks < 2; ++ks) { f32x4 la2[2];
; #pragma unroll
;                     for (int t2 = 0; t2 < 2; ++t2) { const f32x4 z = mfma16(lrf[2 * ks + t2], gwf[ef], zero4);
; #pragma unroll
;                         for (int r = 0; r < 4; ++r) { const float zz = z[r] + bgv[ef]; const float la = (fminf(zz, 0.f) - __logf(1.0f + __expf(-fabsf(zz)))) * (1.0f / 16.0f); la2[t2][r] = la; tot[ef] += la; } }
;                     laop[ef][ks] = pack8(la2[0], la2[1]); __builtin_amdgcn_sched_barrier(0); } }
.LBB0_338:
	s_or_b64 exec, exec, s[0:1]
	s_lshl_b32 s4, s5, 8
	v_add_u32_e32 v30, s4, v88
	v_or_b32_e32 v16, v30, v90
	v_ashrrev_i32_e32 v17, 31, v16
	v_lshlrev_b64 v[16:17], 6, v[16:17]
	v_lshl_add_u64 v[16:17], v[92:93], 0, v[16:17]
	s_or_b32 s0, s5, s13
	global_load_dwordx4 v[24:27], v[16:17], off
	s_ashr_i32 s1, s0, 31
	s_lshl_b64 s[0:1], s[0:1], 10
	v_lshl_add_u64 v[28:29], v[114:115], 0, s[0:1]
	global_load_dword v40, v[28:29], off
	v_or_b32_e32 v16, v30, v117
	v_or_b32_e32 v20, v30, v118
	v_or_b32_e32 v30, v30, v119
	v_ashrrev_i32_e32 v17, 31, v16
	v_ashrrev_i32_e32 v21, 31, v20
	v_ashrrev_i32_e32 v31, 31, v30
	v_lshlrev_b64 v[16:17], 6, v[16:17]
	v_lshlrev_b64 v[20:21], 6, v[20:21]
	v_lshlrev_b64 v[30:31], 6, v[30:31]
	v_lshl_add_u64 v[16:17], v[92:93], 0, v[16:17]
	v_lshl_add_u64 v[20:21], v[92:93], 0, v[20:21]
	v_lshl_add_u64 v[30:31], v[92:93], 0, v[30:31]
	global_load_dwordx4 v[16:19], v[16:17], off
	s_nop 0
	global_load_dword v78, v[28:29], off offset:16
	s_nop 0
	global_load_dwordx4 v[20:23], v[20:21], off
	s_nop 0
	global_load_dword v77, v[28:29], off offset:128
	global_load_dwordx4 v[44:47], v[30:31], off
	global_load_dword v76, v[28:29], off offset:144
	s_waitcnt vmcnt(7)
	v_mfma_f32_16x16x32_bf16 v[28:31], v[12:15], v[24:27], 0
	s_waitcnt vmcnt(6)
	s_nop 6
	v_add_f32_e32 v41, v40, v28
	v_add_f32_e32 v43, v40, v29
	v_min_f32_e32 v28, 0, v41
	v_min_f32_e32 v29, 0, v43
	v_mul_f32_e64 v41, |v41|, s33
	v_mul_f32_e64 v43, |v43|, s33
	v_exp_f32_e32 v41, v41
	v_exp_f32_e32 v43, v43
	v_mul_f32_e32 v28, 0x3db8aa3b, v28
	v_mul_f32_e32 v29, 0x3db8aa3b, v29
	v_add_f32_e32 v41, 1.0, v41
	v_add_f32_e32 v43, 1.0, v43
	v_log_f32_e32 v41, v41
	v_log_f32_e32 v43, v43
	v_fmamk_f32 v68, v41, 0xbd800000, v28
	v_fmamk_f32 v69, v43, 0xbd800000, v29
	v_add_f32_e32 v31, v40, v31
	v_add_f32_e32 v29, v40, v30
	v_add_f32_e32 v28, 0, v68
	v_add_f32_e32 v41, v69, v28
	v_min_f32_e32 v28, 0, v29
	v_min_f32_e32 v30, 0, v31
	v_mul_f32_e64 v29, |v29|, s33
	v_mul_f32_e64 v31, |v31|, s33
	v_exp_f32_e32 v29, v29
	v_exp_f32_e32 v31, v31
	v_mul_f32_e32 v28, 0x3db8aa3b, v28
	v_mul_f32_e32 v30, 0x3db8aa3b, v30
	v_add_f32_e32 v29, 1.0, v29
	v_add_f32_e32 v31, 1.0, v31
	v_log_f32_e32 v29, v29
	v_log_f32_e32 v31, v31
	v_fmamk_f32 v70, v29, 0xbd800000, v28
	v_fmamk_f32 v71, v31, 0xbd800000, v30
	s_nop 0
	v_add_f32_e32 v28, v70, v41
	v_add_f32_e32 v41, v71, v28
	v_mfma_f32_16x16x32_bf16 v[28:31], v[8:11], v[24:27], 0
	s_nop 7
	v_add_f32_e32 v42, v40, v28
	v_add_f32_e32 v48, v40, v29
	v_min_f32_e32 v28, 0, v42
	v_min_f32_e32 v29, 0, v48
	v_mul_f32_e64 v42, |v42|, s33
	v_mul_f32_e64 v48, |v48|, s33
	v_exp_f32_e32 v42, v42
	v_exp_f32_e32 v48, v48
	v_mul_f32_e32 v28, 0x3db8aa3b, v28
	v_mul_f32_e32 v29, 0x3db8aa3b, v29
	v_add_f32_e32 v42, 1.0, v42
	v_add_f32_e32 v48, 1.0, v48
	v_log_f32_e32 v42, v42
	v_log_f32_e32 v48, v48
	v_fmamk_f32 v72, v42, 0xbd800000, v28
	v_fmamk_f32 v73, v48, 0xbd800000, v29
	v_add_f32_e32 v31, v40, v31
	v_add_f32_e32 v29, v40, v30
	v_add_f32_e32 v28, v72, v41
	v_add_f32_e32 v41, v73, v28
	v_min_f32_e32 v28, 0, v29
	v_min_f32_e32 v30, 0, v31
	v_mul_f32_e64 v29, |v29|, s33
	v_mul_f32_e64 v31, |v31|, s33
	v_exp_f32_e32 v29, v29
	v_exp_f32_e32 v31, v31
	v_mul_f32_e32 v28, 0x3db8aa3b, v28
	v_mul_f32_e32 v30, 0x3db8aa3b, v30
	v_add_f32_e32 v29, 1.0, v29
	v_add_f32_e32 v31, 1.0, v31
	v_log_f32_e32 v29, v29
	v_log_f32_e32 v31, v31
	v_fmamk_f32 v74, v29, 0xbd800000, v28
	v_fmamk_f32 v75, v31, 0xbd800000, v30
	s_nop 0
	v_add_f32_e32 v28, v74, v41
	v_add_f32_e32 v41, v75, v28
	v_mfma_f32_16x16x32_bf16 v[28:31], v[36:39], v[24:27], 0
	v_mfma_f32_16x16x32_bf16 v[24:27], v[32:35], v[24:27], 0
	s_nop 6
	v_add_f32_e32 v42, v40, v28
	v_add_f32_e32 v48, v40, v29
	v_min_f32_e32 v28, 0, v42
	v_min_f32_e32 v29, 0, v48
	v_mul_f32_e64 v42, |v42|, s33
	v_mul_f32_e64 v48, |v48|, s33
	v_exp_f32_e32 v42, v42
	v_exp_f32_e32 v48, v48
	v_mul_f32_e32 v28, 0x3db8aa3b, v28
	v_mul_f32_e32 v29, 0x3db8aa3b, v29
	v_add_f32_e32 v42, 1.0, v42
	v_add_f32_e32 v48, 1.0, v48
	v_log_f32_e32 v42, v42
	v_log_f32_e32 v48, v48
	v_fmamk_f32 v80, v42, 0xbd800000, v28
	v_fmamk_f32 v81, v48, 0xbd800000, v29
	v_add_f32_e32 v31, v40, v31
	v_add_f32_e32 v27, v40, v27
	v_add_f32_e32 v29, v40, v30
	v_add_f32_e32 v28, v80, v41
	v_add_f32_e32 v41, v81, v28
	v_min_f32_e32 v28, 0, v29
	v_min_f32_e32 v30, 0, v31
	v_mul_f32_e64 v29, |v29|, s33
	v_mul_f32_e64 v31, |v31|, s33
	v_exp_f32_e32 v29, v29
	v_exp_f32_e32 v31, v31
	v_mul_f32_e32 v28, 0x3db8aa3b, v28
	v_mul_f32_e32 v30, 0x3db8aa3b, v30
	v_add_f32_e32 v29, 1.0, v29
	v_add_f32_e32 v31, 1.0, v31
	v_log_f32_e32 v29, v29
	v_log_f32_e32 v31, v31
	v_fmamk_f32 v82, v29, 0xbd800000, v28
	v_fmamk_f32 v83, v31, 0xbd800000, v30
	s_nop 0
	v_add_f32_e32 v28, v82, v41
	v_add_f32_e32 v30, v83, v28
	v_add_f32_e32 v28, v40, v24
	v_add_f32_e32 v31, v40, v25
	v_min_f32_e32 v24, 0, v28
	v_min_f32_e32 v25, 0, v31
	v_mul_f32_e64 v28, |v28|, s33
	v_mul_f32_e64 v31, |v31|, s33
	v_exp_f32_e32 v28, v28
	v_exp_f32_e32 v31, v31
	v_mul_f32_e32 v24, 0x3db8aa3b, v24
	v_mul_f32_e32 v25, 0x3db8aa3b, v25
	v_add_f32_e32 v28, 1.0, v28
	v_add_f32_e32 v31, 1.0, v31
	v_log_f32_e32 v28, v28
	v_log_f32_e32 v31, v31
	v_fmamk_f32 v84, v28, 0xbd800000, v24
	v_fmamk_f32 v85, v31, 0xbd800000, v25
	v_add_f32_e32 v25, v40, v26
	v_add_f32_e32 v24, v84, v30
	v_add_f32_e32 v28, v85, v24
	v_min_f32_e32 v24, 0, v25
	v_min_f32_e32 v26, 0, v27
	v_mul_f32_e64 v25, |v25|, s33
	v_mul_f32_e64 v27, |v27|, s33
	v_exp_f32_e32 v25, v25
	v_exp_f32_e32 v27, v27
	v_mul_f32_e32 v24, 0x3db8aa3b, v24
	v_mul_f32_e32 v26, 0x3db8aa3b, v26
	v_add_f32_e32 v25, 1.0, v25
	v_add_f32_e32 v27, 1.0, v27
	v_log_f32_e32 v25, v25
	v_log_f32_e32 v27, v27
	v_fmamk_f32 v86, v25, 0xbd800000, v24
	v_fmamk_f32 v87, v27, 0xbd800000, v26
	s_nop 0
	v_add_f32_e32 v24, v86, v28
	v_add_f32_e32 v79, v87, v24
	s_waitcnt vmcnt(5)
	v_mfma_f32_16x16x32_bf16 v[64:67], v[12:15], v[16:19], 0
	v_mfma_f32_16x16x32_bf16 v[60:63], v[8:11], v[16:19], 0
	v_mfma_f32_16x16x32_bf16 v[56:59], v[36:39], v[16:19], 0
	v_mfma_f32_16x16x32_bf16 v[52:55], v[32:35], v[16:19], 0
	s_waitcnt vmcnt(3)
	v_mfma_f32_16x16x32_bf16 v[48:51], v[12:15], v[20:23], 0
	v_mfma_f32_16x16x32_bf16 v[40:43], v[8:11], v[20:23], 0
	v_mfma_f32_16x16x32_bf16 v[28:31], v[36:39], v[20:23], 0
	v_mfma_f32_16x16x32_bf16 v[24:27], v[32:35], v[20:23], 0
	s_waitcnt vmcnt(1)
	v_mfma_f32_16x16x32_bf16 v[20:23], v[12:15], v[44:47], 0
	v_mfma_f32_16x16x32_bf16 v[16:19], v[8:11], v[44:47], 0
	v_mfma_f32_16x16x32_bf16 v[12:15], v[36:39], v[44:47], 0
	v_mfma_f32_16x16x32_bf16 v[8:11], v[32:35], v[44:47], 0
	ds_bpermute_b32 v32, v91, v79
	s_add_i32 s8, s4, s12
	s_ashr_i32 s9, s8, 31
	s_lshl_b64 s[0:1], s[8:9], 10
	v_lshlrev_b32_e32 v176, 2, v90
	s_waitcnt lgkmcnt(0)
	v_add_f32_e32 v34, v79, v32
	ds_bpermute_b32 v35, v116, v34
	v_lshl_add_u64 v[32:33], v[94:95], 0, s[0:1]
	s_and_saveexec_b64 s[0:1], s[40:41]
	s_cbranch_execz .LBB0_340
; __device__ __forceinline__ f32x4 mfma16(bf16x8 a, bf16x8 b, f32x4 c) { return __builtin_amdgcn_mfma_f32_16x16x32_bf16(a, b, c, 0, 0, 0); }
; template <int MODE> __device__ void mixer_gla(const Params& p, int l, int n, LAS unsigned char* lds) {
;     ...
;             for (int ef = 0; ef < 4; ++ef) { tot[ef] = 0.f;
; #pragma unroll
;                 for (int ks = 0; ks < 2; ++ks) { f32x4 la2[2];
; #pragma unroll
;                     for (int t2 = 0; t2 < 2; ++t2) { const f32x4 z = mfma16(lrf[2 * ks + t2], gwf[ef], zero4);
; #pragma unroll
;                         for (int r = 0; r < 4; ++r) { const float zz = z[r] + bgv[ef]; const float la = (fminf(zz, 0.f) - __logf(1.0f + __expf(-fabsf(zz)))) * (1.0f / 16.0f); la2[t2][r] = la; tot[ef] += la; } }
;                     laop[ef][ks] = pack8(la2[0], la2[1]); __builtin_amdgcn_sched_barrier(0); } }
;     ...
;             for (int ef = 0; ef < 4; ++ef) { float tt = tot[ef]; tt += __shfl_xor(tt, 16); tt += __shfl_xor(tt, 32);
;                 if (vh == 0 && q == 0) dec[((size_t)(dir * NCH + n) * 4 + h) * 64 + SIGC(ef, c)] = __expf(tt); }
	s_waitcnt lgkmcnt(0)
	v_add_f32_e32 v34, v34, v35
	v_exp_f32_e32 v36, v34
	v_lshl_add_u64 v[34:35], v[32:33], 0, v[176:177]
	global_store_dword v[34:35], v36, off
.LBB0_340:
	s_or_b64 exec, exec, s[0:1]
	s_waitcnt lgkmcnt(0)
	v_add_f32_e32 v35, v78, v64
	v_add_f32_e32 v38, v78, v65
	v_min_f32_e32 v34, 0, v35
	v_min_f32_e32 v36, 0, v38
	v_mul_f32_e64 v35, |v35|, s33
	v_mul_f32_e64 v38, |v38|, s33
	v_exp_f32_e32 v35, v35
	v_exp_f32_e32 v38, v38
	v_mul_f32_e32 v34, 0x3db8aa3b, v34
	v_mul_f32_e32 v36, 0x3db8aa3b, v36
	v_add_f32_e32 v35, 1.0, v35
	v_add_f32_e32 v38, 1.0, v38
	v_log_f32_e32 v35, v35
	v_log_f32_e32 v38, v38
	v_fmamk_f32 v34, v35, 0xbd800000, v34
	v_fmamk_f32 v35, v38, 0xbd800000, v36
	v_add_f32_e32 v39, v78, v67
	v_add_f32_e32 v57, v78, v57
	v_add_f32_e32 v59, v78, v59
	v_add_f32_e32 v55, v78, v55
	v_add_f32_e32 v37, v78, v66
	s_nop 0
	v_add_f32_e32 v36, 0, v34
	v_add_f32_e32 v44, v35, v36
	v_min_f32_e32 v36, 0, v37
	v_min_f32_e32 v38, 0, v39
	v_mul_f32_e64 v37, |v37|, s33
	v_mul_f32_e64 v39, |v39|, s33
	v_exp_f32_e32 v37, v37
	v_exp_f32_e32 v39, v39
	v_mul_f32_e32 v36, 0x3db8aa3b, v36
	v_mul_f32_e32 v38, 0x3db8aa3b, v38
	v_add_f32_e32 v37, 1.0, v37
	v_add_f32_e32 v39, 1.0, v39
	v_log_f32_e32 v37, v37
	v_log_f32_e32 v39, v39
	v_fmamk_f32 v36, v37, 0xbd800000, v36
	v_fmamk_f32 v37, v39, 0xbd800000, v38
	v_add_f32_e32 v39, v78, v60
	v_add_f32_e32 v45, v78, v61
	v_add_f32_e32 v38, v36, v44
	v_add_f32_e32 v46, v37, v38
	v_min_f32_e32 v38, 0, v39
	v_min_f32_e32 v44, 0, v45
	v_mul_f32_e64 v39, |v39|, s33
	v_mul_f32_e64 v45, |v45|, s33
	v_exp_f32_e32 v39, v39
	v_exp_f32_e32 v45, v45
	v_mul_f32_e32 v38, 0x3db8aa3b, v38
	v_mul_f32_e32 v44, 0x3db8aa3b, v44
	v_add_f32_e32 v39, 1.0, v39
	v_add_f32_e32 v45, 1.0, v45
	v_log_f32_e32 v39, v39
	v_log_f32_e32 v45, v45
	v_fmamk_f32 v38, v39, 0xbd800000, v38
	v_fmamk_f32 v39, v45, 0xbd800000, v44
	v_add_f32_e32 v45, v78, v62
	v_add_f32_e32 v47, v78, v63
	v_add_f32_e32 v44, v38, v46
	v_add_f32_e32 v60, v39, v44
	v_min_f32_e32 v44, 0, v45
	v_min_f32_e32 v46, 0, v47
	v_mul_f32_e64 v45, |v45|, s33
	v_mul_f32_e64 v47, |v47|, s33
	v_exp_f32_e32 v45, v45
	v_exp_f32_e32 v47, v47
	v_mul_f32_e32 v44, 0x3db8aa3b, v44
	v_mul_f32_e32 v46, 0x3db8aa3b, v46
	v_add_f32_e32 v45, 1.0, v45
	v_add_f32_e32 v47, 1.0, v47
	v_log_f32_e32 v45, v45
	v_log_f32_e32 v47, v47
	v_fmamk_f32 v44, v45, 0xbd800000, v44
	v_fmamk_f32 v45, v47, 0xbd800000, v46
	v_add_f32_e32 v47, v78, v56
	s_nop 0
	v_add_f32_e32 v46, v44, v60
	v_add_f32_e32 v60, v45, v46
	v_min_f32_e32 v46, 0, v47
	v_min_f32_e32 v56, 0, v57
	v_mul_f32_e64 v47, |v47|, s33
	v_mul_f32_e64 v57, |v57|, s33
	v_exp_f32_e32 v47, v47
	v_exp_f32_e32 v57, v57
	v_mul_f32_e32 v46, 0x3db8aa3b, v46
	v_mul_f32_e32 v56, 0x3db8aa3b, v56
	v_add_f32_e32 v47, 1.0, v47
	v_add_f32_e32 v57, 1.0, v57
	v_log_f32_e32 v47, v47
	v_log_f32_e32 v57, v57
	v_fmamk_f32 v46, v47, 0xbd800000, v46
	v_fmamk_f32 v47, v57, 0xbd800000, v56
	v_add_f32_e32 v57, v78, v58
	s_nop 0
	v_add_f32_e32 v56, v46, v60
	v_add_f32_e32 v60, v47, v56
	v_min_f32_e32 v56, 0, v57
	v_min_f32_e32 v58, 0, v59
	v_mul_f32_e64 v57, |v57|, s33
	v_mul_f32_e64 v59, |v59|, s33
	v_exp_f32_e32 v57, v57
	v_exp_f32_e32 v59, v59
	v_mul_f32_e32 v56, 0x3db8aa3b, v56
	v_mul_f32_e32 v58, 0x3db8aa3b, v58
	v_add_f32_e32 v57, 1.0, v57
	v_add_f32_e32 v59, 1.0, v59
	v_log_f32_e32 v57, v57
	v_log_f32_e32 v59, v59
	v_fmamk_f32 v56, v57, 0xbd800000, v56
	v_fmamk_f32 v57, v59, 0xbd800000, v58
	s_nop 0
	v_add_f32_e32 v58, v56, v60
	v_add_f32_e32 v60, v57, v58
	v_add_f32_e32 v58, v78, v52
	v_add_f32_e32 v61, v78, v53
	v_min_f32_e32 v52, 0, v58
	v_min_f32_e32 v53, 0, v61
	v_mul_f32_e64 v58, |v58|, s33
	v_mul_f32_e64 v61, |v61|, s33
	v_exp_f32_e32 v58, v58
	v_exp_f32_e32 v61, v61
	v_mul_f32_e32 v52, 0x3db8aa3b, v52
	v_mul_f32_e32 v53, 0x3db8aa3b, v53
	v_add_f32_e32 v58, 1.0, v58
	v_add_f32_e32 v61, 1.0, v61
	v_log_f32_e32 v58, v58
	v_log_f32_e32 v61, v61
	v_fmamk_f32 v58, v58, 0xbd800000, v52
	v_fmamk_f32 v59, v61, 0xbd800000, v53
	v_add_f32_e32 v53, v78, v54
	v_add_f32_e32 v52, v58, v60
	v_add_f32_e32 v60, v59, v52
	v_min_f32_e32 v52, 0, v53
	v_min_f32_e32 v54, 0, v55
	v_mul_f32_e64 v53, |v53|, s33
	v_mul_f32_e64 v55, |v55|, s33
	v_exp_f32_e32 v53, v53
	v_exp_f32_e32 v55, v55
	v_mul_f32_e32 v52, 0x3db8aa3b, v52
	v_mul_f32_e32 v54, 0x3db8aa3b, v54
	v_add_f32_e32 v53, 1.0, v53
	v_add_f32_e32 v55, 1.0, v55
	v_log_f32_e32 v53, v53
	v_log_f32_e32 v55, v55
	v_fmamk_f32 v64, v53, 0xbd800000, v52
	v_fmamk_f32 v65, v55, 0xbd800000, v54
	s_nop 0
	v_add_f32_e32 v52, v64, v60
	v_add_f32_e32 v52, v65, v52
	ds_bpermute_b32 v53, v91, v52
	s_waitcnt lgkmcnt(0)
	v_add_f32_e32 v52, v52, v53
	ds_bpermute_b32 v53, v116, v52
	s_and_saveexec_b64 s[0:1], s[40:41]
	s_cbranch_execz .LBB0_342
	s_waitcnt lgkmcnt(0)
	v_add_f32_e32 v52, v52, v53
	v_exp_f32_e32 v54, v52
	v_lshl_add_u64 v[52:53], v[32:33], 0, v[176:177]
	global_store_dword v[52:53], v54, off offset:16
; __device__ __forceinline__ f32x4 mfma16(bf16x8 a, bf16x8 b, f32x4 c) { return __builtin_amdgcn_mfma_f32_16x16x32_bf16(a, b, c, 0, 0, 0); }
; template <int MODE> __device__ void mixer_gla(const Params& p, int l, int n, LAS unsigned char* lds) {
;     ...
;             for (int ef = 0; ef < 4; ++ef) { tot[ef] = 0.f;
; #pragma unroll
;                 for (int ks = 0; ks < 2; ++ks) { f32x4 la2[2];
; #pragma unroll
;                     for (int t2 = 0; t2 < 2; ++t2) { const f32x4 z = mfma16(lrf[2 * ks + t2], gwf[ef], zero4);
; #pragma unroll
;                         for (int r = 0; r < 4; ++r) { const float zz = z[r] + bgv[ef]; const float la = (fminf(zz, 0.f) - __logf(1.0f + __expf(-fabsf(zz)))) * (1.0f / 16.0f); la2[t2][r] = la; tot[ef] += la; } }
;                     laop[ef][ks] = pack8(la2[0], la2[1]); __builtin_amdgcn_sched_barrier(0); } }
;     ...
;             for (int ef = 0; ef < 4; ++ef) { float tt = tot[ef]; tt += __shfl_xor(tt, 16); tt += __shfl_xor(tt, 32);
;                 if (vh == 0 && q == 0) dec[((size_t)(dir * NCH + n) * 4 + h) * 64 + SIGC(ef, c)] = __expf(tt); }
.LBB0_342:
	s_or_b64 exec, exec, s[0:1]
	v_add_f32_e32 v52, v77, v48
	s_waitcnt lgkmcnt(0)
	v_add_f32_e32 v54, v77, v49
	v_min_f32_e32 v48, 0, v52
	v_min_f32_e32 v49, 0, v54
	v_mul_f32_e64 v52, |v52|, s33
	v_mul_f32_e64 v54, |v54|, s33
	v_exp_f32_e32 v52, v52
	v_exp_f32_e32 v54, v54
	v_mul_f32_e32 v48, 0x3db8aa3b, v48
	v_mul_f32_e32 v49, 0x3db8aa3b, v49
	v_add_f32_e32 v52, 1.0, v52
	v_add_f32_e32 v54, 1.0, v54
	v_log_f32_e32 v52, v52
	v_log_f32_e32 v54, v54
	v_fmamk_f32 v48, v52, 0xbd800000, v48
	v_fmamk_f32 v49, v54, 0xbd800000, v49
	s_nop 0
	v_add_f32_e32 v52, 0, v48
	v_add_f32_e32 v54, v49, v52
	v_add_f32_e32 v52, v77, v50
	v_add_f32_e32 v55, v77, v51
	v_min_f32_e32 v50, 0, v52
	v_min_f32_e32 v51, 0, v55
	v_mul_f32_e64 v52, |v52|, s33
	v_mul_f32_e64 v55, |v55|, s33
	v_exp_f32_e32 v52, v52
	v_exp_f32_e32 v55, v55
	v_mul_f32_e32 v50, 0x3db8aa3b, v50
	v_mul_f32_e32 v51, 0x3db8aa3b, v51
	v_add_f32_e32 v52, 1.0, v52
	v_add_f32_e32 v55, 1.0, v55
	v_log_f32_e32 v52, v52
	v_log_f32_e32 v55, v55
	v_fmamk_f32 v50, v52, 0xbd800000, v50
	v_fmamk_f32 v51, v55, 0xbd800000, v51
	s_nop 0
	v_add_f32_e32 v52, v50, v54
	v_add_f32_e32 v54, v51, v52
	v_add_f32_e32 v52, v77, v40
	v_add_f32_e32 v55, v77, v41
	v_min_f32_e32 v40, 0, v52
	v_min_f32_e32 v41, 0, v55
	v_mul_f32_e64 v52, |v52|, s33
	v_mul_f32_e64 v55, |v55|, s33
	v_exp_f32_e32 v52, v52
	v_exp_f32_e32 v55, v55
	v_mul_f32_e32 v40, 0x3db8aa3b, v40
	v_mul_f32_e32 v41, 0x3db8aa3b, v41
	v_add_f32_e32 v52, 1.0, v52
	v_add_f32_e32 v55, 1.0, v55
	v_log_f32_e32 v52, v52
	v_log_f32_e32 v55, v55
	v_fmamk_f32 v40, v52, 0xbd800000, v40
	v_fmamk_f32 v41, v55, 0xbd800000, v41
	s_nop 0
	v_add_f32_e32 v52, v40, v54
	v_add_f32_e32 v54, v41, v52
	v_add_f32_e32 v52, v77, v42
	v_add_f32_e32 v55, v77, v43
	v_min_f32_e32 v42, 0, v52
	v_min_f32_e32 v43, 0, v55
	v_mul_f32_e64 v52, |v52|, s33
	v_mul_f32_e64 v55, |v55|, s33
	v_exp_f32_e32 v52, v52
	v_exp_f32_e32 v55, v55
	v_mul_f32_e32 v42, 0x3db8aa3b, v42
	v_mul_f32_e32 v43, 0x3db8aa3b, v43
	v_add_f32_e32 v52, 1.0, v52
	v_add_f32_e32 v55, 1.0, v55
	v_log_f32_e32 v52, v52
	v_log_f32_e32 v55, v55
	v_fmamk_f32 v42, v52, 0xbd800000, v42
	v_fmamk_f32 v43, v55, 0xbd800000, v43
	s_nop 0
	v_add_f32_e32 v52, v42, v54
	v_add_f32_e32 v54, v43, v52
	v_add_f32_e32 v52, v77, v28
	v_add_f32_e32 v55, v77, v29
	v_min_f32_e32 v28, 0, v52
	v_min_f32_e32 v29, 0, v55
	v_mul_f32_e64 v52, |v52|, s33
	v_mul_f32_e64 v55, |v55|, s33
	v_exp_f32_e32 v52, v52
	v_exp_f32_e32 v55, v55
	v_mul_f32_e32 v28, 0x3db8aa3b, v28
	v_mul_f32_e32 v29, 0x3db8aa3b, v29
	v_add_f32_e32 v52, 1.0, v52
	v_add_f32_e32 v55, 1.0, v55
	v_log_f32_e32 v52, v52
	v_log_f32_e32 v55, v55
	v_fmamk_f32 v28, v52, 0xbd800000, v28
	v_fmamk_f32 v29, v55, 0xbd800000, v29
	s_nop 0
	v_add_f32_e32 v52, v28, v54
	v_add_f32_e32 v54, v29, v52
	v_add_f32_e32 v52, v77, v30
	v_add_f32_e32 v55, v77, v31
	v_min_f32_e32 v30, 0, v52
	v_min_f32_e32 v31, 0, v55
	v_mul_f32_e64 v52, |v52|, s33
	v_mul_f32_e64 v55, |v55|, s33
	v_exp_f32_e32 v52, v52
	v_exp_f32_e32 v55, v55
	v_mul_f32_e32 v30, 0x3db8aa3b, v30
	v_mul_f32_e32 v31, 0x3db8aa3b, v31
	v_add_f32_e32 v52, 1.0, v52
	v_add_f32_e32 v55, 1.0, v55
	v_log_f32_e32 v52, v52
	v_log_f32_e32 v55, v55
	v_fmamk_f32 v30, v52, 0xbd800000, v30
	v_fmamk_f32 v31, v55, 0xbd800000, v31
	s_nop 0
	v_add_f32_e32 v52, v30, v54
	v_add_f32_e32 v54, v31, v52
	v_add_f32_e32 v52, v77, v24
	v_add_f32_e32 v55, v77, v25
	v_min_f32_e32 v24, 0, v52
	v_min_f32_e32 v25, 0, v55
	v_mul_f32_e64 v52, |v52|, s33
	v_mul_f32_e64 v55, |v55|, s33
	v_exp_f32_e32 v52, v52
	v_exp_f32_e32 v55, v55
	v_mul_f32_e32 v24, 0x3db8aa3b, v24
	v_mul_f32_e32 v25, 0x3db8aa3b, v25
	v_add_f32_e32 v52, 1.0, v52
	v_add_f32_e32 v55, 1.0, v55
	v_log_f32_e32 v52, v52
	v_log_f32_e32 v55, v55
	v_fmamk_f32 v24, v52, 0xbd800000, v24
	v_fmamk_f32 v25, v55, 0xbd800000, v25
	s_nop 0
	v_add_f32_e32 v52, v24, v54
	v_add_f32_e32 v54, v25, v52
	v_add_f32_e32 v52, v77, v26
	v_add_f32_e32 v55, v77, v27
	v_min_f32_e32 v26, 0, v52
	v_min_f32_e32 v27, 0, v55
	v_mul_f32_e64 v52, |v52|, s33
	v_mul_f32_e64 v55, |v55|, s33
	v_exp_f32_e32 v52, v52
	v_exp_f32_e32 v55, v55
	v_mul_f32_e32 v26, 0x3db8aa3b, v26
	v_mul_f32_e32 v27, 0x3db8aa3b, v27
	v_add_f32_e32 v52, 1.0, v52
	v_add_f32_e32 v55, 1.0, v55
	v_log_f32_e32 v52, v52
	v_log_f32_e32 v55, v55
	v_fmamk_f32 v26, v52, 0xbd800000, v26
	v_fmamk_f32 v27, v55, 0xbd800000, v27
	s_nop 0
	v_add_f32_e32 v52, v26, v54
	v_add_f32_e32 v52, v27, v52
	ds_bpermute_b32 v53, v91, v52
	s_waitcnt lgkmcnt(0)
	v_add_f32_e32 v52, v52, v53
	ds_bpermute_b32 v53, v116, v52
	s_and_saveexec_b64 s[0:1], s[40:41]
	s_cbranch_execz .LBB0_344
	s_waitcnt lgkmcnt(0)
	v_add_f32_e32 v52, v52, v53
	v_exp_f32_e32 v54, v52
	v_lshl_add_u64 v[52:53], v[32:33], 0, v[176:177]
	global_store_dword v[52:53], v54, off offset:128
; __device__ __forceinline__ f32x4 mfma16(bf16x8 a, bf16x8 b, f32x4 c) { return __builtin_amdgcn_mfma_f32_16x16x32_bf16(a, b, c, 0, 0, 0); }
; template <int MODE> __device__ void mixer_gla(const Params& p, int l, int n, LAS unsigned char* lds) {
;     ...
;             for (int ef = 0; ef < 4; ++ef) { tot[ef] = 0.f;
; #pragma unroll
;                 for (int ks = 0; ks < 2; ++ks) { f32x4 la2[2];
; #pragma unroll
;                     for (int t2 = 0; t2 < 2; ++t2) { const f32x4 z = mfma16(lrf[2 * ks + t2], gwf[ef], zero4);
; #pragma unroll
;                         for (int r = 0; r < 4; ++r) { const float zz = z[r] + bgv[ef]; const float la = (fminf(zz, 0.f) - __logf(1.0f + __expf(-fabsf(zz)))) * (1.0f / 16.0f); la2[t2][r] = la; tot[ef] += la; } }
;                     laop[ef][ks] = pack8(la2[0], la2[1]); __builtin_amdgcn_sched_barrier(0); } }
;     ...
;             for (int ef = 0; ef < 4; ++ef) { float tt = tot[ef]; tt += __shfl_xor(tt, 16); tt += __shfl_xor(tt, 32);
;                 if (vh == 0 && q == 0) dec[((size_t)(dir * NCH + n) * 4 + h) * 64 + SIGC(ef, c)] = __expf(tt); }
.LBB0_344:
	s_or_b64 exec, exec, s[0:1]
	s_waitcnt vmcnt(0)
	v_add_f32_e32 v52, v76, v20
	s_waitcnt lgkmcnt(0)
	v_add_f32_e32 v54, v76, v21
	v_min_f32_e32 v20, 0, v52
	v_min_f32_e32 v21, 0, v54
	v_mul_f32_e64 v52, |v52|, s33
	v_mul_f32_e64 v54, |v54|, s33
	v_exp_f32_e32 v52, v52
	v_exp_f32_e32 v54, v54
	v_mul_f32_e32 v20, 0x3db8aa3b, v20
	v_mul_f32_e32 v21, 0x3db8aa3b, v21
	v_add_f32_e32 v52, 1.0, v52
	v_add_f32_e32 v54, 1.0, v54
	v_log_f32_e32 v52, v52
	v_log_f32_e32 v54, v54
	v_fmamk_f32 v20, v52, 0xbd800000, v20
	v_fmamk_f32 v21, v54, 0xbd800000, v21
	s_nop 0
	v_add_f32_e32 v52, 0, v20
	v_add_f32_e32 v54, v21, v52
	v_add_f32_e32 v52, v76, v22
	v_add_f32_e32 v55, v76, v23
	v_min_f32_e32 v22, 0, v52
	v_min_f32_e32 v23, 0, v55
	v_mul_f32_e64 v52, |v52|, s33
	v_mul_f32_e64 v55, |v55|, s33
	v_exp_f32_e32 v52, v52
	v_exp_f32_e32 v55, v55
	v_mul_f32_e32 v22, 0x3db8aa3b, v22
	v_mul_f32_e32 v23, 0x3db8aa3b, v23
	v_add_f32_e32 v52, 1.0, v52
	v_add_f32_e32 v55, 1.0, v55
	v_log_f32_e32 v52, v52
	v_log_f32_e32 v55, v55
	v_fmamk_f32 v22, v52, 0xbd800000, v22
	v_fmamk_f32 v23, v55, 0xbd800000, v23
	s_nop 0
	v_add_f32_e32 v52, v22, v54
	v_add_f32_e32 v54, v23, v52
	v_add_f32_e32 v52, v76, v16
	v_add_f32_e32 v55, v76, v17
	v_min_f32_e32 v16, 0, v52
	v_min_f32_e32 v17, 0, v55
	v_mul_f32_e64 v52, |v52|, s33
	v_mul_f32_e64 v55, |v55|, s33
	v_exp_f32_e32 v52, v52
	v_exp_f32_e32 v55, v55
	v_mul_f32_e32 v16, 0x3db8aa3b, v16
	v_mul_f32_e32 v17, 0x3db8aa3b, v17
	v_add_f32_e32 v52, 1.0, v52
	v_add_f32_e32 v55, 1.0, v55
	v_log_f32_e32 v52, v52
	v_log_f32_e32 v55, v55
	v_fmamk_f32 v16, v52, 0xbd800000, v16
	v_fmamk_f32 v17, v55, 0xbd800000, v17
	s_nop 0
	v_add_f32_e32 v52, v16, v54
	v_add_f32_e32 v54, v17, v52
	v_add_f32_e32 v52, v76, v18
	v_add_f32_e32 v55, v76, v19
	v_min_f32_e32 v18, 0, v52
	v_min_f32_e32 v19, 0, v55
	v_mul_f32_e64 v52, |v52|, s33
	v_mul_f32_e64 v55, |v55|, s33
	v_exp_f32_e32 v52, v52
	v_exp_f32_e32 v55, v55
	v_mul_f32_e32 v18, 0x3db8aa3b, v18
	v_mul_f32_e32 v19, 0x3db8aa3b, v19
	v_add_f32_e32 v52, 1.0, v52
	v_add_f32_e32 v55, 1.0, v55
	v_log_f32_e32 v52, v52
	v_log_f32_e32 v55, v55
	v_fmamk_f32 v18, v52, 0xbd800000, v18
	v_fmamk_f32 v19, v55, 0xbd800000, v19
	s_nop 0
	v_add_f32_e32 v52, v18, v54
	v_add_f32_e32 v54, v19, v52
	v_add_f32_e32 v52, v76, v12
	v_add_f32_e32 v55, v76, v13
	v_min_f32_e32 v12, 0, v52
	v_min_f32_e32 v13, 0, v55
	v_mul_f32_e64 v52, |v52|, s33
	v_mul_f32_e64 v55, |v55|, s33
	v_exp_f32_e32 v52, v52
	v_exp_f32_e32 v55, v55
	v_mul_f32_e32 v12, 0x3db8aa3b, v12
	v_mul_f32_e32 v13, 0x3db8aa3b, v13
	v_add_f32_e32 v52, 1.0, v52
	v_add_f32_e32 v55, 1.0, v55
	v_log_f32_e32 v52, v52
	v_log_f32_e32 v55, v55
	v_fmamk_f32 v12, v52, 0xbd800000, v12
	v_fmamk_f32 v13, v55, 0xbd800000, v13
	s_nop 0
	v_add_f32_e32 v52, v12, v54
	v_add_f32_e32 v54, v13, v52
	v_add_f32_e32 v52, v76, v14
	v_add_f32_e32 v55, v76, v15
	v_min_f32_e32 v14, 0, v52
	v_min_f32_e32 v15, 0, v55
	v_mul_f32_e64 v52, |v52|, s33
	v_mul_f32_e64 v55, |v55|, s33
	v_exp_f32_e32 v52, v52
	v_exp_f32_e32 v55, v55
	v_mul_f32_e32 v14, 0x3db8aa3b, v14
	v_mul_f32_e32 v15, 0x3db8aa3b, v15
	v_add_f32_e32 v52, 1.0, v52
	v_add_f32_e32 v55, 1.0, v55
	v_log_f32_e32 v52, v52
	v_log_f32_e32 v55, v55
	v_fmamk_f32 v14, v52, 0xbd800000, v14
	v_fmamk_f32 v15, v55, 0xbd800000, v15
	s_nop 0
	v_add_f32_e32 v52, v14, v54
	v_add_f32_e32 v54, v15, v52
	v_add_f32_e32 v52, v76, v8
	v_add_f32_e32 v55, v76, v9
	v_min_f32_e32 v8, 0, v52
	v_min_f32_e32 v9, 0, v55
	v_mul_f32_e64 v52, |v52|, s33
	v_mul_f32_e64 v55, |v55|, s33
	v_exp_f32_e32 v52, v52
	v_exp_f32_e32 v55, v55
	v_mul_f32_e32 v8, 0x3db8aa3b, v8
	v_mul_f32_e32 v9, 0x3db8aa3b, v9
	v_add_f32_e32 v52, 1.0, v52
	v_add_f32_e32 v55, 1.0, v55
	v_log_f32_e32 v52, v52
	v_log_f32_e32 v55, v55
	v_fmamk_f32 v8, v52, 0xbd800000, v8
	v_fmamk_f32 v9, v55, 0xbd800000, v9
	s_nop 0
	v_add_f32_e32 v52, v8, v54
	v_add_f32_e32 v54, v9, v52
	v_add_f32_e32 v52, v76, v10
	v_add_f32_e32 v55, v76, v11
	v_min_f32_e32 v10, 0, v52
	v_min_f32_e32 v11, 0, v55
	v_mul_f32_e64 v52, |v52|, s33
	v_mul_f32_e64 v55, |v55|, s33
	v_exp_f32_e32 v52, v52
	v_exp_f32_e32 v55, v55
	v_mul_f32_e32 v10, 0x3db8aa3b, v10
	v_mul_f32_e32 v11, 0x3db8aa3b, v11
	v_add_f32_e32 v52, 1.0, v52
	v_add_f32_e32 v55, 1.0, v55
	v_log_f32_e32 v52, v52
	v_log_f32_e32 v55, v55
	v_fmamk_f32 v10, v52, 0xbd800000, v10
	v_fmamk_f32 v11, v55, 0xbd800000, v11
	s_nop 0
	v_add_f32_e32 v52, v10, v54
	v_add_f32_e32 v52, v11, v52
	ds_bpermute_b32 v53, v91, v52
	s_waitcnt lgkmcnt(0)
	v_add_f32_e32 v52, v52, v53
	ds_bpermute_b32 v53, v116, v52
	s_and_saveexec_b64 s[0:1], s[40:41]
	s_cbranch_execz .LBB0_329
	s_waitcnt lgkmcnt(0)
	v_add_f32_e32 v52, v52, v53
	v_exp_f32_e32 v52, v52
	v_lshl_add_u64 v[32:33], v[32:33], 0, v[176:177]
	global_store_dword v[32:33], v52, off offset:144
	s_branch .LBB0_329
